# merge gate_reg: scratch loads software-pipelined one (ai,bj) group ahead into free fragment VGPR banks, counted vmcnt waits
# baseline (speedup 1.0000x reference)
; DI float sigm(float x) { return 1.f / (1.f + __expf(-x)); }
; DI u32x4 pack8(const float* f) { u32x4 o; o.x = pack2(f[0], f[1]); o.y = pack2(f[2], f[3]); o.z = pack2(f[4], f[5]); o.w = pack2(f[6], f[7]); return o; }
; DI int tid512() { int t = threadIdx.x; asm volatile("" : "+v"(t)); return t; }
; DI u32x4* merge_scratch(PREF p, int region) { const int t = tid512(); return (u32x4*)p.fbuf + (size_t)blockIdx.x * 40960 + region * 8192 + (t >> 6) * 1024 + (t & 63); }
; DI void gate_reg(PREF p, int l, int n, f32x4 (&acc)[2][2][4][2], int dt) {
;   const u32x4* sbn = merge_scratch(p, n);
;   u32x4* ssum = merge_scratch(p, 4);
;   const int t = tid512(), wid = t >> 6, lane = t & 63, wc = wid & 3, fr = lane & 15;
;   const float* bm = p.b_merge + (size_t)l * 4096 + n * 1024 + dt * 256 + wc * 32 + fr;
;   float bias[2][2];
; #pragma unroll
;   for (int bj = 0; bj < 2; ++bj)
; #pragma unroll
;     for (int nn = 0; nn < 2; ++nn) bias[bj][nn] = bm[bj * 128 + nn * 16];
; #pragma unroll
;   for (int ai = 0; ai < 2; ++ai)
; #pragma unroll
;     for (int bj = 0; bj < 2; ++bj) {
;       __builtin_amdgcn_sched_barrier(0);
;       u32x4 bn[4], pv[4];
; #pragma unroll
;       for (int m = 0; m < 4; ++m) {
;         bn[m] = sbn[((ai * 2 + bj) * 4 + m) * 64];
;         if (n > 0) pv[m] = ssum[((ai * 2 + bj) * 4 + m) * 64];
;       }
; #pragma unroll
;       for (int m = 0; m < 4; ++m) {
;         float b[8]; unpack8(bn[m], b);
;         float v[8];
; #pragma unroll
;         for (int nn = 0; nn < 2; ++nn)
; #pragma unroll
;           for (int j = 0; j < 4; ++j) v[nn * 4 + j] = sigm(acc[ai][bj][m][nn][j] + bias[bj][nn]) * b[nn * 4 + j];
;         if (n > 0) {
;           float o[8]; unpack8(pv[m], o);
; #pragma unroll
;           for (int e = 0; e < 8; ++e) v[e] += o[e];
;         }
;         if (n < 3) ssum[((ai * 2 + bj) * 4 + m) * 64] = pack8(v);
; #pragma unroll
;         for (int nn = 0; nn < 2; ++nn)
; #pragma unroll
;           for (int j = 0; j < 4; ++j) acc[ai][bj][m][nn][j] = v[nn * 4 + j];
;       }
.LBB0_108:
	s_or_b64 exec, exec, s[8:9]
	v_mov_b32_e32 v8, v168
	v_mov_b32_e32 v18, v168
	v_mov_b32_e32 v0, v168
	s_lshl_b32 s0, s23, 13
	s_lshl_b64 s[8:9], s[52:53], 2
	v_and_b32_e32 v9, 15, v0
	s_add_u32 s8, s25, s8
	v_lshlrev_b32_e32 v0, 1, v0
	s_addc_u32 s9, s48, s9
	v_and_b32_e32 v0, 0x180, v0
	v_lshl_add_u64 v[6:7], s[8:9], 0, v[0:1]
	v_lshlrev_b32_e32 v0, 2, v9
	v_lshl_add_u64 v[6:7], v[6:7], 0, v[0:1]
	global_load_dword v184, v[6:7], off
	global_load_dword v183, v[6:7], off offset:64
	global_load_dword v182, v[6:7], off offset:512
	global_load_dword v162, v[6:7], off offset:576
	s_mov_b32 s1, s53
	v_lshlrev_b32_e32 v0, 4, v8
	s_lshl_b64 s[0:1], s[0:1], 4
	v_and_b32_e32 v6, 0xfffffc00, v0
	v_and_b32_e32 v0, 63, v8
	v_lshlrev_b32_e32 v8, 4, v18
	s_add_u32 s0, s63, s0
	v_ashrrev_i32_e32 v7, 31, v6
	v_and_b32_e32 v8, 0xfffffc00, v8
	s_addc_u32 s1, s64, s1
	v_ashrrev_i32_e32 v9, 31, v8
	v_and_b32_e32 v18, 63, v18
	v_lshl_add_u64 v[6:7], v[6:7], 4, s[0:1]
	v_lshlrev_b32_e32 v0, 4, v0
	v_lshl_add_u64 v[166:167], v[6:7], 0, v[0:1]
	v_lshl_add_u64 v[6:7], v[8:9], 4, s[20:21]
	v_lshlrev_b32_e32 v0, 4, v18
	s_cmp_lg_u32 s23, 0
	v_lshl_add_u64 v[164:165], v[6:7], 0, v[0:1]
	s_cselect_b64 s[10:11], -1, 0
	s_cmp_eq_u32 s23, 0
	s_cbranch_scc1 .LBB0_110
.LBB0_110:
	v_cndmask_b32_e64 v0, 0, 1, s[10:11]
	v_cmp_ne_u32_e64 s[8:9], 1, v0
	s_andn2_b64 vcc, exec, s[10:11]
	s_cbranch_vccnz .LBB0_112
.LBB0_112:
	s_and_b64 vcc, exec, s[8:9]
	s_cbranch_vccnz .LBB0_114
.LBB0_114:
	s_and_b64 vcc, exec, s[8:9]
	s_cbranch_vccnz .LBB0_116
.LBB0_116:
	global_load_dwordx4 v[190:193], v[166:167], off
	global_load_dwordx4 v[194:197], v[164:165], off
	global_load_dwordx4 v[198:201], v[166:167], off offset:1024
	global_load_dwordx4 v[202:205], v[164:165], off offset:1024
	global_load_dwordx4 v[206:209], v[166:167], off offset:2048
	global_load_dwordx4 v[210:213], v[164:165], off offset:2048
	global_load_dwordx4 v[214:217], v[166:167], off offset:3072
	global_load_dwordx4 v[218:221], v[164:165], off offset:3072
	s_mov_b64 s[98:99], 0x1000
	v_lshl_add_u64 v[246:247], v[166:167], 0, s[98:99]
	v_lshl_add_u64 v[250:251], v[164:165], 0, s[98:99]
	global_load_dwordx4 v[222:225], v[246:247], off
	global_load_dwordx4 v[226:229], v[250:251], off
	global_load_dwordx4 v[230:233], v[246:247], off offset:1024
	global_load_dwordx4 v[234:237], v[250:251], off offset:1024
	global_load_dwordx4 v[238:241], v[246:247], off offset:2048
	global_load_dwordx4 v[242:245], v[250:251], off offset:2048
	global_load_dwordx4 v[246:249], v[246:247], off offset:3072
	global_load_dwordx4 v[250:253], v[250:251], off offset:3072
	s_waitcnt vmcnt(8)
	v_add_f32_e32 v0, v158, v184
	v_mul_f32_e32 v0, 0xbfb8aa3b, v0
	v_exp_f32_e32 v158, v0
	v_add_f32_e32 v0, v159, v184
	v_mul_f32_e32 v0, 0xbfb8aa3b, v0
	v_exp_f32_e32 v159, v0
	v_lshlrev_b32_e32 v186, 16, v190
	v_and_b32_e32 v187, 0xffff0000, v190
	v_pk_add_f32 v[158:159], v[158:159], 1.0 op_sel_hi:[1,0]
	s_nop 0
	v_rcp_f32_e32 v159, v159
	v_rcp_f32_e32 v158, v158
	v_add_f32_e32 v0, v160, v184
	v_mul_f32_e32 v0, 0xbfb8aa3b, v0
	v_exp_f32_e32 v160, v0
	v_add_f32_e32 v0, v161, v184
	v_mul_f32_e32 v0, 0xbfb8aa3b, v0
	v_exp_f32_e32 v161, v0
	v_pk_mul_f32 v[158:159], v[158:159], v[186:187]
	v_lshlrev_b32_e32 v154, 16, v191
	v_and_b32_e32 v155, 0xffff0000, v191
	v_pk_add_f32 v[160:161], v[160:161], 1.0 op_sel_hi:[1,0]
	s_nop 0
	v_rcp_f32_e32 v161, v161
	v_rcp_f32_e32 v160, v160
	v_add_f32_e32 v0, v150, v183
	v_mul_f32_e32 v0, 0xbfb8aa3b, v0
	v_exp_f32_e32 v150, v0
	v_add_f32_e32 v0, v151, v183
	v_mul_f32_e32 v0, 0xbfb8aa3b, v0
	v_exp_f32_e32 v151, v0
	v_pk_mul_f32 v[154:155], v[160:161], v[154:155]
	v_lshlrev_b32_e32 v160, 16, v192
	v_and_b32_e32 v161, 0xffff0000, v192
	v_pk_add_f32 v[150:151], v[150:151], 1.0 op_sel_hi:[1,0]
	s_nop 0
	v_rcp_f32_e32 v151, v151
	v_rcp_f32_e32 v150, v150
	v_add_f32_e32 v0, v152, v183
	v_mul_f32_e32 v0, 0xbfb8aa3b, v0
	v_exp_f32_e32 v152, v0
	v_add_f32_e32 v0, v153, v183
	v_mul_f32_e32 v0, 0xbfb8aa3b, v0
	v_exp_f32_e32 v153, v0
	v_pk_mul_f32 v[150:151], v[150:151], v[160:161]
	v_lshlrev_b32_e32 v156, 16, v193
	v_and_b32_e32 v157, 0xffff0000, v193
	v_pk_add_f32 v[152:153], v[152:153], 1.0 op_sel_hi:[1,0]
	s_nop 0
	v_rcp_f32_e32 v153, v153
	v_rcp_f32_e32 v152, v152
	s_nop 0
	v_pk_mul_f32 v[152:153], v[152:153], v[156:157]
	s_and_b64 vcc, exec, s[8:9]
	s_cbranch_vccnz .LBB0_118
	v_lshlrev_b32_e32 v156, 16, v194
	v_and_b32_e32 v157, 0xffff0000, v194
	v_pk_add_f32 v[158:159], v[158:159], v[156:157]
	v_lshlrev_b32_e32 v156, 16, v195
	v_and_b32_e32 v157, 0xffff0000, v195
	v_pk_add_f32 v[154:155], v[154:155], v[156:157]
	v_lshlrev_b32_e32 v156, 16, v196
	v_and_b32_e32 v157, 0xffff0000, v196
	v_pk_add_f32 v[150:151], v[150:151], v[156:157]
	v_lshlrev_b32_e32 v156, 16, v197
	v_and_b32_e32 v157, 0xffff0000, v197
	v_pk_add_f32 v[152:153], v[152:153], v[156:157]

; DI float sigm(float x) { return 1.f / (1.f + __expf(-x)); }
; DI u32x4 pack8(const float* f) { u32x4 o; o.x = pack2(f[0], f[1]); o.y = pack2(f[2], f[3]); o.z = pack2(f[4], f[5]); o.w = pack2(f[6], f[7]); return o; }
; DI void gate_reg(PREF p, int l, int n, f32x4 (&acc)[2][2][4][2], int dt) {
;     ...
; #pragma unroll
;       for (int m = 0; m < 4; ++m) {
;         float b[8]; unpack8(bn[m], b);
;         float v[8];
; #pragma unroll
;         for (int nn = 0; nn < 2; ++nn)
; #pragma unroll
;           for (int j = 0; j < 4; ++j) v[nn * 4 + j] = sigm(acc[ai][bj][m][nn][j] + bias[bj][nn]) * b[nn * 4 + j];
;         if (n > 0) {
;           float o[8]; unpack8(pv[m], o);
; #pragma unroll
;           for (int e = 0; e < 8; ++e) v[e] += o[e];
;         }
;         if (n < 3) ssum[((ai * 2 + bj) * 4 + m) * 64] = pack8(v);
; #pragma unroll
;         for (int nn = 0; nn < 2; ++nn)
; #pragma unroll
;           for (int j = 0; j < 4; ++j) acc[ai][bj][m][nn][j] = v[nn * 4 + j];
;       }
.LBB0_120:
	v_add_f32_e32 v0, v146, v184
	v_mul_f32_e32 v0, 0xbfb8aa3b, v0
	v_exp_f32_e32 v146, v0
	v_add_f32_e32 v0, v147, v184
	v_mul_f32_e32 v0, 0xbfb8aa3b, v0
	v_exp_f32_e32 v147, v0
	v_lshlrev_b32_e32 v156, 16, v198
	v_and_b32_e32 v157, 0xffff0000, v198
	v_pk_add_f32 v[146:147], v[146:147], 1.0 op_sel_hi:[1,0]
	s_nop 0
	v_rcp_f32_e32 v147, v147
	v_rcp_f32_e32 v146, v146
	v_add_f32_e32 v0, v148, v184
	v_mul_f32_e32 v0, 0xbfb8aa3b, v0
	v_exp_f32_e32 v148, v0
	v_add_f32_e32 v0, v149, v184
	v_mul_f32_e32 v0, 0xbfb8aa3b, v0
	v_exp_f32_e32 v149, v0
	v_pk_mul_f32 v[146:147], v[146:147], v[156:157]
	v_lshlrev_b32_e32 v142, 16, v199
	v_and_b32_e32 v143, 0xffff0000, v199
	v_pk_add_f32 v[148:149], v[148:149], 1.0 op_sel_hi:[1,0]
	s_nop 0
	v_rcp_f32_e32 v149, v149
	v_rcp_f32_e32 v148, v148
	v_add_f32_e32 v0, v138, v183
	v_mul_f32_e32 v0, 0xbfb8aa3b, v0
	v_exp_f32_e32 v138, v0
	v_add_f32_e32 v0, v139, v183
	v_mul_f32_e32 v0, 0xbfb8aa3b, v0
	v_exp_f32_e32 v139, v0
	v_pk_mul_f32 v[142:143], v[148:149], v[142:143]
	v_lshlrev_b32_e32 v148, 16, v200
	v_and_b32_e32 v149, 0xffff0000, v200
	v_pk_add_f32 v[138:139], v[138:139], 1.0 op_sel_hi:[1,0]
	s_nop 0
	v_rcp_f32_e32 v139, v139
	v_rcp_f32_e32 v138, v138
	v_add_f32_e32 v0, v140, v183
	v_mul_f32_e32 v0, 0xbfb8aa3b, v0
	v_exp_f32_e32 v140, v0
	v_add_f32_e32 v0, v141, v183
	v_mul_f32_e32 v0, 0xbfb8aa3b, v0
	v_exp_f32_e32 v141, v0
	v_pk_mul_f32 v[138:139], v[138:139], v[148:149]
	v_lshlrev_b32_e32 v144, 16, v201
	v_and_b32_e32 v145, 0xffff0000, v201
	v_pk_add_f32 v[140:141], v[140:141], 1.0 op_sel_hi:[1,0]
	s_nop 0
	v_rcp_f32_e32 v141, v141
	v_rcp_f32_e32 v140, v140
	s_nop 0
	v_pk_mul_f32 v[140:141], v[140:141], v[144:145]
	s_and_b64 vcc, exec, s[8:9]
	s_cbranch_vccnz .LBB0_122
	v_lshlrev_b32_e32 v144, 16, v202
	v_and_b32_e32 v145, 0xffff0000, v202
	v_pk_add_f32 v[146:147], v[146:147], v[144:145]
	v_lshlrev_b32_e32 v144, 16, v203
	v_and_b32_e32 v145, 0xffff0000, v203
	v_pk_add_f32 v[142:143], v[142:143], v[144:145]
	v_lshlrev_b32_e32 v144, 16, v204
	v_and_b32_e32 v145, 0xffff0000, v204
	v_pk_add_f32 v[138:139], v[138:139], v[144:145]
	v_lshlrev_b32_e32 v144, 16, v205
	v_and_b32_e32 v145, 0xffff0000, v205
	v_pk_add_f32 v[140:141], v[140:141], v[144:145]

; DI float sigm(float x) { return 1.f / (1.f + __expf(-x)); }
; DI u32x4 pack8(const float* f) { u32x4 o; o.x = pack2(f[0], f[1]); o.y = pack2(f[2], f[3]); o.z = pack2(f[4], f[5]); o.w = pack2(f[6], f[7]); return o; }
; DI void gate_reg(PREF p, int l, int n, f32x4 (&acc)[2][2][4][2], int dt) {
;     ...
; #pragma unroll
;       for (int m = 0; m < 4; ++m) {
;         float b[8]; unpack8(bn[m], b);
;         float v[8];
; #pragma unroll
;         for (int nn = 0; nn < 2; ++nn)
; #pragma unroll
;           for (int j = 0; j < 4; ++j) v[nn * 4 + j] = sigm(acc[ai][bj][m][nn][j] + bias[bj][nn]) * b[nn * 4 + j];
;         if (n > 0) {
;           float o[8]; unpack8(pv[m], o);
; #pragma unroll
;           for (int e = 0; e < 8; ++e) v[e] += o[e];
;         }
;         if (n < 3) ssum[((ai * 2 + bj) * 4 + m) * 64] = pack8(v);
; #pragma unroll
;         for (int nn = 0; nn < 2; ++nn)
; #pragma unroll
;           for (int j = 0; j < 4; ++j) acc[ai][bj][m][nn][j] = v[nn * 4 + j];
;       }
.LBB0_124:
	v_add_f32_e32 v0, v134, v184
	v_mul_f32_e32 v0, 0xbfb8aa3b, v0
	v_exp_f32_e32 v134, v0
	v_add_f32_e32 v0, v135, v184
	v_mul_f32_e32 v0, 0xbfb8aa3b, v0
	v_exp_f32_e32 v135, v0
	v_lshlrev_b32_e32 v144, 16, v206
	v_and_b32_e32 v145, 0xffff0000, v206
	v_pk_add_f32 v[134:135], v[134:135], 1.0 op_sel_hi:[1,0]
	s_nop 0
	v_rcp_f32_e32 v135, v135
	v_rcp_f32_e32 v134, v134
	v_add_f32_e32 v0, v136, v184
	v_mul_f32_e32 v0, 0xbfb8aa3b, v0
	v_exp_f32_e32 v136, v0
	v_add_f32_e32 v0, v137, v184
	v_mul_f32_e32 v0, 0xbfb8aa3b, v0
	v_exp_f32_e32 v137, v0
	v_pk_mul_f32 v[134:135], v[134:135], v[144:145]
	v_lshlrev_b32_e32 v130, 16, v207
	v_and_b32_e32 v131, 0xffff0000, v207
	v_pk_add_f32 v[136:137], v[136:137], 1.0 op_sel_hi:[1,0]
	s_nop 0
	v_rcp_f32_e32 v137, v137
	v_rcp_f32_e32 v136, v136
	v_add_f32_e32 v0, v126, v183
	v_mul_f32_e32 v0, 0xbfb8aa3b, v0
	v_exp_f32_e32 v126, v0
	v_add_f32_e32 v0, v127, v183
	v_mul_f32_e32 v0, 0xbfb8aa3b, v0
	v_exp_f32_e32 v127, v0
	v_pk_mul_f32 v[130:131], v[136:137], v[130:131]
	v_lshlrev_b32_e32 v136, 16, v208
	v_and_b32_e32 v137, 0xffff0000, v208
	v_pk_add_f32 v[126:127], v[126:127], 1.0 op_sel_hi:[1,0]
	s_nop 0
	v_rcp_f32_e32 v127, v127
	v_rcp_f32_e32 v126, v126
	v_add_f32_e32 v0, v128, v183
	v_mul_f32_e32 v0, 0xbfb8aa3b, v0
	v_pk_mul_f32 v[136:137], v[126:127], v[136:137]
	v_exp_f32_e32 v126, v0
	v_add_f32_e32 v0, v129, v183
	v_mul_f32_e32 v0, 0xbfb8aa3b, v0
	v_exp_f32_e32 v127, v0
	v_lshlrev_b32_e32 v128, 16, v209
	v_and_b32_e32 v129, 0xffff0000, v209
	v_pk_add_f32 v[126:127], v[126:127], 1.0 op_sel_hi:[1,0]
	s_nop 0
	v_rcp_f32_e32 v127, v127
	v_rcp_f32_e32 v126, v126
	s_nop 0
	v_pk_mul_f32 v[132:133], v[126:127], v[128:129]
	s_and_b64 vcc, exec, s[8:9]
	s_cbranch_vccnz .LBB0_126
	v_lshlrev_b32_e32 v126, 16, v210
	v_and_b32_e32 v127, 0xffff0000, v210
	v_pk_add_f32 v[134:135], v[134:135], v[126:127]
	v_lshlrev_b32_e32 v126, 16, v211
	v_and_b32_e32 v127, 0xffff0000, v211
	v_pk_add_f32 v[130:131], v[130:131], v[126:127]
	v_lshlrev_b32_e32 v126, 16, v212
	v_and_b32_e32 v127, 0xffff0000, v212
	v_pk_add_f32 v[136:137], v[136:137], v[126:127]
	v_lshlrev_b32_e32 v126, 16, v213
	v_and_b32_e32 v127, 0xffff0000, v213
	v_pk_add_f32 v[132:133], v[132:133], v[126:127]

; DI float sigm(float x) { return 1.f / (1.f + __expf(-x)); }
; DI u32x4 pack8(const float* f) { u32x4 o; o.x = pack2(f[0], f[1]); o.y = pack2(f[2], f[3]); o.z = pack2(f[4], f[5]); o.w = pack2(f[6], f[7]); return o; }
; DI void gate_reg(PREF p, int l, int n, f32x4 (&acc)[2][2][4][2], int dt) {
;     ...
; #pragma unroll
;       for (int m = 0; m < 4; ++m) {
;         float b[8]; unpack8(bn[m], b);
;         float v[8];
; #pragma unroll
;         for (int nn = 0; nn < 2; ++nn)
; #pragma unroll
;           for (int j = 0; j < 4; ++j) v[nn * 4 + j] = sigm(acc[ai][bj][m][nn][j] + bias[bj][nn]) * b[nn * 4 + j];
;         if (n > 0) {
;           float o[8]; unpack8(pv[m], o);
; #pragma unroll
;           for (int e = 0; e < 8; ++e) v[e] += o[e];
;         }
;         if (n < 3) ssum[((ai * 2 + bj) * 4 + m) * 64] = pack8(v);
; #pragma unroll
;         for (int nn = 0; nn < 2; ++nn)
; #pragma unroll
;           for (int j = 0; j < 4; ++j) acc[ai][bj][m][nn][j] = v[nn * 4 + j];
;       }
.LBB0_128:
	v_add_f32_e32 v0, v122, v184
	v_mul_f32_e32 v0, 0xbfb8aa3b, v0
	v_exp_f32_e32 v122, v0
	v_add_f32_e32 v0, v123, v184
	v_mul_f32_e32 v0, 0xbfb8aa3b, v0
	v_exp_f32_e32 v123, v0
	v_lshlrev_b32_e32 v126, 16, v214
	v_and_b32_e32 v127, 0xffff0000, v214
	v_pk_add_f32 v[122:123], v[122:123], 1.0 op_sel_hi:[1,0]
	s_nop 0
	v_rcp_f32_e32 v123, v123
	v_rcp_f32_e32 v122, v122
	v_add_f32_e32 v0, v124, v184
	v_mul_f32_e32 v0, 0xbfb8aa3b, v0
	v_pk_mul_f32 v[144:145], v[122:123], v[126:127]
	v_exp_f32_e32 v122, v0
	v_add_f32_e32 v0, v125, v184
	v_mul_f32_e32 v0, 0xbfb8aa3b, v0
	v_exp_f32_e32 v123, v0
	v_lshlrev_b32_e32 v118, 16, v215
	v_and_b32_e32 v119, 0xffff0000, v215
	v_pk_add_f32 v[122:123], v[122:123], 1.0 op_sel_hi:[1,0]
	s_nop 0
	v_rcp_f32_e32 v123, v123
	v_rcp_f32_e32 v122, v122
	v_add_f32_e32 v0, v114, v183
	v_mul_f32_e32 v0, 0xbfb8aa3b, v0
	v_exp_f32_e32 v114, v0
	v_add_f32_e32 v0, v115, v183
	v_mul_f32_e32 v0, 0xbfb8aa3b, v0
	v_exp_f32_e32 v115, v0
	v_pk_mul_f32 v[148:149], v[122:123], v[118:119]
	v_lshlrev_b32_e32 v118, 16, v216
	v_and_b32_e32 v119, 0xffff0000, v216
	v_pk_add_f32 v[114:115], v[114:115], 1.0 op_sel_hi:[1,0]
	s_nop 0
	v_rcp_f32_e32 v115, v115
	v_rcp_f32_e32 v114, v114
	v_add_f32_e32 v0, v116, v183
	v_mul_f32_e32 v0, 0xbfb8aa3b, v0
	v_pk_mul_f32 v[156:157], v[114:115], v[118:119]
	v_exp_f32_e32 v114, v0
	v_add_f32_e32 v0, v117, v183
	v_mul_f32_e32 v0, 0xbfb8aa3b, v0
	v_exp_f32_e32 v115, v0
	v_lshlrev_b32_e32 v116, 16, v217
	v_and_b32_e32 v117, 0xffff0000, v217
	v_pk_add_f32 v[114:115], v[114:115], 1.0 op_sel_hi:[1,0]
	s_nop 0
	v_rcp_f32_e32 v115, v115
	v_rcp_f32_e32 v114, v114
	s_nop 0
	v_pk_mul_f32 v[160:161], v[114:115], v[116:117]
	s_and_b64 vcc, exec, s[8:9]
	s_cbranch_vccnz .LBB0_130
	v_lshlrev_b32_e32 v114, 16, v218
	v_and_b32_e32 v115, 0xffff0000, v218
	v_pk_add_f32 v[144:145], v[144:145], v[114:115]
	v_lshlrev_b32_e32 v114, 16, v219
	v_and_b32_e32 v115, 0xffff0000, v219
	v_pk_add_f32 v[148:149], v[148:149], v[114:115]
	v_lshlrev_b32_e32 v114, 16, v220
	v_and_b32_e32 v115, 0xffff0000, v220
	v_pk_add_f32 v[156:157], v[156:157], v[114:115]
	v_lshlrev_b32_e32 v114, 16, v221
	v_and_b32_e32 v115, 0xffff0000, v221
	v_pk_add_f32 v[160:161], v[160:161], v[114:115]

; DI float sigm(float x) { return 1.f / (1.f + __expf(-x)); }
; DI u32x4 pack8(const float* f) { u32x4 o; o.x = pack2(f[0], f[1]); o.y = pack2(f[2], f[3]); o.z = pack2(f[4], f[5]); o.w = pack2(f[6], f[7]); return o; }
; DI void gate_reg(PREF p, int l, int n, f32x4 (&acc)[2][2][4][2], int dt) {
;     ...
;       u32x4 bn[4], pv[4];
; #pragma unroll
;       for (int m = 0; m < 4; ++m) {
;         bn[m] = sbn[((ai * 2 + bj) * 4 + m) * 64];
;         if (n > 0) pv[m] = ssum[((ai * 2 + bj) * 4 + m) * 64];
;       }
; #pragma unroll
;       for (int m = 0; m < 4; ++m) {
;         float b[8]; unpack8(bn[m], b);
;         float v[8];
; #pragma unroll
;         for (int nn = 0; nn < 2; ++nn)
; #pragma unroll
;           for (int j = 0; j < 4; ++j) v[nn * 4 + j] = sigm(acc[ai][bj][m][nn][j] + bias[bj][nn]) * b[nn * 4 + j];
;         if (n > 0) {
;           float o[8]; unpack8(pv[m], o);
; #pragma unroll
;           for (int e = 0; e < 8; ++e) v[e] += o[e];
;         }
;         if (n < 3) ssum[((ai * 2 + bj) * 4 + m) * 64] = pack8(v);
; #pragma unroll
;         for (int nn = 0; nn < 2; ++nn)
; #pragma unroll
;           for (int j = 0; j < 4; ++j) acc[ai][bj][m][nn][j] = v[nn * 4 + j];
;       }
.LBB0_132:
	s_mov_b64 s[98:99], 0x2000
	v_lshl_add_u64 v[214:215], v[166:167], 0, s[98:99]
	v_lshl_add_u64 v[218:219], v[164:165], 0, s[98:99]
	global_load_dwordx4 v[190:193], v[214:215], off
	global_load_dwordx4 v[194:197], v[218:219], off
	global_load_dwordx4 v[198:201], v[214:215], off offset:1024
	global_load_dwordx4 v[202:205], v[218:219], off offset:1024
	global_load_dwordx4 v[206:209], v[214:215], off offset:2048
	global_load_dwordx4 v[210:213], v[218:219], off offset:2048
	global_load_dwordx4 v[214:217], v[214:215], off offset:3072
	global_load_dwordx4 v[218:221], v[218:219], off offset:3072
	s_cmp_eq_u32 s23, 3
	s_cbranch_scc1 .Lmy_gw_g1_n3
	s_waitcnt vmcnt(12)
	s_branch .Lmy_gw_g1_d
.Lmy_gw_g1_n3:
	s_waitcnt vmcnt(8)
.Lmy_gw_g1_d:
	s_and_b64 vcc, exec, s[8:9]
	s_cbranch_vccnz .LBB0_134
.LBB0_134:
	s_and_b64 vcc, exec, s[8:9]
	s_cbranch_vccnz .LBB0_136
.LBB0_136:
	s_and_b64 vcc, exec, s[8:9]
	s_cbranch_vccnz .LBB0_138
.LBB0_138:
	s_and_b64 vcc, exec, s[8:9]
	s_cbranch_vccnz .LBB0_140
.LBB0_140:
	v_add_f32_e32 v0, v110, v182
	v_mul_f32_e32 v0, 0xbfb8aa3b, v0
	v_exp_f32_e32 v110, v0
	v_add_f32_e32 v0, v111, v182
	v_mul_f32_e32 v0, 0xbfb8aa3b, v0
	v_exp_f32_e32 v111, v0
	v_lshlrev_b32_e32 v186, 16, v222
	v_and_b32_e32 v187, 0xffff0000, v222
	v_pk_add_f32 v[110:111], v[110:111], 1.0 op_sel_hi:[1,0]
	s_nop 0
	v_rcp_f32_e32 v111, v111
	v_rcp_f32_e32 v110, v110
	v_add_f32_e32 v0, v112, v182
	v_mul_f32_e32 v0, 0xbfb8aa3b, v0
	v_exp_f32_e32 v112, v0
	v_add_f32_e32 v0, v113, v182
	v_mul_f32_e32 v0, 0xbfb8aa3b, v0
	v_exp_f32_e32 v113, v0
	v_pk_mul_f32 v[110:111], v[110:111], v[186:187]
	v_lshlrev_b32_e32 v126, 16, v223
	v_and_b32_e32 v127, 0xffff0000, v223
	v_pk_add_f32 v[112:113], v[112:113], 1.0 op_sel_hi:[1,0]
	s_nop 0
	v_rcp_f32_e32 v113, v113
	v_rcp_f32_e32 v112, v112
	v_add_f32_e32 v0, v106, v162
	v_mul_f32_e32 v0, 0xbfb8aa3b, v0
	v_exp_f32_e32 v106, v0
	v_add_f32_e32 v0, v107, v162
	v_mul_f32_e32 v0, 0xbfb8aa3b, v0
	v_exp_f32_e32 v107, v0
	v_pk_mul_f32 v[112:113], v[112:113], v[126:127]
	v_lshlrev_b32_e32 v126, 16, v224
	v_and_b32_e32 v127, 0xffff0000, v224
	v_pk_add_f32 v[106:107], v[106:107], 1.0 op_sel_hi:[1,0]
	s_nop 0
	v_rcp_f32_e32 v107, v107
	v_rcp_f32_e32 v106, v106
	v_add_f32_e32 v0, v108, v162
	v_mul_f32_e32 v0, 0xbfb8aa3b, v0
	v_exp_f32_e32 v108, v0
	v_add_f32_e32 v0, v109, v162
	v_mul_f32_e32 v0, 0xbfb8aa3b, v0
	v_exp_f32_e32 v109, v0
	v_pk_mul_f32 v[106:107], v[106:107], v[126:127]
	v_lshlrev_b32_e32 v126, 16, v225
	v_and_b32_e32 v127, 0xffff0000, v225
	v_pk_add_f32 v[108:109], v[108:109], 1.0 op_sel_hi:[1,0]
	s_nop 0
	v_rcp_f32_e32 v109, v109
	v_rcp_f32_e32 v108, v108
	s_nop 0
	v_pk_mul_f32 v[108:109], v[108:109], v[126:127]
	s_and_b64 vcc, exec, s[8:9]
	s_cbranch_vccnz .LBB0_142
	v_lshlrev_b32_e32 v126, 16, v226
	v_and_b32_e32 v127, 0xffff0000, v226
	v_pk_add_f32 v[110:111], v[110:111], v[126:127]
	v_lshlrev_b32_e32 v126, 16, v227
	v_and_b32_e32 v127, 0xffff0000, v227
	v_pk_add_f32 v[112:113], v[112:113], v[126:127]
	v_lshlrev_b32_e32 v126, 16, v228
	v_and_b32_e32 v127, 0xffff0000, v228
	v_pk_add_f32 v[106:107], v[106:107], v[126:127]
	v_lshlrev_b32_e32 v126, 16, v229
	v_and_b32_e32 v127, 0xffff0000, v229
	v_pk_add_f32 v[108:109], v[108:109], v[126:127]

; DI float sigm(float x) { return 1.f / (1.f + __expf(-x)); }
; DI u32x4 pack8(const float* f) { u32x4 o; o.x = pack2(f[0], f[1]); o.y = pack2(f[2], f[3]); o.z = pack2(f[4], f[5]); o.w = pack2(f[6], f[7]); return o; }
; DI void gate_reg(PREF p, int l, int n, f32x4 (&acc)[2][2][4][2], int dt) {
;     ...
; #pragma unroll
;       for (int m = 0; m < 4; ++m) {
;         float b[8]; unpack8(bn[m], b);
;         float v[8];
; #pragma unroll
;         for (int nn = 0; nn < 2; ++nn)
; #pragma unroll
;           for (int j = 0; j < 4; ++j) v[nn * 4 + j] = sigm(acc[ai][bj][m][nn][j] + bias[bj][nn]) * b[nn * 4 + j];
;         if (n > 0) {
;           float o[8]; unpack8(pv[m], o);
; #pragma unroll
;           for (int e = 0; e < 8; ++e) v[e] += o[e];
;         }
;         if (n < 3) ssum[((ai * 2 + bj) * 4 + m) * 64] = pack8(v);
; #pragma unroll
;         for (int nn = 0; nn < 2; ++nn)
; #pragma unroll
;           for (int j = 0; j < 4; ++j) acc[ai][bj][m][nn][j] = v[nn * 4 + j];
;       }
.LBB0_144:
	v_add_f32_e32 v0, v102, v182
	v_mul_f32_e32 v0, 0xbfb8aa3b, v0
	v_exp_f32_e32 v102, v0
	v_add_f32_e32 v0, v103, v182
	v_mul_f32_e32 v0, 0xbfb8aa3b, v0
	v_exp_f32_e32 v103, v0
	v_lshlrev_b32_e32 v126, 16, v230
	v_and_b32_e32 v127, 0xffff0000, v230
	v_pk_add_f32 v[102:103], v[102:103], 1.0 op_sel_hi:[1,0]
	s_nop 0
	v_rcp_f32_e32 v103, v103
	v_rcp_f32_e32 v102, v102
	v_add_f32_e32 v0, v104, v182
	v_mul_f32_e32 v0, 0xbfb8aa3b, v0
	v_exp_f32_e32 v104, v0
	v_add_f32_e32 v0, v105, v182
	v_mul_f32_e32 v0, 0xbfb8aa3b, v0
	v_exp_f32_e32 v105, v0
	v_pk_mul_f32 v[102:103], v[102:103], v[126:127]
	v_lshlrev_b32_e32 v122, 16, v231
	v_and_b32_e32 v123, 0xffff0000, v231
	v_pk_add_f32 v[104:105], v[104:105], 1.0 op_sel_hi:[1,0]
	s_nop 0
	v_rcp_f32_e32 v105, v105
	v_rcp_f32_e32 v104, v104
	v_add_f32_e32 v0, v98, v162
	v_mul_f32_e32 v0, 0xbfb8aa3b, v0
	v_exp_f32_e32 v98, v0
	v_add_f32_e32 v0, v99, v162
	v_mul_f32_e32 v0, 0xbfb8aa3b, v0
	v_exp_f32_e32 v99, v0
	v_pk_mul_f32 v[104:105], v[104:105], v[122:123]
	v_lshlrev_b32_e32 v122, 16, v232
	v_and_b32_e32 v123, 0xffff0000, v232
	v_pk_add_f32 v[98:99], v[98:99], 1.0 op_sel_hi:[1,0]
	s_nop 0
	v_rcp_f32_e32 v99, v99
	v_rcp_f32_e32 v98, v98
	v_add_f32_e32 v0, v100, v162
	v_mul_f32_e32 v0, 0xbfb8aa3b, v0
	v_exp_f32_e32 v100, v0
	v_add_f32_e32 v0, v101, v162
	v_mul_f32_e32 v0, 0xbfb8aa3b, v0
	v_exp_f32_e32 v101, v0
	v_pk_mul_f32 v[98:99], v[98:99], v[122:123]
	v_lshlrev_b32_e32 v122, 16, v233
	v_and_b32_e32 v123, 0xffff0000, v233
	v_pk_add_f32 v[100:101], v[100:101], 1.0 op_sel_hi:[1,0]
	s_nop 0
	v_rcp_f32_e32 v101, v101
	v_rcp_f32_e32 v100, v100
	s_nop 0
	v_pk_mul_f32 v[100:101], v[100:101], v[122:123]
	s_and_b64 vcc, exec, s[8:9]
	s_cbranch_vccnz .LBB0_146
	v_lshlrev_b32_e32 v122, 16, v234
	v_and_b32_e32 v123, 0xffff0000, v234
	v_pk_add_f32 v[102:103], v[102:103], v[122:123]
	v_lshlrev_b32_e32 v122, 16, v235
	v_and_b32_e32 v123, 0xffff0000, v235
	v_pk_add_f32 v[104:105], v[104:105], v[122:123]
	v_lshlrev_b32_e32 v122, 16, v236
	v_and_b32_e32 v123, 0xffff0000, v236
	v_pk_add_f32 v[98:99], v[98:99], v[122:123]
	v_lshlrev_b32_e32 v122, 16, v237
	v_and_b32_e32 v123, 0xffff0000, v237
	v_pk_add_f32 v[100:101], v[100:101], v[122:123]

; DI float sigm(float x) { return 1.f / (1.f + __expf(-x)); }
; DI u32x4 pack8(const float* f) { u32x4 o; o.x = pack2(f[0], f[1]); o.y = pack2(f[2], f[3]); o.z = pack2(f[4], f[5]); o.w = pack2(f[6], f[7]); return o; }
; DI void gate_reg(PREF p, int l, int n, f32x4 (&acc)[2][2][4][2], int dt) {
;     ...
; #pragma unroll
;       for (int m = 0; m < 4; ++m) {
;         float b[8]; unpack8(bn[m], b);
;         float v[8];
; #pragma unroll
;         for (int nn = 0; nn < 2; ++nn)
; #pragma unroll
;           for (int j = 0; j < 4; ++j) v[nn * 4 + j] = sigm(acc[ai][bj][m][nn][j] + bias[bj][nn]) * b[nn * 4 + j];
;         if (n > 0) {
;           float o[8]; unpack8(pv[m], o);
; #pragma unroll
;           for (int e = 0; e < 8; ++e) v[e] += o[e];
;         }
;         if (n < 3) ssum[((ai * 2 + bj) * 4 + m) * 64] = pack8(v);
; #pragma unroll
;         for (int nn = 0; nn < 2; ++nn)
; #pragma unroll
;           for (int j = 0; j < 4; ++j) acc[ai][bj][m][nn][j] = v[nn * 4 + j];
;       }
.LBB0_148:
	v_add_f32_e32 v0, v94, v182
	v_mul_f32_e32 v0, 0xbfb8aa3b, v0
	v_exp_f32_e32 v94, v0
	v_add_f32_e32 v0, v95, v182
	v_mul_f32_e32 v0, 0xbfb8aa3b, v0
	v_exp_f32_e32 v95, v0
	v_lshlrev_b32_e32 v122, 16, v238
	v_and_b32_e32 v123, 0xffff0000, v238
	v_pk_add_f32 v[94:95], v[94:95], 1.0 op_sel_hi:[1,0]
	s_nop 0
	v_rcp_f32_e32 v95, v95
	v_rcp_f32_e32 v94, v94
	v_add_f32_e32 v0, v96, v182
	v_mul_f32_e32 v0, 0xbfb8aa3b, v0
	v_pk_mul_f32 v[122:123], v[94:95], v[122:123]
	v_exp_f32_e32 v94, v0
	v_add_f32_e32 v0, v97, v182
	v_mul_f32_e32 v0, 0xbfb8aa3b, v0
	v_exp_f32_e32 v95, v0
	v_lshlrev_b32_e32 v96, 16, v239
	v_and_b32_e32 v97, 0xffff0000, v239
	v_pk_add_f32 v[94:95], v[94:95], 1.0 op_sel_hi:[1,0]
	s_nop 0
	v_rcp_f32_e32 v95, v95
	v_rcp_f32_e32 v94, v94
	v_add_f32_e32 v0, v90, v162
	v_mul_f32_e32 v0, 0xbfb8aa3b, v0
	v_exp_f32_e32 v90, v0
	v_add_f32_e32 v0, v91, v162
	v_mul_f32_e32 v0, 0xbfb8aa3b, v0
	v_exp_f32_e32 v91, v0
	v_pk_mul_f32 v[118:119], v[94:95], v[96:97]
	v_lshlrev_b32_e32 v94, 16, v240
	v_and_b32_e32 v95, 0xffff0000, v240
	v_pk_add_f32 v[90:91], v[90:91], 1.0 op_sel_hi:[1,0]
	s_nop 0
	v_rcp_f32_e32 v91, v91
	v_rcp_f32_e32 v90, v90
	v_add_f32_e32 v0, v92, v162
	v_mul_f32_e32 v0, 0xbfb8aa3b, v0
	v_pk_mul_f32 v[124:125], v[90:91], v[94:95]
	v_exp_f32_e32 v90, v0
	v_add_f32_e32 v0, v93, v162
	v_mul_f32_e32 v0, 0xbfb8aa3b, v0
	v_exp_f32_e32 v91, v0
	v_lshlrev_b32_e32 v92, 16, v241
	v_and_b32_e32 v93, 0xffff0000, v241
	v_pk_add_f32 v[90:91], v[90:91], 1.0 op_sel_hi:[1,0]
	s_nop 0
	v_rcp_f32_e32 v91, v91
	v_rcp_f32_e32 v90, v90
	s_nop 0
	v_pk_mul_f32 v[120:121], v[90:91], v[92:93]
	s_and_b64 vcc, exec, s[8:9]
	s_cbranch_vccnz .LBB0_150
	v_lshlrev_b32_e32 v90, 16, v242
	v_and_b32_e32 v91, 0xffff0000, v242
	v_pk_add_f32 v[122:123], v[122:123], v[90:91]
	v_lshlrev_b32_e32 v90, 16, v243
	v_and_b32_e32 v91, 0xffff0000, v243
	v_pk_add_f32 v[118:119], v[118:119], v[90:91]
	v_lshlrev_b32_e32 v90, 16, v244
	v_and_b32_e32 v91, 0xffff0000, v244
	v_pk_add_f32 v[124:125], v[124:125], v[90:91]
	v_lshlrev_b32_e32 v90, 16, v245
	v_and_b32_e32 v91, 0xffff0000, v245
	v_pk_add_f32 v[120:121], v[120:121], v[90:91]

; DI float sigm(float x) { return 1.f / (1.f + __expf(-x)); }
; DI u32x4 pack8(const float* f) { u32x4 o; o.x = pack2(f[0], f[1]); o.y = pack2(f[2], f[3]); o.z = pack2(f[4], f[5]); o.w = pack2(f[6], f[7]); return o; }
; DI void gate_reg(PREF p, int l, int n, f32x4 (&acc)[2][2][4][2], int dt) {
;     ...
; #pragma unroll
;       for (int m = 0; m < 4; ++m) {
;         float b[8]; unpack8(bn[m], b);
;         float v[8];
; #pragma unroll
;         for (int nn = 0; nn < 2; ++nn)
; #pragma unroll
;           for (int j = 0; j < 4; ++j) v[nn * 4 + j] = sigm(acc[ai][bj][m][nn][j] + bias[bj][nn]) * b[nn * 4 + j];
;         if (n > 0) {
;           float o[8]; unpack8(pv[m], o);
; #pragma unroll
;           for (int e = 0; e < 8; ++e) v[e] += o[e];
;         }
;         if (n < 3) ssum[((ai * 2 + bj) * 4 + m) * 64] = pack8(v);
; #pragma unroll
;         for (int nn = 0; nn < 2; ++nn)
; #pragma unroll
;           for (int j = 0; j < 4; ++j) acc[ai][bj][m][nn][j] = v[nn * 4 + j];
;       }
.LBB0_152:
	v_add_f32_e32 v0, v86, v182
	v_mul_f32_e32 v0, 0xbfb8aa3b, v0
	v_exp_f32_e32 v86, v0
	v_add_f32_e32 v0, v87, v182
	v_mul_f32_e32 v0, 0xbfb8aa3b, v0
	v_exp_f32_e32 v87, v0
	v_lshlrev_b32_e32 v90, 16, v246
	v_and_b32_e32 v91, 0xffff0000, v246
	v_pk_add_f32 v[86:87], v[86:87], 1.0 op_sel_hi:[1,0]
	s_nop 0
	v_rcp_f32_e32 v87, v87
	v_rcp_f32_e32 v86, v86
	v_add_f32_e32 v0, v88, v182
	v_mul_f32_e32 v0, 0xbfb8aa3b, v0
	v_pk_mul_f32 v[126:127], v[86:87], v[90:91]
	v_exp_f32_e32 v86, v0
	v_add_f32_e32 v0, v89, v182
	v_mul_f32_e32 v0, 0xbfb8aa3b, v0
	v_exp_f32_e32 v87, v0
	v_lshlrev_b32_e32 v88, 16, v247
	v_and_b32_e32 v89, 0xffff0000, v247
	v_pk_add_f32 v[86:87], v[86:87], 1.0 op_sel_hi:[1,0]
	s_nop 0
	v_rcp_f32_e32 v87, v87
	v_rcp_f32_e32 v86, v86
	v_add_f32_e32 v0, v82, v162
	v_mul_f32_e32 v0, 0xbfb8aa3b, v0
	v_exp_f32_e32 v82, v0
	v_add_f32_e32 v0, v83, v162
	v_mul_f32_e32 v0, 0xbfb8aa3b, v0
	v_exp_f32_e32 v83, v0
	v_pk_mul_f32 v[114:115], v[86:87], v[88:89]
	v_lshlrev_b32_e32 v86, 16, v248
	v_and_b32_e32 v87, 0xffff0000, v248
	v_pk_add_f32 v[82:83], v[82:83], 1.0 op_sel_hi:[1,0]
	s_nop 0
	v_rcp_f32_e32 v83, v83
	v_rcp_f32_e32 v82, v82
	v_add_f32_e32 v0, v84, v162
	v_mul_f32_e32 v0, 0xbfb8aa3b, v0
	v_pk_mul_f32 v[128:129], v[82:83], v[86:87]
	v_exp_f32_e32 v82, v0
	v_add_f32_e32 v0, v85, v162
	v_mul_f32_e32 v0, 0xbfb8aa3b, v0
	v_exp_f32_e32 v83, v0
	v_lshlrev_b32_e32 v84, 16, v249
	v_and_b32_e32 v85, 0xffff0000, v249
	v_pk_add_f32 v[82:83], v[82:83], 1.0 op_sel_hi:[1,0]
	s_nop 0
	v_rcp_f32_e32 v83, v83
	v_rcp_f32_e32 v82, v82
	s_nop 0
	v_pk_mul_f32 v[116:117], v[82:83], v[84:85]
	s_and_b64 vcc, exec, s[8:9]
	s_cbranch_vccnz .LBB0_154
	v_lshlrev_b32_e32 v82, 16, v250
	v_and_b32_e32 v83, 0xffff0000, v250
	v_pk_add_f32 v[126:127], v[126:127], v[82:83]
	v_lshlrev_b32_e32 v82, 16, v251
	v_and_b32_e32 v83, 0xffff0000, v251
	v_pk_add_f32 v[114:115], v[114:115], v[82:83]
	v_lshlrev_b32_e32 v82, 16, v252
	v_and_b32_e32 v83, 0xffff0000, v252
	v_pk_add_f32 v[128:129], v[128:129], v[82:83]
	v_lshlrev_b32_e32 v82, 16, v253
	v_and_b32_e32 v83, 0xffff0000, v253
	v_pk_add_f32 v[116:117], v[116:117], v[82:83]

; DI void gate_reg(PREF p, int l, int n, f32x4 (&acc)[2][2][4][2], int dt) {
;     ...
;       u32x4 bn[4], pv[4];
; #pragma unroll
;       for (int m = 0; m < 4; ++m) {
;         bn[m] = sbn[((ai * 2 + bj) * 4 + m) * 64];
;         if (n > 0) pv[m] = ssum[((ai * 2 + bj) * 4 + m) * 64];
;       }
.LBB0_156:
	s_mov_b64 s[98:99], 0x3000
	v_lshl_add_u64 v[246:247], v[166:167], 0, s[98:99]
	v_lshl_add_u64 v[250:251], v[164:165], 0, s[98:99]
	global_load_dwordx4 v[222:225], v[246:247], off
	global_load_dwordx4 v[226:229], v[250:251], off
	global_load_dwordx4 v[230:233], v[246:247], off offset:1024
	global_load_dwordx4 v[234:237], v[250:251], off offset:1024
	global_load_dwordx4 v[238:241], v[246:247], off offset:2048
	global_load_dwordx4 v[242:245], v[250:251], off offset:2048
	global_load_dwordx4 v[246:249], v[246:247], off offset:3072
	global_load_dwordx4 v[250:253], v[250:251], off offset:3072
	s_cmp_eq_u32 s23, 3
	s_cbranch_scc1 .Lmy_gw_g2_n3
	s_waitcnt vmcnt(12)
	s_branch .Lmy_gw_g2_d

; DI float sigm(float x) { return 1.f / (1.f + __expf(-x)); }
; DI u32x4 pack8(const float* f) { u32x4 o; o.x = pack2(f[0], f[1]); o.y = pack2(f[2], f[3]); o.z = pack2(f[4], f[5]); o.w = pack2(f[6], f[7]); return o; }
; DI void gate_reg(PREF p, int l, int n, f32x4 (&acc)[2][2][4][2], int dt) {
;     ...
;       u32x4 bn[4], pv[4];
; #pragma unroll
;       for (int m = 0; m < 4; ++m) {
;         bn[m] = sbn[((ai * 2 + bj) * 4 + m) * 64];
;         if (n > 0) pv[m] = ssum[((ai * 2 + bj) * 4 + m) * 64];
;       }
; #pragma unroll
;       for (int m = 0; m < 4; ++m) {
;         float b[8]; unpack8(bn[m], b);
;         float v[8];
; #pragma unroll
;         for (int nn = 0; nn < 2; ++nn)
; #pragma unroll
;           for (int j = 0; j < 4; ++j) v[nn * 4 + j] = sigm(acc[ai][bj][m][nn][j] + bias[bj][nn]) * b[nn * 4 + j];
;         if (n > 0) {
;           float o[8]; unpack8(pv[m], o);
; #pragma unroll
;           for (int e = 0; e < 8; ++e) v[e] += o[e];
;         }
;         if (n < 3) ssum[((ai * 2 + bj) * 4 + m) * 64] = pack8(v);
; #pragma unroll
;         for (int nn = 0; nn < 2; ++nn)
; #pragma unroll
;           for (int j = 0; j < 4; ++j) acc[ai][bj][m][nn][j] = v[nn * 4 + j];
;       }
.Lmy_gw_g2_d:
	s_and_b64 vcc, exec, s[8:9]
	s_cbranch_vccnz .LBB0_158
.LBB0_158:
	s_and_b64 vcc, exec, s[8:9]
	s_cbranch_vccnz .LBB0_160
.LBB0_160:
	s_and_b64 vcc, exec, s[8:9]
	s_cbranch_vccnz .LBB0_162
.LBB0_162:
	s_and_b64 vcc, exec, s[8:9]
	s_cbranch_vccnz .LBB0_164
.LBB0_164:
	v_add_f32_e32 v0, v78, v184
	v_mul_f32_e32 v0, 0xbfb8aa3b, v0
	v_exp_f32_e32 v78, v0
	v_add_f32_e32 v0, v79, v184
	v_mul_f32_e32 v0, 0xbfb8aa3b, v0
	v_exp_f32_e32 v79, v0
	v_lshlrev_b32_e32 v186, 16, v190
	v_and_b32_e32 v187, 0xffff0000, v190
	v_pk_add_f32 v[78:79], v[78:79], 1.0 op_sel_hi:[1,0]
	s_nop 0
	v_rcp_f32_e32 v79, v79
	v_rcp_f32_e32 v78, v78
	v_add_f32_e32 v0, v80, v184
	v_mul_f32_e32 v0, 0xbfb8aa3b, v0
	v_exp_f32_e32 v80, v0
	v_add_f32_e32 v0, v81, v184
	v_mul_f32_e32 v0, 0xbfb8aa3b, v0
	v_exp_f32_e32 v81, v0
	v_pk_mul_f32 v[78:79], v[78:79], v[186:187]
	v_lshlrev_b32_e32 v94, 16, v191
	v_and_b32_e32 v95, 0xffff0000, v191
	v_pk_add_f32 v[80:81], v[80:81], 1.0 op_sel_hi:[1,0]
	s_nop 0
	v_rcp_f32_e32 v81, v81
	v_rcp_f32_e32 v80, v80
	v_add_f32_e32 v0, v74, v183
	v_mul_f32_e32 v0, 0xbfb8aa3b, v0
	v_exp_f32_e32 v74, v0
	v_add_f32_e32 v0, v75, v183
	v_mul_f32_e32 v0, 0xbfb8aa3b, v0
	v_exp_f32_e32 v75, v0
	v_pk_mul_f32 v[80:81], v[80:81], v[94:95]
	v_lshlrev_b32_e32 v94, 16, v192
	v_and_b32_e32 v95, 0xffff0000, v192
	v_pk_add_f32 v[74:75], v[74:75], 1.0 op_sel_hi:[1,0]
	s_nop 0
	v_rcp_f32_e32 v75, v75
	v_rcp_f32_e32 v74, v74
	v_add_f32_e32 v0, v76, v183
	v_mul_f32_e32 v0, 0xbfb8aa3b, v0
	v_exp_f32_e32 v76, v0
	v_add_f32_e32 v0, v77, v183
	v_mul_f32_e32 v0, 0xbfb8aa3b, v0
	v_exp_f32_e32 v77, v0
	v_pk_mul_f32 v[74:75], v[74:75], v[94:95]
	v_lshlrev_b32_e32 v94, 16, v193
	v_and_b32_e32 v95, 0xffff0000, v193
	v_pk_add_f32 v[76:77], v[76:77], 1.0 op_sel_hi:[1,0]
	s_nop 0
	v_rcp_f32_e32 v77, v77
	v_rcp_f32_e32 v76, v76
	s_nop 0
	v_pk_mul_f32 v[76:77], v[76:77], v[94:95]
	s_and_b64 vcc, exec, s[8:9]
	s_cbranch_vccnz .LBB0_166
	v_lshlrev_b32_e32 v94, 16, v194
	v_and_b32_e32 v95, 0xffff0000, v194
	v_pk_add_f32 v[78:79], v[78:79], v[94:95]
	v_lshlrev_b32_e32 v94, 16, v195
	v_and_b32_e32 v95, 0xffff0000, v195
	v_pk_add_f32 v[80:81], v[80:81], v[94:95]
	v_lshlrev_b32_e32 v94, 16, v196
	v_and_b32_e32 v95, 0xffff0000, v196
	v_pk_add_f32 v[74:75], v[74:75], v[94:95]
	v_lshlrev_b32_e32 v94, 16, v197
	v_and_b32_e32 v95, 0xffff0000, v197
	v_pk_add_f32 v[76:77], v[76:77], v[94:95]

; DI float sigm(float x) { return 1.f / (1.f + __expf(-x)); }
; DI u32x4 pack8(const float* f) { u32x4 o; o.x = pack2(f[0], f[1]); o.y = pack2(f[2], f[3]); o.z = pack2(f[4], f[5]); o.w = pack2(f[6], f[7]); return o; }
; DI void gate_reg(PREF p, int l, int n, f32x4 (&acc)[2][2][4][2], int dt) {
;     ...
; #pragma unroll
;       for (int m = 0; m < 4; ++m) {
;         float b[8]; unpack8(bn[m], b);
;         float v[8];
; #pragma unroll
;         for (int nn = 0; nn < 2; ++nn)
; #pragma unroll
;           for (int j = 0; j < 4; ++j) v[nn * 4 + j] = sigm(acc[ai][bj][m][nn][j] + bias[bj][nn]) * b[nn * 4 + j];
;         if (n > 0) {
;           float o[8]; unpack8(pv[m], o);
; #pragma unroll
;           for (int e = 0; e < 8; ++e) v[e] += o[e];
;         }
;         if (n < 3) ssum[((ai * 2 + bj) * 4 + m) * 64] = pack8(v);
; #pragma unroll
;         for (int nn = 0; nn < 2; ++nn)
; #pragma unroll
;           for (int j = 0; j < 4; ++j) acc[ai][bj][m][nn][j] = v[nn * 4 + j];
;       }
.LBB0_168:
	v_add_f32_e32 v0, v70, v184
	v_mul_f32_e32 v0, 0xbfb8aa3b, v0
	v_exp_f32_e32 v70, v0
	v_add_f32_e32 v0, v71, v184
	v_mul_f32_e32 v0, 0xbfb8aa3b, v0
	v_exp_f32_e32 v71, v0
	v_lshlrev_b32_e32 v94, 16, v198
	v_and_b32_e32 v95, 0xffff0000, v198
	v_pk_add_f32 v[70:71], v[70:71], 1.0 op_sel_hi:[1,0]
	s_nop 0
	v_rcp_f32_e32 v71, v71
	v_rcp_f32_e32 v70, v70
	v_add_f32_e32 v0, v72, v184
	v_mul_f32_e32 v0, 0xbfb8aa3b, v0
	v_exp_f32_e32 v72, v0
	v_add_f32_e32 v0, v73, v184
	v_mul_f32_e32 v0, 0xbfb8aa3b, v0
	v_exp_f32_e32 v73, v0
	v_pk_mul_f32 v[70:71], v[70:71], v[94:95]
	v_lshlrev_b32_e32 v90, 16, v199
	v_and_b32_e32 v91, 0xffff0000, v199
	v_pk_add_f32 v[72:73], v[72:73], 1.0 op_sel_hi:[1,0]
	s_nop 0
	v_rcp_f32_e32 v73, v73
	v_rcp_f32_e32 v72, v72
	v_add_f32_e32 v0, v66, v183
	v_mul_f32_e32 v0, 0xbfb8aa3b, v0
	v_exp_f32_e32 v66, v0
	v_add_f32_e32 v0, v67, v183
	v_mul_f32_e32 v0, 0xbfb8aa3b, v0
	v_exp_f32_e32 v67, v0
	v_pk_mul_f32 v[72:73], v[72:73], v[90:91]
	v_lshlrev_b32_e32 v90, 16, v200
	v_and_b32_e32 v91, 0xffff0000, v200
	v_pk_add_f32 v[66:67], v[66:67], 1.0 op_sel_hi:[1,0]
	s_nop 0
	v_rcp_f32_e32 v67, v67
	v_rcp_f32_e32 v66, v66
	v_add_f32_e32 v0, v68, v183
	v_mul_f32_e32 v0, 0xbfb8aa3b, v0
	v_exp_f32_e32 v68, v0
	v_add_f32_e32 v0, v69, v183
	v_mul_f32_e32 v0, 0xbfb8aa3b, v0
	v_exp_f32_e32 v69, v0
	v_pk_mul_f32 v[66:67], v[66:67], v[90:91]
	v_lshlrev_b32_e32 v90, 16, v201
	v_and_b32_e32 v91, 0xffff0000, v201
	v_pk_add_f32 v[68:69], v[68:69], 1.0 op_sel_hi:[1,0]
	s_nop 0
	v_rcp_f32_e32 v69, v69
	v_rcp_f32_e32 v68, v68
	s_nop 0
	v_pk_mul_f32 v[68:69], v[68:69], v[90:91]
	s_and_b64 vcc, exec, s[8:9]
	s_cbranch_vccnz .LBB0_170
	v_lshlrev_b32_e32 v90, 16, v202
	v_and_b32_e32 v91, 0xffff0000, v202
	v_pk_add_f32 v[70:71], v[70:71], v[90:91]
	v_lshlrev_b32_e32 v90, 16, v203
	v_and_b32_e32 v91, 0xffff0000, v203
	v_pk_add_f32 v[72:73], v[72:73], v[90:91]
	v_lshlrev_b32_e32 v90, 16, v204
	v_and_b32_e32 v91, 0xffff0000, v204
	v_pk_add_f32 v[66:67], v[66:67], v[90:91]
	v_lshlrev_b32_e32 v90, 16, v205
	v_and_b32_e32 v91, 0xffff0000, v205
	v_pk_add_f32 v[68:69], v[68:69], v[90:91]

; DI float sigm(float x) { return 1.f / (1.f + __expf(-x)); }
; DI u32x4 pack8(const float* f) { u32x4 o; o.x = pack2(f[0], f[1]); o.y = pack2(f[2], f[3]); o.z = pack2(f[4], f[5]); o.w = pack2(f[6], f[7]); return o; }
; DI void gate_reg(PREF p, int l, int n, f32x4 (&acc)[2][2][4][2], int dt) {
;     ...
; #pragma unroll
;       for (int m = 0; m < 4; ++m) {
;         float b[8]; unpack8(bn[m], b);
;         float v[8];
; #pragma unroll
;         for (int nn = 0; nn < 2; ++nn)
; #pragma unroll
;           for (int j = 0; j < 4; ++j) v[nn * 4 + j] = sigm(acc[ai][bj][m][nn][j] + bias[bj][nn]) * b[nn * 4 + j];
;         if (n > 0) {
;           float o[8]; unpack8(pv[m], o);
; #pragma unroll
;           for (int e = 0; e < 8; ++e) v[e] += o[e];
;         }
;         if (n < 3) ssum[((ai * 2 + bj) * 4 + m) * 64] = pack8(v);
; #pragma unroll
;         for (int nn = 0; nn < 2; ++nn)
; #pragma unroll
;           for (int j = 0; j < 4; ++j) acc[ai][bj][m][nn][j] = v[nn * 4 + j];
;       }
.LBB0_172:
	v_add_f32_e32 v0, v62, v184
	v_mul_f32_e32 v0, 0xbfb8aa3b, v0
	v_exp_f32_e32 v62, v0
	v_add_f32_e32 v0, v63, v184
	v_mul_f32_e32 v0, 0xbfb8aa3b, v0
	v_exp_f32_e32 v63, v0
	v_lshlrev_b32_e32 v90, 16, v206
	v_and_b32_e32 v91, 0xffff0000, v206
	v_pk_add_f32 v[62:63], v[62:63], 1.0 op_sel_hi:[1,0]
	s_nop 0
	v_rcp_f32_e32 v63, v63
	v_rcp_f32_e32 v62, v62
	v_add_f32_e32 v0, v64, v184
	v_mul_f32_e32 v0, 0xbfb8aa3b, v0
	v_pk_mul_f32 v[90:91], v[62:63], v[90:91]
	v_exp_f32_e32 v62, v0
	v_add_f32_e32 v0, v65, v184
	v_mul_f32_e32 v0, 0xbfb8aa3b, v0
	v_exp_f32_e32 v63, v0
	v_lshlrev_b32_e32 v64, 16, v207
	v_and_b32_e32 v65, 0xffff0000, v207
	v_pk_add_f32 v[62:63], v[62:63], 1.0 op_sel_hi:[1,0]
	s_nop 0
	v_rcp_f32_e32 v63, v63
	v_rcp_f32_e32 v62, v62
	v_add_f32_e32 v0, v58, v183
	v_mul_f32_e32 v0, 0xbfb8aa3b, v0
	v_exp_f32_e32 v58, v0
	v_add_f32_e32 v0, v59, v183
	v_mul_f32_e32 v0, 0xbfb8aa3b, v0
	v_exp_f32_e32 v59, v0
	v_pk_mul_f32 v[86:87], v[62:63], v[64:65]
	v_lshlrev_b32_e32 v62, 16, v208
	v_and_b32_e32 v63, 0xffff0000, v208
	v_pk_add_f32 v[58:59], v[58:59], 1.0 op_sel_hi:[1,0]
	s_nop 0
	v_rcp_f32_e32 v59, v59
	v_rcp_f32_e32 v58, v58
	v_add_f32_e32 v0, v60, v183
	v_mul_f32_e32 v0, 0xbfb8aa3b, v0
	v_pk_mul_f32 v[92:93], v[58:59], v[62:63]
	v_exp_f32_e32 v58, v0
	v_add_f32_e32 v0, v61, v183
	v_mul_f32_e32 v0, 0xbfb8aa3b, v0
	v_exp_f32_e32 v59, v0
	v_lshlrev_b32_e32 v60, 16, v209
	v_and_b32_e32 v61, 0xffff0000, v209
	v_pk_add_f32 v[58:59], v[58:59], 1.0 op_sel_hi:[1,0]
	s_nop 0
	v_rcp_f32_e32 v59, v59
	v_rcp_f32_e32 v58, v58
	s_nop 0
	v_pk_mul_f32 v[88:89], v[58:59], v[60:61]
	s_and_b64 vcc, exec, s[8:9]
	s_cbranch_vccnz .LBB0_174
	v_lshlrev_b32_e32 v58, 16, v210
	v_and_b32_e32 v59, 0xffff0000, v210
	v_pk_add_f32 v[90:91], v[90:91], v[58:59]
	v_lshlrev_b32_e32 v58, 16, v211
	v_and_b32_e32 v59, 0xffff0000, v211
	v_pk_add_f32 v[86:87], v[86:87], v[58:59]
	v_lshlrev_b32_e32 v58, 16, v212
	v_and_b32_e32 v59, 0xffff0000, v212
	v_pk_add_f32 v[92:93], v[92:93], v[58:59]
	v_lshlrev_b32_e32 v58, 16, v213
	v_and_b32_e32 v59, 0xffff0000, v213
	v_pk_add_f32 v[88:89], v[88:89], v[58:59]

; DI float sigm(float x) { return 1.f / (1.f + __expf(-x)); }
; DI u32x4 pack8(const float* f) { u32x4 o; o.x = pack2(f[0], f[1]); o.y = pack2(f[2], f[3]); o.z = pack2(f[4], f[5]); o.w = pack2(f[6], f[7]); return o; }
; DI void gate_reg(PREF p, int l, int n, f32x4 (&acc)[2][2][4][2], int dt) {
;     ...
; #pragma unroll
;       for (int m = 0; m < 4; ++m) {
;         float b[8]; unpack8(bn[m], b);
;         float v[8];
; #pragma unroll
;         for (int nn = 0; nn < 2; ++nn)
; #pragma unroll
;           for (int j = 0; j < 4; ++j) v[nn * 4 + j] = sigm(acc[ai][bj][m][nn][j] + bias[bj][nn]) * b[nn * 4 + j];
;         if (n > 0) {
;           float o[8]; unpack8(pv[m], o);
; #pragma unroll
;           for (int e = 0; e < 8; ++e) v[e] += o[e];
;         }
;         if (n < 3) ssum[((ai * 2 + bj) * 4 + m) * 64] = pack8(v);
; #pragma unroll
;         for (int nn = 0; nn < 2; ++nn)
; #pragma unroll
;           for (int j = 0; j < 4; ++j) acc[ai][bj][m][nn][j] = v[nn * 4 + j];
;       }
.LBB0_176:
	v_add_f32_e32 v0, v54, v184
	v_mul_f32_e32 v0, 0xbfb8aa3b, v0
	v_exp_f32_e32 v54, v0
	v_add_f32_e32 v0, v55, v184
	v_mul_f32_e32 v0, 0xbfb8aa3b, v0
	v_exp_f32_e32 v55, v0
	v_lshlrev_b32_e32 v58, 16, v214
	v_and_b32_e32 v59, 0xffff0000, v214
	v_pk_add_f32 v[54:55], v[54:55], 1.0 op_sel_hi:[1,0]
	s_nop 0
	v_rcp_f32_e32 v55, v55
	v_rcp_f32_e32 v54, v54
	v_add_f32_e32 v0, v56, v184
	v_mul_f32_e32 v0, 0xbfb8aa3b, v0
	v_pk_mul_f32 v[94:95], v[54:55], v[58:59]
	v_exp_f32_e32 v54, v0
	v_add_f32_e32 v0, v57, v184
	v_mul_f32_e32 v0, 0xbfb8aa3b, v0
	v_exp_f32_e32 v55, v0
	v_lshlrev_b32_e32 v56, 16, v215
	v_and_b32_e32 v57, 0xffff0000, v215
	v_pk_add_f32 v[54:55], v[54:55], 1.0 op_sel_hi:[1,0]
	s_nop 0
	v_rcp_f32_e32 v55, v55
	v_rcp_f32_e32 v54, v54
	v_add_f32_e32 v0, v50, v183
	v_mul_f32_e32 v0, 0xbfb8aa3b, v0
	v_exp_f32_e32 v50, v0
	v_add_f32_e32 v0, v51, v183
	v_mul_f32_e32 v0, 0xbfb8aa3b, v0
	v_exp_f32_e32 v51, v0
	v_pk_mul_f32 v[82:83], v[54:55], v[56:57]
	v_lshlrev_b32_e32 v54, 16, v216
	v_and_b32_e32 v55, 0xffff0000, v216
	v_pk_add_f32 v[50:51], v[50:51], 1.0 op_sel_hi:[1,0]
	s_nop 0
	v_rcp_f32_e32 v51, v51
	v_rcp_f32_e32 v50, v50
	v_add_f32_e32 v0, v52, v183
	v_mul_f32_e32 v0, 0xbfb8aa3b, v0
	v_pk_mul_f32 v[96:97], v[50:51], v[54:55]
	v_exp_f32_e32 v50, v0
	v_add_f32_e32 v0, v53, v183
	v_mul_f32_e32 v0, 0xbfb8aa3b, v0
	v_exp_f32_e32 v51, v0
	v_lshlrev_b32_e32 v52, 16, v217
	v_and_b32_e32 v53, 0xffff0000, v217
	v_pk_add_f32 v[50:51], v[50:51], 1.0 op_sel_hi:[1,0]
	s_nop 0
	v_rcp_f32_e32 v51, v51
	v_rcp_f32_e32 v50, v50
	s_nop 0
	v_pk_mul_f32 v[84:85], v[50:51], v[52:53]
	s_and_b64 vcc, exec, s[8:9]
	s_cbranch_vccnz .LBB0_178
	v_lshlrev_b32_e32 v50, 16, v218
	v_and_b32_e32 v51, 0xffff0000, v218
	v_pk_add_f32 v[94:95], v[94:95], v[50:51]
	v_lshlrev_b32_e32 v50, 16, v219
	v_and_b32_e32 v51, 0xffff0000, v219
	v_pk_add_f32 v[82:83], v[82:83], v[50:51]
	v_lshlrev_b32_e32 v50, 16, v220
	v_and_b32_e32 v51, 0xffff0000, v220
	v_pk_add_f32 v[96:97], v[96:97], v[50:51]
	v_lshlrev_b32_e32 v50, 16, v221
	v_and_b32_e32 v51, 0xffff0000, v221
	v_pk_add_f32 v[84:85], v[84:85], v[50:51]

; DI float sigm(float x) { return 1.f / (1.f + __expf(-x)); }
; DI u32x4 pack8(const float* f) { u32x4 o; o.x = pack2(f[0], f[1]); o.y = pack2(f[2], f[3]); o.z = pack2(f[4], f[5]); o.w = pack2(f[6], f[7]); return o; }
; DI void gate_reg(PREF p, int l, int n, f32x4 (&acc)[2][2][4][2], int dt) {
;     ...
;       u32x4 bn[4], pv[4];
; #pragma unroll
;       for (int m = 0; m < 4; ++m) {
;         bn[m] = sbn[((ai * 2 + bj) * 4 + m) * 64];
;         if (n > 0) pv[m] = ssum[((ai * 2 + bj) * 4 + m) * 64];
;       }
; #pragma unroll
;       for (int m = 0; m < 4; ++m) {
;         float b[8]; unpack8(bn[m], b);
;         float v[8];
; #pragma unroll
;         for (int nn = 0; nn < 2; ++nn)
; #pragma unroll
;           for (int j = 0; j < 4; ++j) v[nn * 4 + j] = sigm(acc[ai][bj][m][nn][j] + bias[bj][nn]) * b[nn * 4 + j];
;         if (n > 0) {
;           float o[8]; unpack8(pv[m], o);
; #pragma unroll
;           for (int e = 0; e < 8; ++e) v[e] += o[e];
;         }
;         if (n < 3) ssum[((ai * 2 + bj) * 4 + m) * 64] = pack8(v);
; #pragma unroll
;         for (int nn = 0; nn < 2; ++nn)
; #pragma unroll
;           for (int j = 0; j < 4; ++j) acc[ai][bj][m][nn][j] = v[nn * 4 + j];
;       }
.LBB0_180:
	s_cmp_eq_u32 s23, 3
	s_cbranch_scc1 .Lmy_gw_g3_n3
	s_waitcnt vmcnt(4)
	s_branch .Lmy_gw_g3_d
.Lmy_gw_g3_n3:
	s_waitcnt vmcnt(0)
.Lmy_gw_g3_d:
	s_and_b64 vcc, exec, s[8:9]
	s_cbranch_vccnz .LBB0_182
.LBB0_182:
	s_and_b64 vcc, exec, s[8:9]
	s_cbranch_vccnz .LBB0_184
.LBB0_184:
	s_and_b64 vcc, exec, s[8:9]
	s_cbranch_vccnz .LBB0_186
.LBB0_186:
	s_and_b64 vcc, exec, s[8:9]
	s_cbranch_vccnz .LBB0_188
.LBB0_188:
	v_add_f32_e32 v0, v46, v182
	v_mul_f32_e32 v0, 0xbfb8aa3b, v0
	v_exp_f32_e32 v46, v0
	v_add_f32_e32 v0, v47, v182
	v_mul_f32_e32 v0, 0xbfb8aa3b, v0
	v_exp_f32_e32 v47, v0
	v_lshlrev_b32_e32 v166, 16, v222
	v_and_b32_e32 v167, 0xffff0000, v222
	v_pk_add_f32 v[46:47], v[46:47], 1.0 op_sel_hi:[1,0]
	s_nop 0
	v_rcp_f32_e32 v47, v47
	v_rcp_f32_e32 v46, v46
	v_add_f32_e32 v0, v48, v182
	v_mul_f32_e32 v0, 0xbfb8aa3b, v0
	v_exp_f32_e32 v48, v0
	v_add_f32_e32 v0, v49, v182
	v_mul_f32_e32 v0, 0xbfb8aa3b, v0
	v_exp_f32_e32 v49, v0
	v_pk_mul_f32 v[46:47], v[46:47], v[166:167]
	v_lshlrev_b32_e32 v62, 16, v223
	v_and_b32_e32 v63, 0xffff0000, v223
	v_pk_add_f32 v[48:49], v[48:49], 1.0 op_sel_hi:[1,0]
	s_nop 0
	v_rcp_f32_e32 v49, v49
	v_rcp_f32_e32 v48, v48
	v_add_f32_e32 v0, v38, v162
	v_mul_f32_e32 v0, 0xbfb8aa3b, v0
	v_exp_f32_e32 v38, v0
	v_add_f32_e32 v0, v39, v162
	v_mul_f32_e32 v0, 0xbfb8aa3b, v0
	v_exp_f32_e32 v39, v0
	v_pk_mul_f32 v[48:49], v[48:49], v[62:63]
	v_lshlrev_b32_e32 v62, 16, v224
	v_and_b32_e32 v63, 0xffff0000, v224
	v_pk_add_f32 v[38:39], v[38:39], 1.0 op_sel_hi:[1,0]
	s_nop 0
	v_rcp_f32_e32 v39, v39
	v_rcp_f32_e32 v38, v38
	v_add_f32_e32 v0, v40, v162
	v_mul_f32_e32 v0, 0xbfb8aa3b, v0
	v_exp_f32_e32 v40, v0
	v_add_f32_e32 v0, v41, v162
	v_mul_f32_e32 v0, 0xbfb8aa3b, v0
	v_exp_f32_e32 v41, v0
	v_pk_mul_f32 v[38:39], v[38:39], v[62:63]
	v_lshlrev_b32_e32 v62, 16, v225
	v_and_b32_e32 v63, 0xffff0000, v225
	v_pk_add_f32 v[40:41], v[40:41], 1.0 op_sel_hi:[1,0]
	s_nop 0
	v_rcp_f32_e32 v41, v41
	v_rcp_f32_e32 v40, v40
	s_nop 0
	v_pk_mul_f32 v[40:41], v[40:41], v[62:63]
	s_and_b64 vcc, exec, s[8:9]
	s_cbranch_vccnz .LBB0_190
	v_lshlrev_b32_e32 v62, 16, v226
	v_and_b32_e32 v63, 0xffff0000, v226
	v_lshlrev_b32_e32 v42, 16, v227
	v_and_b32_e32 v43, 0xffff0000, v227
	v_pk_add_f32 v[48:49], v[48:49], v[42:43]
	v_lshlrev_b32_e32 v42, 16, v228
	v_and_b32_e32 v43, 0xffff0000, v228
	v_pk_add_f32 v[38:39], v[38:39], v[42:43]
	v_lshlrev_b32_e32 v42, 16, v229
	v_and_b32_e32 v43, 0xffff0000, v229
	v_pk_add_f32 v[46:47], v[46:47], v[62:63]
	v_pk_add_f32 v[40:41], v[40:41], v[42:43]

; DI float sigm(float x) { return 1.f / (1.f + __expf(-x)); }
; DI u32x4 pack8(const float* f) { u32x4 o; o.x = pack2(f[0], f[1]); o.y = pack2(f[2], f[3]); o.z = pack2(f[4], f[5]); o.w = pack2(f[6], f[7]); return o; }
; DI void gate_reg(PREF p, int l, int n, f32x4 (&acc)[2][2][4][2], int dt) {
;     ...
; #pragma unroll
;       for (int m = 0; m < 4; ++m) {
;         float b[8]; unpack8(bn[m], b);
;         float v[8];
; #pragma unroll
;         for (int nn = 0; nn < 2; ++nn)
; #pragma unroll
;           for (int j = 0; j < 4; ++j) v[nn * 4 + j] = sigm(acc[ai][bj][m][nn][j] + bias[bj][nn]) * b[nn * 4 + j];
;         if (n > 0) {
;           float o[8]; unpack8(pv[m], o);
; #pragma unroll
;           for (int e = 0; e < 8; ++e) v[e] += o[e];
;         }
;         if (n < 3) ssum[((ai * 2 + bj) * 4 + m) * 64] = pack8(v);
; #pragma unroll
;         for (int nn = 0; nn < 2; ++nn)
; #pragma unroll
;           for (int j = 0; j < 4; ++j) acc[ai][bj][m][nn][j] = v[nn * 4 + j];
;       }
.LBB0_192:
	v_add_f32_e32 v0, v34, v182
	v_mul_f32_e32 v0, 0xbfb8aa3b, v0
	v_exp_f32_e32 v34, v0
	v_add_f32_e32 v0, v35, v182
	v_mul_f32_e32 v0, 0xbfb8aa3b, v0
	v_exp_f32_e32 v35, v0
	v_lshlrev_b32_e32 v42, 16, v230
	v_and_b32_e32 v43, 0xffff0000, v230
	v_pk_add_f32 v[34:35], v[34:35], 1.0 op_sel_hi:[1,0]
	s_nop 0
	v_rcp_f32_e32 v35, v35
	v_rcp_f32_e32 v34, v34
	v_add_f32_e32 v0, v36, v182
	v_mul_f32_e32 v0, 0xbfb8aa3b, v0
	v_exp_f32_e32 v36, v0
	v_add_f32_e32 v0, v37, v182
	v_mul_f32_e32 v0, 0xbfb8aa3b, v0
	v_exp_f32_e32 v37, v0
	v_pk_mul_f32 v[34:35], v[34:35], v[42:43]
	v_lshlrev_b32_e32 v42, 16, v231
	v_and_b32_e32 v43, 0xffff0000, v231
	v_pk_add_f32 v[36:37], v[36:37], 1.0 op_sel_hi:[1,0]
	s_nop 0
	v_rcp_f32_e32 v37, v37
	v_rcp_f32_e32 v36, v36
	v_add_f32_e32 v0, v26, v162
	v_mul_f32_e32 v0, 0xbfb8aa3b, v0
	v_exp_f32_e32 v26, v0
	v_add_f32_e32 v0, v27, v162
	v_mul_f32_e32 v0, 0xbfb8aa3b, v0
	v_exp_f32_e32 v27, v0
	v_pk_mul_f32 v[36:37], v[36:37], v[42:43]
	v_lshlrev_b32_e32 v42, 16, v232
	v_and_b32_e32 v43, 0xffff0000, v232
	v_pk_add_f32 v[26:27], v[26:27], 1.0 op_sel_hi:[1,0]
	s_nop 0
	v_rcp_f32_e32 v27, v27
	v_rcp_f32_e32 v26, v26
	v_add_f32_e32 v0, v28, v162
	v_mul_f32_e32 v0, 0xbfb8aa3b, v0
	v_exp_f32_e32 v28, v0
	v_add_f32_e32 v0, v29, v162
	v_mul_f32_e32 v0, 0xbfb8aa3b, v0
	v_exp_f32_e32 v29, v0
	v_pk_mul_f32 v[26:27], v[26:27], v[42:43]
	v_lshlrev_b32_e32 v42, 16, v233
	v_and_b32_e32 v43, 0xffff0000, v233
	v_pk_add_f32 v[28:29], v[28:29], 1.0 op_sel_hi:[1,0]
	s_nop 0
	v_rcp_f32_e32 v29, v29
	v_rcp_f32_e32 v28, v28
	s_nop 0
	v_pk_mul_f32 v[28:29], v[28:29], v[42:43]
	s_and_b64 vcc, exec, s[8:9]
	s_cbranch_vccnz .LBB0_194
	v_lshlrev_b32_e32 v42, 16, v234
	v_and_b32_e32 v43, 0xffff0000, v234
	v_lshlrev_b32_e32 v30, 16, v235
	v_and_b32_e32 v31, 0xffff0000, v235
	v_pk_add_f32 v[36:37], v[36:37], v[30:31]
	v_lshlrev_b32_e32 v30, 16, v236
	v_and_b32_e32 v31, 0xffff0000, v236
	v_pk_add_f32 v[26:27], v[26:27], v[30:31]
	v_lshlrev_b32_e32 v30, 16, v237
	v_and_b32_e32 v31, 0xffff0000, v237
	v_pk_add_f32 v[34:35], v[34:35], v[42:43]
	v_pk_add_f32 v[28:29], v[28:29], v[30:31]

; DI float sigm(float x) { return 1.f / (1.f + __expf(-x)); }
; DI u32x4 pack8(const float* f) { u32x4 o; o.x = pack2(f[0], f[1]); o.y = pack2(f[2], f[3]); o.z = pack2(f[4], f[5]); o.w = pack2(f[6], f[7]); return o; }
; DI void gate_reg(PREF p, int l, int n, f32x4 (&acc)[2][2][4][2], int dt) {
;     ...
; #pragma unroll
;       for (int m = 0; m < 4; ++m) {
;         float b[8]; unpack8(bn[m], b);
;         float v[8];
; #pragma unroll
;         for (int nn = 0; nn < 2; ++nn)
; #pragma unroll
;           for (int j = 0; j < 4; ++j) v[nn * 4 + j] = sigm(acc[ai][bj][m][nn][j] + bias[bj][nn]) * b[nn * 4 + j];
;         if (n > 0) {
;           float o[8]; unpack8(pv[m], o);
; #pragma unroll
;           for (int e = 0; e < 8; ++e) v[e] += o[e];
;         }
;         if (n < 3) ssum[((ai * 2 + bj) * 4 + m) * 64] = pack8(v);
; #pragma unroll
;         for (int nn = 0; nn < 2; ++nn)
; #pragma unroll
;           for (int j = 0; j < 4; ++j) acc[ai][bj][m][nn][j] = v[nn * 4 + j];
;       }
.LBB0_196:
	v_add_f32_e32 v0, v22, v182
	v_mul_f32_e32 v0, 0xbfb8aa3b, v0
	v_exp_f32_e32 v22, v0
	v_add_f32_e32 v0, v23, v182
	v_mul_f32_e32 v0, 0xbfb8aa3b, v0
	v_exp_f32_e32 v23, v0
	v_lshlrev_b32_e32 v30, 16, v238
	v_and_b32_e32 v31, 0xffff0000, v238
	v_pk_add_f32 v[22:23], v[22:23], 1.0 op_sel_hi:[1,0]
	s_nop 0
	v_rcp_f32_e32 v23, v23
	v_rcp_f32_e32 v22, v22
	v_add_f32_e32 v0, v24, v182
	v_mul_f32_e32 v0, 0xbfb8aa3b, v0
	v_exp_f32_e32 v24, v0
	v_add_f32_e32 v0, v25, v182
	v_mul_f32_e32 v0, 0xbfb8aa3b, v0
	v_exp_f32_e32 v25, v0
	v_pk_mul_f32 v[22:23], v[22:23], v[30:31]
	v_lshlrev_b32_e32 v30, 16, v239
	v_and_b32_e32 v31, 0xffff0000, v239
	v_pk_add_f32 v[24:25], v[24:25], 1.0 op_sel_hi:[1,0]
	s_nop 0
	v_rcp_f32_e32 v25, v25
	v_rcp_f32_e32 v24, v24
	v_add_f32_e32 v0, v14, v162
	v_mul_f32_e32 v0, 0xbfb8aa3b, v0
	v_exp_f32_e32 v14, v0
	v_add_f32_e32 v0, v15, v162
	v_mul_f32_e32 v0, 0xbfb8aa3b, v0
	v_exp_f32_e32 v15, v0
	v_pk_mul_f32 v[24:25], v[24:25], v[30:31]
	v_lshlrev_b32_e32 v30, 16, v240
	v_and_b32_e32 v31, 0xffff0000, v240
	v_pk_add_f32 v[14:15], v[14:15], 1.0 op_sel_hi:[1,0]
	s_nop 0
	v_rcp_f32_e32 v15, v15
	v_rcp_f32_e32 v14, v14
	v_add_f32_e32 v0, v16, v162
	v_mul_f32_e32 v0, 0xbfb8aa3b, v0
	v_exp_f32_e32 v16, v0
	v_add_f32_e32 v0, v17, v162
	v_mul_f32_e32 v0, 0xbfb8aa3b, v0
	v_exp_f32_e32 v17, v0
	v_pk_mul_f32 v[14:15], v[14:15], v[30:31]
	v_lshlrev_b32_e32 v30, 16, v241
	v_and_b32_e32 v31, 0xffff0000, v241
	v_pk_add_f32 v[16:17], v[16:17], 1.0 op_sel_hi:[1,0]
	s_nop 0
	v_rcp_f32_e32 v17, v17
	v_rcp_f32_e32 v16, v16
	s_nop 0
	v_pk_mul_f32 v[16:17], v[16:17], v[30:31]
	s_and_b64 vcc, exec, s[8:9]
	s_cbranch_vccnz .LBB0_198
	v_lshlrev_b32_e32 v30, 16, v242
	v_and_b32_e32 v31, 0xffff0000, v242
	v_lshlrev_b32_e32 v18, 16, v243
	v_and_b32_e32 v19, 0xffff0000, v243
	v_pk_add_f32 v[24:25], v[24:25], v[18:19]
	v_lshlrev_b32_e32 v18, 16, v244
	v_and_b32_e32 v19, 0xffff0000, v244
	v_pk_add_f32 v[14:15], v[14:15], v[18:19]
	v_lshlrev_b32_e32 v18, 16, v245
	v_and_b32_e32 v19, 0xffff0000, v245
	v_pk_add_f32 v[22:23], v[22:23], v[30:31]
	v_pk_add_f32 v[16:17], v[16:17], v[18:19]

; DI float sigm(float x) { return 1.f / (1.f + __expf(-x)); }
; DI u32x4 pack8(const float* f) { u32x4 o; o.x = pack2(f[0], f[1]); o.y = pack2(f[2], f[3]); o.z = pack2(f[4], f[5]); o.w = pack2(f[6], f[7]); return o; }
; DI void gate_reg(PREF p, int l, int n, f32x4 (&acc)[2][2][4][2], int dt) {
;     ...
; #pragma unroll
;       for (int m = 0; m < 4; ++m) {
;         float b[8]; unpack8(bn[m], b);
;         float v[8];
; #pragma unroll
;         for (int nn = 0; nn < 2; ++nn)
; #pragma unroll
;           for (int j = 0; j < 4; ++j) v[nn * 4 + j] = sigm(acc[ai][bj][m][nn][j] + bias[bj][nn]) * b[nn * 4 + j];
;         if (n > 0) {
;           float o[8]; unpack8(pv[m], o);
; #pragma unroll
;           for (int e = 0; e < 8; ++e) v[e] += o[e];
;         }
;         if (n < 3) ssum[((ai * 2 + bj) * 4 + m) * 64] = pack8(v);
; #pragma unroll
;         for (int nn = 0; nn < 2; ++nn)
; #pragma unroll
;           for (int j = 0; j < 4; ++j) acc[ai][bj][m][nn][j] = v[nn * 4 + j];
;       }
.LBB0_200:
	v_add_f32_e32 v0, v10, v182
	v_mul_f32_e32 v0, 0xbfb8aa3b, v0
	v_exp_f32_e32 v10, v0
	v_add_f32_e32 v0, v11, v182
	v_mul_f32_e32 v0, 0xbfb8aa3b, v0
	v_exp_f32_e32 v11, v0
	v_lshlrev_b32_e32 v18, 16, v246
	v_and_b32_e32 v19, 0xffff0000, v246
	v_pk_add_f32 v[10:11], v[10:11], 1.0 op_sel_hi:[1,0]
	s_nop 0
	v_rcp_f32_e32 v11, v11
	v_rcp_f32_e32 v10, v10
	v_add_f32_e32 v0, v12, v182
	v_mul_f32_e32 v0, 0xbfb8aa3b, v0
	v_exp_f32_e32 v12, v0
	v_add_f32_e32 v0, v13, v182
	v_mul_f32_e32 v0, 0xbfb8aa3b, v0
	v_exp_f32_e32 v13, v0
	v_pk_mul_f32 v[10:11], v[10:11], v[18:19]
	v_lshlrev_b32_e32 v18, 16, v247
	v_and_b32_e32 v19, 0xffff0000, v247
	v_pk_add_f32 v[12:13], v[12:13], 1.0 op_sel_hi:[1,0]
	s_nop 0
	v_rcp_f32_e32 v13, v13
	v_rcp_f32_e32 v12, v12
	v_add_f32_e32 v0, v2, v162
	v_mul_f32_e32 v0, 0xbfb8aa3b, v0
	v_exp_f32_e32 v2, v0
	v_add_f32_e32 v0, v3, v162
	v_mul_f32_e32 v0, 0xbfb8aa3b, v0
	v_exp_f32_e32 v3, v0
	v_pk_mul_f32 v[12:13], v[12:13], v[18:19]
	v_lshlrev_b32_e32 v18, 16, v248
	v_and_b32_e32 v19, 0xffff0000, v248
	v_pk_add_f32 v[2:3], v[2:3], 1.0 op_sel_hi:[1,0]
	s_nop 0
	v_rcp_f32_e32 v3, v3
	v_rcp_f32_e32 v2, v2
	v_add_f32_e32 v0, v4, v162
	v_mul_f32_e32 v0, 0xbfb8aa3b, v0
	v_exp_f32_e32 v4, v0
	v_add_f32_e32 v0, v5, v162
	v_mul_f32_e32 v0, 0xbfb8aa3b, v0
	v_exp_f32_e32 v5, v0
	v_pk_mul_f32 v[2:3], v[2:3], v[18:19]
	v_lshlrev_b32_e32 v18, 16, v249
	v_and_b32_e32 v19, 0xffff0000, v249
	v_pk_add_f32 v[4:5], v[4:5], 1.0 op_sel_hi:[1,0]
	s_nop 0
	v_rcp_f32_e32 v5, v5
	v_rcp_f32_e32 v4, v4
	s_nop 0
	v_pk_mul_f32 v[4:5], v[4:5], v[18:19]
	s_and_b64 vcc, exec, s[8:9]
	s_cbranch_vccnz .LBB0_202
	v_lshlrev_b32_e32 v18, 16, v250
	v_and_b32_e32 v19, 0xffff0000, v250
	v_lshlrev_b32_e32 v6, 16, v251
	v_and_b32_e32 v7, 0xffff0000, v251
	v_pk_add_f32 v[12:13], v[12:13], v[6:7]
	v_lshlrev_b32_e32 v6, 16, v252
	v_and_b32_e32 v7, 0xffff0000, v252
	v_pk_add_f32 v[2:3], v[2:3], v[6:7]
	v_lshlrev_b32_e32 v6, 16, v253
	v_and_b32_e32 v7, 0xffff0000, v253
	v_pk_add_f32 v[10:11], v[10:11], v[18:19]
	v_pk_add_f32 v[4:5], v[4:5], v[6:7]

; #define MFMA32(a, b, c) __builtin_amdgcn_mfma_f32_32x32x16_bf16((a), (b), (c), 0, 0, 0)
; template <int DQK, bool WIN>
; DI void attn_item(const u16* __restrict__ Qb, int ldq, const u16* __restrict__ Kb, int ldk, const u16* __restrict__ Vtb, int qb,
;                   float qscale, float sink2, const u16* __restrict__ zb, int ldz, u16* __restrict__ ob, int ldo, u16* lds) {
;     ...
;     bool active = (k0 <= q0 + 31);
;     if (WIN) active = active && (k0 + 63 >= q0 - 127);
;     if (active) {
;       f32x16 st[2];
; #pragma unroll
;       for (int kb = 0; kb < 2; ++kb) {
; #pragma unroll
;         for (int i = 0; i < 16; ++i) st[kb][i] = 0.f;
; #pragma unroll
;         for (int s = 0; s < NKS; ++s) {
;           bf16x8 a = *(const bf16x8*)(ks + (kb * 32 + r) * KST + 16 * s + 8 * hh);
;           st[kb] = MFMA32(a, qf[s], st[kb]);
;         }
;       }
;       float mx = -INFINITY;
; #pragma unroll
;       for (int kb = 0; kb < 2; ++kb)
; #pragma unroll
;         for (int i = 0; i < 16; ++i) {
;           float v = st[kb][i];
;           if (MASK) {
;             int kg = k0 + kb * 32 + (i & 3) + 8 * (i >> 2) + 4 * hh;
;             bool ok = kg <= qrow;
;             if (WIN) ok = ok && (qrow - kg < 128);
;             v = ok ? v : -INFINITY;
;             st[kb][i] = v;
;           }
;           mx = fmaxf(mx, v);
;         }
;       mx = fmaxf(mx, __shfl_xor(mx, 32));
.LBB0_233:
	s_add_i32 s0, s31, -1
	s_add_i32 s1, s20, 0xffffff40
	s_cmp_lt_u32 s0, s29
	v_cmp_le_i32_e64 s[8:9], s1, v154
	s_mov_b64 s[24:25], -1
	s_cbranch_scc1 .LBB0_239
	v_mov_b64_e32 v[64:65], v[16:17]
	v_mov_b64_e32 v[48:49], v[32:33]
	v_mov_b32_e32 v158, v157
	v_mov_b32_e32 v0, v142
	v_mov_b64_e32 v[62:63], v[14:15]
	v_mov_b64_e32 v[60:61], v[12:13]
	v_mov_b64_e32 v[58:59], v[10:11]
	v_mov_b64_e32 v[56:57], v[8:9]
	v_mov_b64_e32 v[54:55], v[6:7]
	v_mov_b64_e32 v[52:53], v[4:5]
	v_mov_b64_e32 v[50:51], v[2:3]
	v_mov_b64_e32 v[46:47], v[30:31]
	v_mov_b64_e32 v[44:45], v[28:29]
	v_mov_b64_e32 v[42:43], v[26:27]
	v_mov_b64_e32 v[40:41], v[24:25]
	v_mov_b64_e32 v[38:39], v[22:23]
	v_mov_b64_e32 v[36:37], v[20:21]
	v_mov_b64_e32 v[34:35], v[18:19]
	s_and_saveexec_b64 s[24:25], s[8:9]
	s_cbranch_execz .LBB0_238
	ds_read_b128 v[206:209], v155
	ds_read_b128 v[210:213], v155 offset:32
	ds_read_b128 v[214:217], v155 offset:64
	ds_read_b128 v[218:221], v155 offset:6688
	ds_read_b128 v[222:225], v155 offset:96
	ds_read_b128 v[226:229], v155 offset:128
	ds_read_b128 v[230:233], v155 offset:160
	ds_read_b128 v[234:237], v155 offset:6656
	ds_read_b128 v[238:241], v155 offset:6720
	ds_read_b128 v[242:245], v155 offset:6752
	ds_read_b128 v[246:249], v155 offset:6784
	ds_read_b128 v[250:253], v155 offset:6816
	v_mov_b32_e32 v196, v142
	s_waitcnt lgkmcnt(11)
	v_mfma_f32_32x32x16_bf16 v[50:65], v[206:209], v[66:69], 0
	s_waitcnt lgkmcnt(10)
	v_mfma_f32_32x32x16_bf16 v[50:65], v[210:213], v[70:73], v[50:65]
	s_waitcnt lgkmcnt(9)
	v_mfma_f32_32x32x16_bf16 v[50:65], v[214:217], v[74:77], v[50:65]
	s_waitcnt lgkmcnt(7)
	v_mfma_f32_32x32x16_bf16 v[50:65], v[222:225], v[78:81], v[50:65]
	s_waitcnt lgkmcnt(6)
	v_mfma_f32_32x32x16_bf16 v[50:65], v[226:229], v[82:85], v[50:65]
	s_waitcnt lgkmcnt(5)
	v_mfma_f32_32x32x16_bf16 v[50:65], v[230:233], v[86:89], v[50:65]
	s_waitcnt lgkmcnt(4)
	v_mfma_f32_32x32x16_bf16 v[34:49], v[234:237], v[66:69], 0
	v_mfma_f32_32x32x16_bf16 v[34:49], v[218:221], v[70:73], v[34:49]
	s_waitcnt lgkmcnt(3)
	v_mfma_f32_32x32x16_bf16 v[34:49], v[238:241], v[74:77], v[34:49]
	s_waitcnt lgkmcnt(2)
	v_mfma_f32_32x32x16_bf16 v[34:49], v[242:245], v[78:81], v[34:49]
	s_waitcnt lgkmcnt(1)
	v_mfma_f32_32x32x16_bf16 v[34:49], v[246:249], v[82:85], v[34:49]
	s_waitcnt lgkmcnt(0)
	v_mfma_f32_32x32x16_bf16 v[34:49], v[250:253], v[86:89], v[34:49]
	v_add_u32_e32 v158, s20, v146
	v_add_u32_e32 v0, 0xffffff40, v158
	v_cmp_le_i32_e32 vcc, v0, v130
	s_nop 1
	v_cndmask_b32_e32 v159, v176, v50, vcc
	v_cmp_lt_i32_e32 vcc, v0, v130
	s_nop 1
	v_cndmask_b32_e32 v0, v176, v51, vcc
	v_add_u32_e32 v51, 0xffffff42, v158
	v_cmp_le_i32_e32 vcc, v51, v130
	v_add_u32_e32 v51, 0xffffff43, v158
	v_max3_f32 v50, v159, s94, v0
	v_cndmask_b32_e32 v161, v176, v52, vcc
	v_cmp_le_i32_e32 vcc, v51, v130
	v_add_u32_e32 v51, 0xffffff48, v158
	s_nop 0
	v_cndmask_b32_e32 v160, v176, v53, vcc
	v_cmp_le_i32_e32 vcc, v51, v130
	v_add_u32_e32 v51, 0xffffff49, v158
	v_max3_f32 v50, v50, v161, v160
	v_cndmask_b32_e32 v164, v176, v54, vcc
	v_cmp_le_i32_e32 vcc, v51, v130
	v_add_u32_e32 v51, 0xffffff4a, v158
	s_nop 0
	v_cndmask_b32_e32 v162, v176, v55, vcc
	v_cmp_le_i32_e32 vcc, v51, v130
	v_add_u32_e32 v51, 0xffffff4b, v158
	v_max3_f32 v50, v50, v164, v162
	v_cndmask_b32_e32 v165, v176, v56, vcc
	v_cmp_le_i32_e32 vcc, v51, v130
	v_add_u32_e32 v51, 0xffffff50, v158
	s_nop 0
	v_cndmask_b32_e32 v166, v176, v57, vcc
	v_cmp_le_i32_e32 vcc, v51, v130
	v_add_u32_e32 v51, 0xffffff51, v158
	v_max3_f32 v50, v50, v165, v166
	v_cndmask_b32_e32 v205, v176, v58, vcc
	v_cmp_le_i32_e32 vcc, v51, v130
	v_add_u32_e32 v51, 0xffffff52, v158
	s_nop 0
	v_cndmask_b32_e32 v203, v176, v59, vcc
	v_cmp_le_i32_e32 vcc, v51, v130
	v_add_u32_e32 v51, 0xffffff53, v158
	v_max3_f32 v50, v50, v205, v203
	v_cndmask_b32_e32 v204, v176, v60, vcc
	v_cmp_le_i32_e32 vcc, v51, v130
	v_add_u32_e32 v51, 0xffffff58, v158
	s_nop 0
	v_cndmask_b32_e32 v201, v176, v61, vcc
	v_cmp_le_i32_e32 vcc, v51, v130
	v_add_u32_e32 v51, 0xffffff59, v158
	v_max3_f32 v50, v50, v204, v201
	v_cndmask_b32_e32 v202, v176, v62, vcc
	v_cmp_le_i32_e32 vcc, v51, v130
	v_add_u32_e32 v51, 0xffffff5a, v158
	s_nop 0
	v_cndmask_b32_e32 v199, v176, v63, vcc
	v_cmp_le_i32_e32 vcc, v51, v130
	v_add_u32_e32 v51, 0xffffff5b, v158
	v_max3_f32 v50, v50, v202, v199
	v_cndmask_b32_e32 v200, v176, v64, vcc
	v_cmp_le_i32_e32 vcc, v51, v130
	v_add_u32_e32 v51, 0xffffff60, v158
	s_nop 0
	v_cndmask_b32_e32 v197, v176, v65, vcc
	v_cmp_le_i32_e32 vcc, v51, v130
	v_max3_f32 v50, v50, v200, v197
	s_nop 0
	v_cndmask_b32_e32 v198, v176, v34, vcc
	v_add_u32_e32 v34, 0xffffff61, v158
	v_cmp_le_i32_e32 vcc, v34, v130
	s_nop 1
	v_cndmask_b32_e32 v195, v176, v35, vcc
	v_add_u32_e32 v35, 0xffffff62, v158
	v_cmp_le_i32_e32 vcc, v35, v130
	v_add_u32_e32 v35, 0xffffff63, v158
	v_max3_f32 v34, v50, v198, v195
	v_cndmask_b32_e32 v194, v176, v36, vcc
	v_cmp_le_i32_e32 vcc, v35, v130
	v_add_u32_e32 v35, 0xffffff68, v158
	v_and_b32_e32 v36, 64, v172
	v_cndmask_b32_e32 v193, v176, v37, vcc
	v_cmp_le_i32_e32 vcc, v35, v130
	v_add_u32_e32 v35, 0xffffff69, v158
	v_max3_f32 v34, v34, v194, v193
	v_cndmask_b32_e32 v192, v176, v38, vcc
	v_cmp_le_i32_e32 vcc, v35, v130
	v_add_u32_e32 v35, 0xffffff6a, v158
	v_add_u32_e32 v36, 64, v36
	v_cndmask_b32_e32 v167, v176, v39, vcc
	v_cmp_le_i32_e32 vcc, v35, v130
	v_add_u32_e32 v35, 0xffffff6b, v158
	v_max3_f32 v34, v34, v192, v167
	v_cndmask_b32_e32 v182, v176, v40, vcc
	v_cmp_le_i32_e32 vcc, v35, v130
	v_add_u32_e32 v35, 0xffffff70, v158
	v_mov_b64_e32 v[64:65], v[16:17]
	v_cndmask_b32_e32 v183, v176, v41, vcc
	v_cmp_le_i32_e32 vcc, v35, v130
	v_add_u32_e32 v35, 0xffffff71, v158
	v_max3_f32 v34, v34, v182, v183
	v_cndmask_b32_e32 v184, v176, v42, vcc
	v_cmp_le_i32_e32 vcc, v35, v130
	v_add_u32_e32 v35, 0xffffff72, v158
	v_mov_b64_e32 v[62:63], v[14:15]
	v_cndmask_b32_e32 v185, v176, v43, vcc
	v_cmp_le_i32_e32 vcc, v35, v130
	v_add_u32_e32 v35, 0xffffff73, v158
	v_max3_f32 v34, v34, v184, v185
	v_cndmask_b32_e32 v186, v176, v44, vcc
	v_cmp_le_i32_e32 vcc, v35, v130
	v_add_u32_e32 v35, 0xffffff78, v158
	v_mov_b64_e32 v[60:61], v[12:13]
	v_cndmask_b32_e32 v187, v176, v45, vcc
	v_cmp_le_i32_e32 vcc, v35, v130
	v_add_u32_e32 v35, 0xffffff79, v158
	v_max3_f32 v34, v34, v186, v187
	v_cndmask_b32_e32 v188, v176, v46, vcc
	v_cmp_le_i32_e32 vcc, v35, v130
	v_add_u32_e32 v35, 0xffffff7a, v158
	v_mov_b64_e32 v[58:59], v[10:11]
	v_cndmask_b32_e32 v189, v176, v47, vcc
	v_cmp_le_i32_e32 vcc, v35, v130
	v_add_u32_e32 v35, 0xffffff7b, v158
	v_max3_f32 v34, v34, v188, v189
	v_cndmask_b32_e32 v190, v176, v48, vcc
	v_cmp_le_i32_e32 vcc, v35, v130
	v_xor_b32_e32 v35, 32, v172
	v_mov_b64_e32 v[56:57], v[8:9]
	v_cndmask_b32_e32 v191, v176, v49, vcc
	v_cmp_lt_i32_e32 vcc, v35, v36
	v_max3_f32 v34, v34, v190, v191
	v_mov_b64_e32 v[54:55], v[6:7]
	v_cndmask_b32_e32 v35, v172, v35, vcc
	v_lshlrev_b32_e32 v35, 2, v35
	ds_bpermute_b32 v35, v35, v34
	v_mov_b64_e32 v[52:53], v[4:5]
	v_mov_b64_e32 v[50:51], v[2:3]
	s_waitcnt lgkmcnt(0)
; DI unsigned pack2(float a, float b) { unsigned r; asm("v_cvt_pk_bf16_f32 %0, %1, %2\n\ts_nop 1" : "=v"(r) : "v"(a), "v"(b)); return r; }
; #define MFMA32(a, b, c) __builtin_amdgcn_mfma_f32_32x32x16_bf16((a), (b), (c), 0, 0, 0)
; template <int DQK, bool WIN>
; DI void attn_item(const u16* __restrict__ Qb, int ldq, const u16* __restrict__ Kb, int ldk, const u16* __restrict__ Vtb, int qb,
;                   float qscale, float sink2, const u16* __restrict__ zb, int ldz, u16* __restrict__ ob, int ldo, u16* lds) {
;     ...
;       mx = fmaxf(mx, __shfl_xor(mx, 32));
;       const float mn = fmaxf(m, mx);
;       if (__any(mn != m)) {
;         const float alpha = __builtin_amdgcn_exp2f((m - mn) * qscale);
;         lsum *= alpha;
; #pragma unroll
;         for (int i = 0; i < 16; ++i) { o[0][i] *= alpha; o[1][i] *= alpha; }
;       }
;       m = mn;
;       const float nb = -mn * qscale;
;       float ps = 0.f;
; #pragma unroll
;       for (int kb = 0; kb < 2; ++kb)
; #pragma unroll
;         for (int i = 0; i < 16; ++i) { float pv = __builtin_amdgcn_exp2f(fmaf(st[kb][i], qscale, nb)); st[kb][i] = pv; ps += pv; }
;       lsum += ps;
; #pragma unroll
;       for (int kb = 0; kb < 2; ++kb)
; #pragma unroll
;         for (int s2 = 0; s2 < 2; ++s2) {
;           union { bf16x8 v; unsigned u[4]; } pf;
; #pragma unroll
;           for (int j = 0; j < 4; ++j) pf.u[j] = pack2(st[kb][8 * s2 + 2 * j], st[kb][8 * s2 + 2 * j + 1]);
; #pragma unroll
;           for (int vb = 0; vb < 2; ++vb) {
;             const bf16x8 vf = *(const bf16x8*)(vs + (vb * 32 + r) * 72 + (kb * 2 + s2) * 16 + hh * 8);
;             o[vb] = MFMA32(vf, pf.v, o[vb]);
;           }
;         }
	v_max3_f32 v158, v157, v34, v35
	v_mov_b64_e32 v[48:49], v[32:33]
	v_cmp_neq_f32_e32 vcc, v158, v157
	v_mov_b64_e32 v[46:47], v[30:31]
	v_mov_b64_e32 v[44:45], v[28:29]
	v_mov_b64_e32 v[42:43], v[26:27]
	v_mov_b64_e32 v[40:41], v[24:25]
	v_mov_b64_e32 v[38:39], v[22:23]
	v_mov_b64_e32 v[36:37], v[20:21]
	v_mov_b64_e32 v[34:35], v[18:19]
	s_cbranch_vccz .LBB0_237
	v_sub_f32_e32 v34, v157, v158
	v_mul_f32_e32 v34, 0x3e16c740, v34
	v_exp_f32_e32 v50, v34
	s_nop 0
	v_mul_f32_e32 v196, v142, v50
	v_pk_mul_f32 v[48:49], v[32:33], v[50:51] op_sel_hi:[1,0]
	v_pk_mul_f32 v[46:47], v[30:31], v[50:51] op_sel_hi:[1,0]
	v_pk_mul_f32 v[44:45], v[28:29], v[50:51] op_sel_hi:[1,0]
	v_pk_mul_f32 v[42:43], v[26:27], v[50:51] op_sel_hi:[1,0]
	v_pk_mul_f32 v[40:41], v[24:25], v[50:51] op_sel_hi:[1,0]
	v_pk_mul_f32 v[38:39], v[22:23], v[50:51] op_sel_hi:[1,0]
	v_pk_mul_f32 v[36:37], v[20:21], v[50:51] op_sel_hi:[1,0]
	v_pk_mul_f32 v[34:35], v[18:19], v[50:51] op_sel_hi:[1,0]
	v_pk_mul_f32 v[64:65], v[16:17], v[50:51] op_sel_hi:[1,0]
	v_pk_mul_f32 v[62:63], v[14:15], v[50:51] op_sel_hi:[1,0]
	v_pk_mul_f32 v[60:61], v[12:13], v[50:51] op_sel_hi:[1,0]
	v_pk_mul_f32 v[58:59], v[10:11], v[50:51] op_sel_hi:[1,0]
	v_pk_mul_f32 v[56:57], v[8:9], v[50:51] op_sel_hi:[1,0]
	v_pk_mul_f32 v[54:55], v[6:7], v[50:51] op_sel_hi:[1,0]
	v_pk_mul_f32 v[52:53], v[4:5], v[50:51] op_sel_hi:[1,0]
	v_pk_mul_f32 v[50:51], v[2:3], v[50:51] op_sel_hi:[1,0]
.LBB0_237:
	ds_read_b128 v[220:223], v156 offset:13312
	ds_read_b128 v[224:227], v156 offset:13344
	ds_read_b128 v[228:231], v156 offset:17920
	ds_read_b128 v[232:235], v156 offset:17952
	ds_read_b128 v[236:239], v156 offset:13376
	ds_read_b128 v[240:243], v156 offset:17984
	ds_read_b128 v[244:247], v156 offset:13408
	ds_read_b128 v[248:251], v156 offset:18016
	v_mul_f32_e32 v206, 0xbe16c740, v158
	v_fmamk_f32 v159, v159, 0x3e16c740, v206
	v_exp_f32_e32 v159, v159
	v_fmamk_f32 v0, v0, 0x3e16c740, v206
	v_exp_f32_e32 v208, v0
	v_fmamk_f32 v164, v164, 0x3e16c740, v206
	v_add_f32_e32 v207, 0, v159
	v_fmamk_f32 v161, v161, 0x3e16c740, v206
	v_add_f32_e32 v0, v208, v207
	v_exp_f32_e32 v207, v164
	v_fmamk_f32 v164, v165, 0x3e16c740, v206
	v_exp_f32_e32 v209, v164
	v_fmamk_f32 v164, v166, 0x3e16c740, v206
	v_exp_f32_e32 v210, v164
	v_fmamk_f32 v164, v205, 0x3e16c740, v206
	v_exp_f32_e32 v205, v164
	v_fmamk_f32 v164, v203, 0x3e16c740, v206
	v_exp_f32_e32 v203, v164
	v_fmamk_f32 v164, v204, 0x3e16c740, v206
	v_exp_f32_e32 v204, v164
	v_fmamk_f32 v164, v201, 0x3e16c740, v206
	v_exp_f32_e32 v201, v164
	v_fmamk_f32 v164, v202, 0x3e16c740, v206
	v_exp_f32_e32 v202, v164
	v_fmamk_f32 v164, v199, 0x3e16c740, v206
	v_exp_f32_e32 v199, v164
	v_fmamk_f32 v164, v200, 0x3e16c740, v206
	v_exp_f32_e32 v200, v164
	v_fmamk_f32 v164, v197, 0x3e16c740, v206
	v_exp_f32_e32 v197, v164
	v_fmamk_f32 v164, v198, 0x3e16c740, v206
	v_exp_f32_e32 v198, v164
	v_fmamk_f32 v164, v195, 0x3e16c740, v206
	v_exp_f32_e32 v195, v164
	v_fmamk_f32 v164, v194, 0x3e16c740, v206
	v_exp_f32_e32 v194, v164
	v_fmamk_f32 v164, v193, 0x3e16c740, v206
	v_exp_f32_e32 v193, v164
	v_fmamk_f32 v164, v192, 0x3e16c740, v206
	v_exp_f32_e32 v192, v164
	v_fmamk_f32 v164, v167, 0x3e16c740, v206
	v_exp_f32_e32 v211, v164
	v_fmamk_f32 v164, v182, 0x3e16c740, v206
	v_exp_f32_e32 v212, v164
	v_fmamk_f32 v164, v183, 0x3e16c740, v206
	v_exp_f32_e32 v213, v164
	v_fmamk_f32 v164, v184, 0x3e16c740, v206
	v_exp_f32_e32 v214, v164
	v_fmamk_f32 v164, v185, 0x3e16c740, v206
	v_exp_f32_e32 v215, v164
	v_fmamk_f32 v164, v186, 0x3e16c740, v206
	v_exp_f32_e32 v216, v164
	v_fmamk_f32 v164, v187, 0x3e16c740, v206
	v_exp_f32_e32 v217, v164
	v_fmamk_f32 v164, v188, 0x3e16c740, v206
	v_exp_f32_e32 v218, v164
	v_fmamk_f32 v164, v189, 0x3e16c740, v206
	v_fmamk_f32 v160, v160, 0x3e16c740, v206
	v_fmamk_f32 v162, v162, 0x3e16c740, v206
	v_exp_f32_e32 v219, v164
	v_fmamk_f32 v164, v190, 0x3e16c740, v206
	v_exp_f32_e32 v161, v161
	v_exp_f32_e32 v160, v160
	v_exp_f32_e32 v162, v162
	v_exp_f32_e32 v190, v164
	v_cvt_pk_bf16_f32 v164, v159, v208
	s_nop 1
	v_cvt_pk_bf16_f32 v165, v161, v160
	s_nop 1
	v_cvt_pk_bf16_f32 v166, v207, v162
	s_nop 1
	v_cvt_pk_bf16_f32 v167, v209, v210
	s_nop 1
	v_add_f32_e32 v0, v161, v0
	s_waitcnt lgkmcnt(7)
	v_mfma_f32_32x32x16_bf16 v[34:49], v[220:223], v[164:167], v[34:49]
	v_add_f32_e32 v0, v160, v0
	v_add_f32_e32 v0, v207, v0
	v_add_f32_e32 v0, v162, v0
	v_add_f32_e32 v0, v209, v0
	v_add_f32_e32 v0, v210, v0
	v_add_f32_e32 v0, v205, v0
	s_waitcnt lgkmcnt(5)
	v_mfma_f32_32x32x16_bf16 v[50:65], v[228:231], v[164:167], v[50:65]
	v_cvt_pk_bf16_f32 v164, v205, v203
	s_nop 1
	v_cvt_pk_bf16_f32 v165, v204, v201
	s_nop 1
	v_cvt_pk_bf16_f32 v166, v202, v199
	s_nop 1
	v_cvt_pk_bf16_f32 v167, v200, v197
	s_nop 1
	v_add_f32_e32 v0, v203, v0
	v_add_f32_e32 v0, v204, v0
	s_waitcnt lgkmcnt(4)
	v_mfma_f32_32x32x16_bf16 v[50:65], v[232:235], v[164:167], v[50:65]
	v_add_f32_e32 v0, v201, v0
	v_add_f32_e32 v0, v202, v0
	v_add_f32_e32 v0, v199, v0
	v_add_f32_e32 v0, v200, v0
	v_add_f32_e32 v0, v197, v0
	v_fmac_f32_e32 v206, 0x3e16c740, v191
	v_mfma_f32_32x32x16_bf16 v[34:49], v[224:227], v[164:167], v[34:49]
	v_cvt_pk_bf16_f32 v164, v198, v195
	s_nop 1
	v_cvt_pk_bf16_f32 v165, v194, v193
	s_nop 1
	v_cvt_pk_bf16_f32 v166, v192, v211
	s_nop 1
	v_cvt_pk_bf16_f32 v167, v212, v213
	s_nop 1
	v_add_f32_e32 v0, v198, v0
	v_exp_f32_e32 v191, v206
	v_add_f32_e32 v0, v195, v0
	s_waitcnt lgkmcnt(3)
	v_mfma_f32_32x32x16_bf16 v[34:49], v[236:239], v[164:167], v[34:49]
	v_add_f32_e32 v0, v194, v0
	v_add_f32_e32 v0, v193, v0
	v_add_f32_e32 v0, v192, v0
	v_add_f32_e32 v0, v211, v0
	v_add_f32_e32 v0, v212, v0
	v_add_f32_e32 v0, v213, v0
	s_waitcnt lgkmcnt(2)
	v_mfma_f32_32x32x16_bf16 v[50:65], v[240:243], v[164:167], v[50:65]
	v_cvt_pk_bf16_f32 v164, v214, v215
	s_nop 1
	v_cvt_pk_bf16_f32 v165, v216, v217
	s_nop 1
	v_cvt_pk_bf16_f32 v166, v218, v219
	s_nop 1
	v_cvt_pk_bf16_f32 v167, v190, v191
	s_nop 1
	v_add_f32_e32 v0, v214, v0
	v_add_f32_e32 v0, v215, v0
	s_waitcnt lgkmcnt(1)
	v_mfma_f32_32x32x16_bf16 v[34:49], v[244:247], v[164:167], v[34:49]
	v_add_f32_e32 v0, v216, v0
	v_add_f32_e32 v0, v217, v0
	v_add_f32_e32 v0, v218, v0
	v_add_f32_e32 v0, v219, v0
	v_add_f32_e32 v0, v190, v0
	v_add_f32_e32 v0, v191, v0
	s_waitcnt lgkmcnt(0)
	v_mfma_f32_32x32x16_bf16 v[50:65], v[248:251], v[164:167], v[50:65]
	v_add_f32_e32 v0, v0, v196

; #define MFMA32(a, b, c) __builtin_amdgcn_mfma_f32_32x32x16_bf16((a), (b), (c), 0, 0, 0)
; template <int DQK, bool WIN>
; DI void attn_item(const u16* __restrict__ Qb, int ldq, const u16* __restrict__ Kb, int ldk, const u16* __restrict__ Vtb, int qb,
;                   float qscale, float sink2, const u16* __restrict__ zb, int ldz, u16* __restrict__ ob, int ldo, u16* lds) {
;     ...
;       for (int kb = 0; kb < 2; ++kb) {
; #pragma unroll
;         for (int i = 0; i < 16; ++i) st[kb][i] = 0.f;
; #pragma unroll
;         for (int s = 0; s < NKS; ++s) {
;           bf16x8 a = *(const bf16x8*)(ks + (kb * 32 + r) * KST + 16 * s + 8 * hh);
;           st[kb] = MFMA32(a, qf[s], st[kb]);
;         }
;       }
;       float mx = -INFINITY;
; #pragma unroll
;       for (int kb = 0; kb < 2; ++kb)
; #pragma unroll
;         for (int i = 0; i < 16; ++i) {
;           float v = st[kb][i];
;           if (MASK) {
;             int kg = k0 + kb * 32 + (i & 3) + 8 * (i >> 2) + 4 * hh;
;             bool ok = kg <= qrow;
;             if (WIN) ok = ok && (qrow - kg < 128);
;             v = ok ? v : -INFINITY;
;             st[kb][i] = v;
;           }
;           mx = fmaxf(mx, v);
;         }
;       mx = fmaxf(mx, __shfl_xor(mx, 32));
;       const float mn = fmaxf(m, mx);
;       if (__any(mn != m)) {
;         const float alpha = __builtin_amdgcn_exp2f((m - mn) * qscale);
;         lsum *= alpha;
; #pragma unroll
;         for (int i = 0; i < 16; ++i) { o[0][i] *= alpha; o[1][i] *= alpha; }
;       }
.LBB0_239:
	s_andn2_b64 vcc, exec, s[24:25]
	s_cbranch_vccnz .LBB0_245
	s_and_saveexec_b64 s[24:25], s[8:9]
	s_cbranch_execz .LBB0_244
	ds_read_b128 v[164:167], v155
	ds_read_b128 v[182:185], v155 offset:32
	ds_read_b128 v[186:189], v155 offset:64
	ds_read_b128 v[190:193], v155 offset:6688
	ds_read_b128 v[194:197], v155 offset:96
	ds_read_b128 v[198:201], v155 offset:128
	ds_read_b128 v[202:205], v155 offset:160
	ds_read_b128 v[206:209], v155 offset:6656
	ds_read_b128 v[210:213], v155 offset:6720
	ds_read_b128 v[214:217], v155 offset:6752
	ds_read_b128 v[218:221], v155 offset:6784
	ds_read_b128 v[222:225], v155 offset:6816
	s_waitcnt lgkmcnt(11)
	v_mfma_f32_32x32x16_bf16 v[50:65], v[164:167], v[66:69], 0
	s_waitcnt lgkmcnt(10)
	v_mfma_f32_32x32x16_bf16 v[50:65], v[182:185], v[70:73], v[50:65]
	s_waitcnt lgkmcnt(9)
	v_mfma_f32_32x32x16_bf16 v[50:65], v[186:189], v[74:77], v[50:65]
	s_waitcnt lgkmcnt(7)
	v_mfma_f32_32x32x16_bf16 v[50:65], v[194:197], v[78:81], v[50:65]
	s_waitcnt lgkmcnt(6)
	v_mfma_f32_32x32x16_bf16 v[50:65], v[198:201], v[82:85], v[50:65]
	s_waitcnt lgkmcnt(5)
	v_mfma_f32_32x32x16_bf16 v[50:65], v[202:205], v[86:89], v[50:65]
	s_waitcnt lgkmcnt(4)
	v_mfma_f32_32x32x16_bf16 v[34:49], v[206:209], v[66:69], 0
	s_nop 8
	s_nop 0
	v_max3_f32 v0, v50, s94, v51
	v_max3_f32 v0, v0, v52, v53
	v_max3_f32 v0, v0, v54, v55
	v_max3_f32 v0, v0, v56, v57
	v_max3_f32 v0, v0, v58, v59
	v_max3_f32 v0, v0, v60, v61
	v_max3_f32 v0, v0, v62, v63
	v_mfma_f32_32x32x16_bf16 v[34:49], v[190:193], v[70:73], v[34:49]
	v_max3_f32 v0, v0, v64, v65
	s_waitcnt lgkmcnt(3)
	v_mfma_f32_32x32x16_bf16 v[34:49], v[210:213], v[74:77], v[34:49]
	s_waitcnt lgkmcnt(2)
	v_mfma_f32_32x32x16_bf16 v[34:49], v[214:217], v[78:81], v[34:49]
	s_waitcnt lgkmcnt(1)
	v_mfma_f32_32x32x16_bf16 v[34:49], v[218:221], v[82:85], v[34:49]
	s_waitcnt lgkmcnt(0)
	v_mfma_f32_32x32x16_bf16 v[34:49], v[222:225], v[86:89], v[34:49]
	v_and_b32_e32 v159, 64, v172
	v_xor_b32_e32 v158, 32, v172
	v_add_u32_e32 v159, 64, v159
	v_cmp_lt_i32_e32 vcc, v158, v159
	s_nop 7
	v_max3_f32 v0, v0, v34, v35
	v_max3_f32 v0, v0, v36, v37
	v_max3_f32 v0, v0, v38, v39
	v_max3_f32 v0, v0, v40, v41
	v_max3_f32 v0, v0, v42, v43
	v_max3_f32 v0, v0, v44, v45
	v_max3_f32 v0, v0, v46, v47
	v_cndmask_b32_e32 v158, v172, v158, vcc
	v_max3_f32 v0, v0, v48, v49
	v_lshlrev_b32_e32 v158, 2, v158
	ds_bpermute_b32 v158, v158, v0
	s_waitcnt lgkmcnt(0)
	v_max3_f32 v0, v157, v0, v158
	v_cmp_neq_f32_e32 vcc, v0, v157
	s_cbranch_vccz .LBB0_243
	v_sub_f32_e32 v157, v157, v0
	v_mul_f32_e32 v157, 0x3e16c740, v157
	v_exp_f32_e32 v158, v157
	s_nop 0
	v_mul_f32_e32 v142, v142, v158
	v_pk_mul_f32 v[32:33], v[32:33], v[158:159] op_sel_hi:[1,0]
	v_pk_mul_f32 v[30:31], v[30:31], v[158:159] op_sel_hi:[1,0]
	v_pk_mul_f32 v[28:29], v[28:29], v[158:159] op_sel_hi:[1,0]
	v_pk_mul_f32 v[26:27], v[26:27], v[158:159] op_sel_hi:[1,0]
	v_pk_mul_f32 v[24:25], v[24:25], v[158:159] op_sel_hi:[1,0]
	v_pk_mul_f32 v[22:23], v[22:23], v[158:159] op_sel_hi:[1,0]
	v_pk_mul_f32 v[20:21], v[20:21], v[158:159] op_sel_hi:[1,0]
	v_pk_mul_f32 v[18:19], v[18:19], v[158:159] op_sel_hi:[1,0]
	v_pk_mul_f32 v[16:17], v[16:17], v[158:159] op_sel_hi:[1,0]
	v_pk_mul_f32 v[14:15], v[14:15], v[158:159] op_sel_hi:[1,0]
	v_pk_mul_f32 v[12:13], v[12:13], v[158:159] op_sel_hi:[1,0]
	v_pk_mul_f32 v[10:11], v[10:11], v[158:159] op_sel_hi:[1,0]
	v_pk_mul_f32 v[8:9], v[8:9], v[158:159] op_sel_hi:[1,0]
	v_pk_mul_f32 v[6:7], v[6:7], v[158:159] op_sel_hi:[1,0]
	v_pk_mul_f32 v[4:5], v[4:5], v[158:159] op_sel_hi:[1,0]
	v_pk_mul_f32 v[2:3], v[2:3], v[158:159] op_sel_hi:[1,0]
; DI unsigned pack2(float a, float b) { unsigned r; asm("v_cvt_pk_bf16_f32 %0, %1, %2\n\ts_nop 1" : "=v"(r) : "v"(a), "v"(b)); return r; }
; #define MFMA32(a, b, c) __builtin_amdgcn_mfma_f32_32x32x16_bf16((a), (b), (c), 0, 0, 0)
; template <int DQK, bool WIN>
; DI void attn_item(const u16* __restrict__ Qb, int ldq, const u16* __restrict__ Kb, int ldk, const u16* __restrict__ Vtb, int qb,
;                   float qscale, float sink2, const u16* __restrict__ zb, int ldz, u16* __restrict__ ob, int ldo, u16* lds) {
;     ...
;       const float nb = -mn * qscale;
;       float ps = 0.f;
; #pragma unroll
;       for (int kb = 0; kb < 2; ++kb)
; #pragma unroll
;         for (int i = 0; i < 16; ++i) { float pv = __builtin_amdgcn_exp2f(fmaf(st[kb][i], qscale, nb)); st[kb][i] = pv; ps += pv; }
;       lsum += ps;
; #pragma unroll
;       for (int kb = 0; kb < 2; ++kb)
; #pragma unroll
;         for (int s2 = 0; s2 < 2; ++s2) {
;           union { bf16x8 v; unsigned u[4]; } pf;
; #pragma unroll
;           for (int j = 0; j < 4; ++j) pf.u[j] = pack2(st[kb][8 * s2 + 2 * j], st[kb][8 * s2 + 2 * j + 1]);
; #pragma unroll
;           for (int vb = 0; vb < 2; ++vb) {
;             const bf16x8 vf = *(const bf16x8*)(vs + (vb * 32 + r) * 72 + (kb * 2 + s2) * 16 + hh * 8);
;             o[vb] = MFMA32(vf, pf.v, o[vb]);
;           }
;         }
.LBB0_243:
	ds_read_b128 v[186:189], v156 offset:13312
	ds_read_b128 v[190:193], v156 offset:13344
	ds_read_b128 v[194:197], v156 offset:17920
	ds_read_b128 v[198:201], v156 offset:17952
	ds_read_b128 v[202:205], v156 offset:13376
	ds_read_b128 v[206:209], v156 offset:17984
	ds_read_b128 v[210:213], v156 offset:13408
	ds_read_b128 v[214:217], v156 offset:18016
	v_mul_f32_e32 v157, 0xbe16c740, v0
	v_fmamk_f32 v50, v50, 0x3e16c740, v157
	v_exp_f32_e32 v50, v50
	v_fmamk_f32 v51, v51, 0x3e16c740, v157
	v_exp_f32_e32 v51, v51
	v_fmamk_f32 v52, v52, 0x3e16c740, v157
	v_exp_f32_e32 v52, v52
	v_fmamk_f32 v53, v53, 0x3e16c740, v157
	v_exp_f32_e32 v53, v53
	v_fmamk_f32 v54, v54, 0x3e16c740, v157
	v_add_f32_e32 v158, 0, v50
	v_exp_f32_e32 v54, v54
	v_fmamk_f32 v55, v55, 0x3e16c740, v157
	v_add_f32_e32 v158, v51, v158
	v_exp_f32_e32 v55, v55
	v_fmamk_f32 v56, v56, 0x3e16c740, v157
	v_add_f32_e32 v158, v52, v158
	v_exp_f32_e32 v56, v56
	v_fmamk_f32 v57, v57, 0x3e16c740, v157
	v_add_f32_e32 v158, v53, v158
	v_exp_f32_e32 v57, v57
	v_fmamk_f32 v58, v58, 0x3e16c740, v157
	v_add_f32_e32 v158, v54, v158
	v_exp_f32_e32 v58, v58
	v_fmamk_f32 v59, v59, 0x3e16c740, v157
	v_add_f32_e32 v158, v55, v158
	v_exp_f32_e32 v59, v59
	v_fmamk_f32 v60, v60, 0x3e16c740, v157
	v_add_f32_e32 v158, v56, v158
	v_exp_f32_e32 v60, v60
	v_fmamk_f32 v61, v61, 0x3e16c740, v157
	v_add_f32_e32 v158, v57, v158
	v_exp_f32_e32 v61, v61
	v_fmamk_f32 v62, v62, 0x3e16c740, v157
	v_add_f32_e32 v158, v58, v158
	v_exp_f32_e32 v62, v62
	v_fmamk_f32 v63, v63, 0x3e16c740, v157
	v_add_f32_e32 v158, v59, v158
	v_exp_f32_e32 v63, v63
	v_fmamk_f32 v64, v64, 0x3e16c740, v157
	v_add_f32_e32 v158, v60, v158
	v_exp_f32_e32 v64, v64
	v_fmamk_f32 v65, v65, 0x3e16c740, v157
	v_add_f32_e32 v158, v61, v158
	v_exp_f32_e32 v65, v65
	v_fmamk_f32 v34, v34, 0x3e16c740, v157
	v_add_f32_e32 v158, v62, v158
	v_exp_f32_e32 v159, v34
	v_add_f32_e32 v158, v63, v158
	v_add_f32_e32 v158, v64, v158
	v_add_f32_e32 v158, v65, v158
	v_fmamk_f32 v35, v35, 0x3e16c740, v157
	v_add_f32_e32 v34, v159, v158
	v_exp_f32_e32 v158, v35
	v_fmamk_f32 v35, v36, 0x3e16c740, v157
	v_exp_f32_e32 v160, v35
	v_fmamk_f32 v35, v37, 0x3e16c740, v157
	v_exp_f32_e32 v161, v35
	v_fmamk_f32 v35, v38, 0x3e16c740, v157
	v_exp_f32_e32 v162, v35
	v_fmamk_f32 v35, v39, 0x3e16c740, v157
	v_add_f32_e32 v34, v158, v34
	v_exp_f32_e32 v164, v35
	v_fmamk_f32 v35, v40, 0x3e16c740, v157
	v_add_f32_e32 v34, v160, v34
	v_exp_f32_e32 v165, v35
	v_fmamk_f32 v35, v41, 0x3e16c740, v157
	v_add_f32_e32 v34, v161, v34
	v_exp_f32_e32 v166, v35
	v_fmamk_f32 v35, v42, 0x3e16c740, v157
	v_add_f32_e32 v34, v162, v34
	v_exp_f32_e32 v167, v35
	v_fmamk_f32 v35, v43, 0x3e16c740, v157
	v_add_f32_e32 v34, v164, v34
	v_exp_f32_e32 v182, v35
	v_fmamk_f32 v35, v44, 0x3e16c740, v157
	v_add_f32_e32 v34, v165, v34
	v_exp_f32_e32 v183, v35
	v_fmamk_f32 v35, v45, 0x3e16c740, v157
	v_add_f32_e32 v34, v166, v34
	v_exp_f32_e32 v184, v35
	v_fmamk_f32 v35, v46, 0x3e16c740, v157
	v_add_f32_e32 v34, v167, v34
	v_exp_f32_e32 v46, v35
	v_fmamk_f32 v35, v47, 0x3e16c740, v157
	v_add_f32_e32 v34, v182, v34
	v_exp_f32_e32 v47, v35
	v_fmamk_f32 v35, v48, 0x3e16c740, v157
	v_add_f32_e32 v34, v183, v34
	v_exp_f32_e32 v48, v35
	v_fmac_f32_e32 v157, 0x3e16c740, v49
	v_add_f32_e32 v34, v184, v34
	v_exp_f32_e32 v49, v157
	v_add_f32_e32 v34, v46, v34
	v_add_f32_e32 v34, v47, v34
	v_add_f32_e32 v34, v48, v34
	v_add_f32_e32 v34, v49, v34
	v_add_f32_e32 v142, v34, v142
	v_cvt_pk_bf16_f32 v34, v50, v51
	s_nop 1
	v_cvt_pk_bf16_f32 v35, v52, v53
	s_nop 1
	v_cvt_pk_bf16_f32 v36, v54, v55
	s_nop 1
	v_cvt_pk_bf16_f32 v37, v56, v57
	s_nop 1
	v_mov_b32_e32 v157, v0
	s_waitcnt lgkmcnt(7)
	v_mfma_f32_32x32x16_bf16 v[18:33], v[186:189], v[34:37], v[18:33]
	s_waitcnt lgkmcnt(5)
	v_mfma_f32_32x32x16_bf16 v[2:17], v[194:197], v[34:37], v[2:17]
	v_cvt_pk_bf16_f32 v34, v58, v59
	s_nop 1
	v_cvt_pk_bf16_f32 v35, v60, v61
	s_nop 1
	v_cvt_pk_bf16_f32 v36, v62, v63
	s_nop 1
	v_cvt_pk_bf16_f32 v37, v64, v65
	s_nop 1
	s_waitcnt lgkmcnt(4)
	v_mfma_f32_32x32x16_bf16 v[2:17], v[198:201], v[34:37], v[2:17]
	v_mfma_f32_32x32x16_bf16 v[18:33], v[190:193], v[34:37], v[18:33]
	v_cvt_pk_bf16_f32 v34, v159, v158
	s_nop 1
	v_cvt_pk_bf16_f32 v35, v160, v161
	s_nop 1
	v_cvt_pk_bf16_f32 v36, v162, v164
	s_nop 1
	v_cvt_pk_bf16_f32 v37, v165, v166
	s_nop 1
	s_waitcnt lgkmcnt(3)
	v_mfma_f32_32x32x16_bf16 v[18:33], v[202:205], v[34:37], v[18:33]
	s_waitcnt lgkmcnt(2)
	v_mfma_f32_32x32x16_bf16 v[2:17], v[206:209], v[34:37], v[2:17]
	v_cvt_pk_bf16_f32 v34, v167, v182
	s_nop 1
	v_cvt_pk_bf16_f32 v35, v183, v184
	s_nop 1
	v_cvt_pk_bf16_f32 v36, v46, v47
	s_nop 1
	v_cvt_pk_bf16_f32 v37, v48, v49
	s_nop 1
	s_waitcnt lgkmcnt(1)
	v_mfma_f32_32x32x16_bf16 v[18:33], v[210:213], v[34:37], v[18:33]
	s_waitcnt lgkmcnt(0)
	v_mfma_f32_32x32x16_bf16 v[2:17], v[214:217], v[34:37], v[2:17]

; #define MFMA32(a, b, c) __builtin_amdgcn_mfma_f32_32x32x16_bf16((a), (b), (c), 0, 0, 0)
; template <int DQK, bool WIN>
; DI void attn_item(const u16* __restrict__ Qb, int ldq, const u16* __restrict__ Kb, int ldk, const u16* __restrict__ Vtb, int qb,
;                   float qscale, float sink2, const u16* __restrict__ zb, int ldz, u16* __restrict__ ob, int ldo, u16* lds) {
;     ...
;     bool active = (k0 <= q0 + 31);
;     if (WIN) active = active && (k0 + 63 >= q0 - 127);
;     if (active) {
;       f32x16 st[2];
; #pragma unroll
;       for (int kb = 0; kb < 2; ++kb) {
; #pragma unroll
;         for (int i = 0; i < 16; ++i) st[kb][i] = 0.f;
; #pragma unroll
;         for (int s = 0; s < NKS; ++s) {
;           bf16x8 a = *(const bf16x8*)(ks + (kb * 32 + r) * KST + 16 * s + 8 * hh);
;           st[kb] = MFMA32(a, qf[s], st[kb]);
;         }
;       }
;       float mx = -INFINITY;
; #pragma unroll
;       for (int kb = 0; kb < 2; ++kb)
; #pragma unroll
;         for (int i = 0; i < 16; ++i) {
;           float v = st[kb][i];
;           if (MASK) {
;             int kg = k0 + kb * 32 + (i & 3) + 8 * (i >> 2) + 4 * hh;
;             bool ok = kg <= qrow;
;             if (WIN) ok = ok && (qrow - kg < 128);
;             v = ok ? v : -INFINITY;
;             st[kb][i] = v;
;           }
;           mx = fmaxf(mx, v);
;         }
;       mx = fmaxf(mx, __shfl_xor(mx, 32));
.LBB0_247:
	s_add_i32 s0, s20, 0xffffff80
	s_cmp_lt_u32 s31, s29
	v_cmp_le_i32_e64 s[8:9], s0, v154
	s_mov_b64 s[24:25], -1
	s_cbranch_scc1 .LBB0_257
	v_mov_b64_e32 v[2:3], v[50:51]
	v_mov_b64_e32 v[18:19], v[34:35]
	v_mov_b32_e32 v157, v158
	v_mov_b32_e32 v142, v0
	v_mov_b64_e32 v[4:5], v[52:53]
	v_mov_b64_e32 v[6:7], v[54:55]
	v_mov_b64_e32 v[8:9], v[56:57]
	v_mov_b64_e32 v[10:11], v[58:59]
	v_mov_b64_e32 v[12:13], v[60:61]
	v_mov_b64_e32 v[14:15], v[62:63]
	v_mov_b64_e32 v[16:17], v[64:65]
	v_mov_b64_e32 v[20:21], v[36:37]
	v_mov_b64_e32 v[22:23], v[38:39]
	v_mov_b64_e32 v[24:25], v[40:41]
	v_mov_b64_e32 v[26:27], v[42:43]
	v_mov_b64_e32 v[28:29], v[44:45]
	v_mov_b64_e32 v[30:31], v[46:47]
	v_mov_b64_e32 v[32:33], v[48:49]
	s_and_saveexec_b64 s[24:25], s[8:9]
	s_cbranch_execz .LBB0_252
	ds_read_b128 v[206:209], v155 offset:22528
	ds_read_b128 v[210:213], v155 offset:22560
	ds_read_b128 v[214:217], v155 offset:22592
	ds_read_b128 v[218:221], v155 offset:29216
	ds_read_b128 v[222:225], v155 offset:22624
	ds_read_b128 v[226:229], v155 offset:22656
	ds_read_b128 v[230:233], v155 offset:22688
	ds_read_b128 v[234:237], v155 offset:29184
	ds_read_b128 v[238:241], v155 offset:29248
	ds_read_b128 v[242:245], v155 offset:29280
	ds_read_b128 v[246:249], v155 offset:29312
	ds_read_b128 v[250:253], v155 offset:29344
	v_add_u32_e32 v142, s20, v146
	v_add_u32_e32 v157, 0xffffff80, v142
	v_cmp_le_i32_e32 vcc, v157, v130
	s_waitcnt lgkmcnt(11)
	v_mfma_f32_32x32x16_bf16 v[18:33], v[206:209], v[66:69], 0
	s_waitcnt lgkmcnt(10)
	v_mfma_f32_32x32x16_bf16 v[18:33], v[210:213], v[70:73], v[18:33]
	s_waitcnt lgkmcnt(9)
	v_mfma_f32_32x32x16_bf16 v[18:33], v[214:217], v[74:77], v[18:33]
	s_waitcnt lgkmcnt(7)
	v_mfma_f32_32x32x16_bf16 v[18:33], v[222:225], v[78:81], v[18:33]
	s_waitcnt lgkmcnt(6)
	v_mfma_f32_32x32x16_bf16 v[18:33], v[226:229], v[82:85], v[18:33]
	s_waitcnt lgkmcnt(5)
	v_mfma_f32_32x32x16_bf16 v[18:33], v[230:233], v[86:89], v[18:33]
	s_waitcnt lgkmcnt(4)
	v_mfma_f32_32x32x16_bf16 v[2:17], v[234:237], v[66:69], 0
	v_mfma_f32_32x32x16_bf16 v[2:17], v[218:221], v[70:73], v[2:17]
	s_waitcnt lgkmcnt(3)
	v_mfma_f32_32x32x16_bf16 v[2:17], v[238:241], v[74:77], v[2:17]
	s_waitcnt lgkmcnt(2)
	v_mfma_f32_32x32x16_bf16 v[2:17], v[242:245], v[78:81], v[2:17]
	s_waitcnt lgkmcnt(1)
	v_mfma_f32_32x32x16_bf16 v[2:17], v[246:249], v[82:85], v[2:17]
	s_waitcnt lgkmcnt(0)
	v_mfma_f32_32x32x16_bf16 v[2:17], v[250:253], v[86:89], v[2:17]
	s_nop 0
	v_cndmask_b32_e32 v167, v176, v18, vcc
	v_cmp_lt_i32_e32 vcc, v157, v130
	s_nop 1
	v_cndmask_b32_e32 v166, v176, v19, vcc
	v_add_u32_e32 v19, 0xffffff82, v142
	v_cmp_le_i32_e32 vcc, v19, v130
	v_add_u32_e32 v19, 0xffffff83, v142
	v_max3_f32 v18, v167, s94, v166
	v_cndmask_b32_e32 v182, v176, v20, vcc
	v_cmp_le_i32_e32 vcc, v19, v130
	v_add_u32_e32 v19, 0xffffff88, v142
	s_nop 0
	v_cndmask_b32_e32 v183, v176, v21, vcc
	v_cmp_le_i32_e32 vcc, v19, v130
	v_add_u32_e32 v19, 0xffffff89, v142
	v_max3_f32 v18, v18, v182, v183
	v_cndmask_b32_e32 v185, v176, v22, vcc
	v_cmp_le_i32_e32 vcc, v19, v130
	v_add_u32_e32 v19, 0xffffff8a, v142
	s_nop 0
	v_cndmask_b32_e32 v186, v176, v23, vcc
	v_cmp_le_i32_e32 vcc, v19, v130
	v_add_u32_e32 v19, 0xffffff8b, v142
	v_max3_f32 v18, v18, v185, v186
	v_cndmask_b32_e32 v190, v176, v24, vcc
	v_cmp_le_i32_e32 vcc, v19, v130
	v_add_u32_e32 v19, 0xffffff90, v142
	s_nop 0
	v_cndmask_b32_e32 v191, v176, v25, vcc
	v_cmp_le_i32_e32 vcc, v19, v130
	v_add_u32_e32 v19, 0xffffff91, v142
	v_max3_f32 v18, v18, v190, v191
	v_cndmask_b32_e32 v201, v176, v26, vcc
	v_cmp_le_i32_e32 vcc, v19, v130
	v_add_u32_e32 v19, 0xffffff92, v142
	s_nop 0
	v_cndmask_b32_e32 v195, v176, v27, vcc
	v_cmp_le_i32_e32 vcc, v19, v130
	v_add_u32_e32 v19, 0xffffff93, v142
	v_max3_f32 v18, v18, v201, v195
	v_cndmask_b32_e32 v202, v176, v28, vcc
	v_cmp_le_i32_e32 vcc, v19, v130
	v_add_u32_e32 v19, 0xffffff98, v142
	s_nop 0
	v_cndmask_b32_e32 v196, v176, v29, vcc
	v_cmp_le_i32_e32 vcc, v19, v130
	v_add_u32_e32 v19, 0xffffff99, v142
	v_max3_f32 v18, v18, v202, v196
	v_cndmask_b32_e32 v203, v176, v30, vcc
	v_cmp_le_i32_e32 vcc, v19, v130
	v_add_u32_e32 v19, 0xffffff9a, v142
	s_nop 0
	v_cndmask_b32_e32 v197, v176, v31, vcc
	v_cmp_le_i32_e32 vcc, v19, v130
	v_add_u32_e32 v19, 0xffffff9b, v142
	v_max3_f32 v18, v18, v203, v197
	v_cndmask_b32_e32 v204, v176, v32, vcc
	v_cmp_le_i32_e32 vcc, v19, v130
	v_add_u32_e32 v19, 0xffffffa0, v142
	s_nop 0
	v_cndmask_b32_e32 v198, v176, v33, vcc
	v_cmp_le_i32_e32 vcc, v19, v130
	v_max3_f32 v18, v18, v204, v198
	s_nop 0
	v_cndmask_b32_e32 v205, v176, v2, vcc
	v_add_u32_e32 v2, 0xffffffa1, v142
	v_cmp_le_i32_e32 vcc, v2, v130
	s_nop 1
	v_cndmask_b32_e32 v199, v176, v3, vcc
	v_add_u32_e32 v3, 0xffffffa2, v142
	v_cmp_le_i32_e32 vcc, v3, v130
	v_add_u32_e32 v3, 0xffffffa3, v142
	v_max3_f32 v2, v18, v205, v199
	v_cndmask_b32_e32 v200, v176, v4, vcc
	v_cmp_le_i32_e32 vcc, v3, v130
	v_add_u32_e32 v3, 0xffffffa8, v142
	v_and_b32_e32 v4, 64, v172
	v_cndmask_b32_e32 v193, v176, v5, vcc
	v_cmp_le_i32_e32 vcc, v3, v130
	v_add_u32_e32 v3, 0xffffffa9, v142
	v_max3_f32 v2, v2, v200, v193
	v_cndmask_b32_e32 v194, v176, v6, vcc
	v_cmp_le_i32_e32 vcc, v3, v130
	v_add_u32_e32 v3, 0xffffffaa, v142
	v_add_u32_e32 v4, 64, v4
	v_cndmask_b32_e32 v192, v176, v7, vcc
	v_cmp_le_i32_e32 vcc, v3, v130
	v_add_u32_e32 v3, 0xffffffab, v142
	v_max3_f32 v2, v2, v194, v192
	v_cndmask_b32_e32 v187, v176, v8, vcc
	v_cmp_le_i32_e32 vcc, v3, v130
	v_add_u32_e32 v3, 0xffffffb0, v142
	v_mov_b64_e32 v[18:19], v[34:35]
	v_cndmask_b32_e32 v188, v176, v9, vcc
	v_cmp_le_i32_e32 vcc, v3, v130
	v_add_u32_e32 v3, 0xffffffb1, v142
	v_max3_f32 v2, v2, v187, v188
	v_cndmask_b32_e32 v189, v176, v10, vcc
	v_cmp_le_i32_e32 vcc, v3, v130
	v_add_u32_e32 v3, 0xffffffb2, v142
	v_mov_b64_e32 v[20:21], v[36:37]
	v_cndmask_b32_e32 v184, v176, v11, vcc
	v_cmp_le_i32_e32 vcc, v3, v130
	v_add_u32_e32 v3, 0xffffffb3, v142
	v_max3_f32 v2, v2, v189, v184
	v_cndmask_b32_e32 v165, v176, v12, vcc
	v_cmp_le_i32_e32 vcc, v3, v130
	v_add_u32_e32 v3, 0xffffffb8, v142
	v_mov_b64_e32 v[22:23], v[38:39]
	v_cndmask_b32_e32 v164, v176, v13, vcc
	v_cmp_le_i32_e32 vcc, v3, v130
	v_add_u32_e32 v3, 0xffffffb9, v142
	v_max3_f32 v2, v2, v165, v164
	v_cndmask_b32_e32 v160, v176, v14, vcc
	v_cmp_le_i32_e32 vcc, v3, v130
	v_add_u32_e32 v3, 0xffffffba, v142
	v_mov_b64_e32 v[24:25], v[40:41]
	v_cndmask_b32_e32 v161, v176, v15, vcc
	v_cmp_le_i32_e32 vcc, v3, v130
	v_add_u32_e32 v3, 0xffffffbb, v142
	v_max3_f32 v2, v2, v160, v161
	v_cndmask_b32_e32 v162, v176, v16, vcc
	v_cmp_le_i32_e32 vcc, v3, v130
	v_xor_b32_e32 v3, 32, v172
	v_mov_b64_e32 v[26:27], v[42:43]
	v_cndmask_b32_e32 v159, v176, v17, vcc
	v_cmp_lt_i32_e32 vcc, v3, v4
	v_max3_f32 v2, v2, v162, v159
	v_mov_b64_e32 v[28:29], v[44:45]
	v_cndmask_b32_e32 v3, v172, v3, vcc
	v_lshlrev_b32_e32 v3, 2, v3
	ds_bpermute_b32 v3, v3, v2
	v_mov_b64_e32 v[30:31], v[46:47]
	v_mov_b64_e32 v[32:33], v[48:49]
	v_mov_b32_e32 v142, v0
	s_waitcnt lgkmcnt(0)
; DI unsigned pack2(float a, float b) { unsigned r; asm("v_cvt_pk_bf16_f32 %0, %1, %2\n\ts_nop 1" : "=v"(r) : "v"(a), "v"(b)); return r; }
; #define MFMA32(a, b, c) __builtin_amdgcn_mfma_f32_32x32x16_bf16((a), (b), (c), 0, 0, 0)
; template <int DQK, bool WIN>
; DI void attn_item(const u16* __restrict__ Qb, int ldq, const u16* __restrict__ Kb, int ldk, const u16* __restrict__ Vtb, int qb,
;                   float qscale, float sink2, const u16* __restrict__ zb, int ldz, u16* __restrict__ ob, int ldo, u16* lds) {
;     ...
;       mx = fmaxf(mx, __shfl_xor(mx, 32));
;       const float mn = fmaxf(m, mx);
;       if (__any(mn != m)) {
;         const float alpha = __builtin_amdgcn_exp2f((m - mn) * qscale);
;         lsum *= alpha;
; #pragma unroll
;         for (int i = 0; i < 16; ++i) { o[0][i] *= alpha; o[1][i] *= alpha; }
;       }
;       m = mn;
;       const float nb = -mn * qscale;
;       float ps = 0.f;
; #pragma unroll
;       for (int kb = 0; kb < 2; ++kb)
; #pragma unroll
;         for (int i = 0; i < 16; ++i) { float pv = __builtin_amdgcn_exp2f(fmaf(st[kb][i], qscale, nb)); st[kb][i] = pv; ps += pv; }
;       lsum += ps;
; #pragma unroll
;       for (int kb = 0; kb < 2; ++kb)
; #pragma unroll
;         for (int s2 = 0; s2 < 2; ++s2) {
;           union { bf16x8 v; unsigned u[4]; } pf;
; #pragma unroll
;           for (int j = 0; j < 4; ++j) pf.u[j] = pack2(st[kb][8 * s2 + 2 * j], st[kb][8 * s2 + 2 * j + 1]);
; #pragma unroll
;           for (int vb = 0; vb < 2; ++vb) {
;             const bf16x8 vf = *(const bf16x8*)(vs + (vb * 32 + r) * 72 + (kb * 2 + s2) * 16 + hh * 8);
;             o[vb] = MFMA32(vf, pf.v, o[vb]);
;           }
;         }
	v_max3_f32 v157, v158, v2, v3
	v_mov_b64_e32 v[2:3], v[50:51]
	v_cmp_neq_f32_e32 vcc, v157, v158
	v_mov_b64_e32 v[4:5], v[52:53]
	v_mov_b64_e32 v[6:7], v[54:55]
	v_mov_b64_e32 v[8:9], v[56:57]
	v_mov_b64_e32 v[10:11], v[58:59]
	v_mov_b64_e32 v[12:13], v[60:61]
	v_mov_b64_e32 v[14:15], v[62:63]
	v_mov_b64_e32 v[16:17], v[64:65]
	s_cbranch_vccz .LBB0_251
	v_sub_f32_e32 v2, v158, v157
	v_mul_f32_e32 v2, 0x3e16c740, v2
	v_exp_f32_e32 v2, v2
	s_nop 0
	v_mul_f32_e32 v142, v0, v2
	v_pk_mul_f32 v[32:33], v[48:49], v[2:3] op_sel_hi:[1,0]
	v_pk_mul_f32 v[30:31], v[46:47], v[2:3] op_sel_hi:[1,0]
	v_pk_mul_f32 v[28:29], v[44:45], v[2:3] op_sel_hi:[1,0]
	v_pk_mul_f32 v[26:27], v[42:43], v[2:3] op_sel_hi:[1,0]
	v_pk_mul_f32 v[24:25], v[40:41], v[2:3] op_sel_hi:[1,0]
	v_pk_mul_f32 v[22:23], v[38:39], v[2:3] op_sel_hi:[1,0]
	v_pk_mul_f32 v[20:21], v[36:37], v[2:3] op_sel_hi:[1,0]
	v_pk_mul_f32 v[18:19], v[34:35], v[2:3] op_sel_hi:[1,0]
	v_pk_mul_f32 v[16:17], v[64:65], v[2:3] op_sel_hi:[1,0]
	v_pk_mul_f32 v[14:15], v[62:63], v[2:3] op_sel_hi:[1,0]
	v_pk_mul_f32 v[12:13], v[60:61], v[2:3] op_sel_hi:[1,0]
	v_pk_mul_f32 v[10:11], v[58:59], v[2:3] op_sel_hi:[1,0]
	v_pk_mul_f32 v[8:9], v[56:57], v[2:3] op_sel_hi:[1,0]
	v_pk_mul_f32 v[6:7], v[54:55], v[2:3] op_sel_hi:[1,0]
	v_pk_mul_f32 v[4:5], v[52:53], v[2:3] op_sel_hi:[1,0]
	v_pk_mul_f32 v[2:3], v[50:51], v[2:3] op_sel_hi:[1,0]
.LBB0_251:
	ds_read_b128 v[220:223], v156 offset:35840
	ds_read_b128 v[224:227], v156 offset:40448
	ds_read_b128 v[228:231], v156 offset:35872
	ds_read_b128 v[232:235], v156 offset:40480
	ds_read_b128 v[236:239], v156 offset:35904
	ds_read_b128 v[240:243], v156 offset:40512
	ds_read_b128 v[244:247], v156 offset:35936
	ds_read_b128 v[248:251], v156 offset:40544
	v_mul_f32_e32 v206, 0xbe16c740, v157
	v_fmamk_f32 v167, v167, 0x3e16c740, v206
	v_exp_f32_e32 v167, v167
	v_fmamk_f32 v166, v166, 0x3e16c740, v206
	v_exp_f32_e32 v166, v166
	v_fmamk_f32 v182, v182, 0x3e16c740, v206
	v_exp_f32_e32 v182, v182
	v_fmamk_f32 v183, v183, 0x3e16c740, v206
	v_exp_f32_e32 v183, v183
	v_fmamk_f32 v185, v185, 0x3e16c740, v206
	v_add_f32_e32 v207, 0, v167
	v_exp_f32_e32 v185, v185
	v_fmamk_f32 v186, v186, 0x3e16c740, v206
	v_add_f32_e32 v207, v166, v207
	v_exp_f32_e32 v186, v186
	v_fmamk_f32 v190, v190, 0x3e16c740, v206
	v_add_f32_e32 v207, v182, v207
	v_exp_f32_e32 v208, v190
	v_fmamk_f32 v191, v191, 0x3e16c740, v206
	v_add_f32_e32 v190, v183, v207
	v_exp_f32_e32 v207, v191
	v_fmamk_f32 v191, v201, 0x3e16c740, v206
	v_add_f32_e32 v190, v185, v190
	v_exp_f32_e32 v209, v191
	v_fmamk_f32 v191, v195, 0x3e16c740, v206
	v_add_f32_e32 v190, v186, v190
	v_exp_f32_e32 v210, v191
	v_fmamk_f32 v191, v202, 0x3e16c740, v206
	v_add_f32_e32 v190, v208, v190
	v_exp_f32_e32 v202, v191
	v_fmamk_f32 v191, v196, 0x3e16c740, v206
	v_add_f32_e32 v190, v207, v190
	v_exp_f32_e32 v211, v191
	v_fmamk_f32 v191, v203, 0x3e16c740, v206
	v_add_f32_e32 v190, v209, v190
	v_exp_f32_e32 v203, v191
	v_fmamk_f32 v191, v197, 0x3e16c740, v206
	v_add_f32_e32 v190, v210, v190
	v_exp_f32_e32 v212, v191
	v_fmamk_f32 v191, v204, 0x3e16c740, v206
	v_add_f32_e32 v190, v202, v190
	v_exp_f32_e32 v204, v191
	v_fmamk_f32 v191, v198, 0x3e16c740, v206
	v_add_f32_e32 v190, v211, v190
	v_exp_f32_e32 v213, v191
	v_fmamk_f32 v191, v205, 0x3e16c740, v206
	v_add_f32_e32 v190, v203, v190
	v_exp_f32_e32 v205, v191
	v_fmamk_f32 v191, v199, 0x3e16c740, v206
	v_add_f32_e32 v190, v212, v190
	v_exp_f32_e32 v214, v191
	v_fmamk_f32 v191, v200, 0x3e16c740, v206
	v_add_f32_e32 v190, v204, v190
	v_exp_f32_e32 v215, v191
	v_add_f32_e32 v190, v213, v190
	v_add_f32_e32 v190, v205, v190
	v_add_f32_e32 v190, v214, v190
	v_add_f32_e32 v195, v215, v190
	v_fmamk_f32 v190, v193, 0x3e16c740, v206
	v_exp_f32_e32 v216, v190
	v_fmamk_f32 v190, v194, 0x3e16c740, v206
	v_exp_f32_e32 v217, v190
	v_fmamk_f32 v190, v192, 0x3e16c740, v206
	v_exp_f32_e32 v218, v190
	v_add_f32_e32 v194, v216, v195
	v_add_f32_e32 v194, v217, v194
	v_add_f32_e32 v219, v218, v194
	v_cvt_pk_bf16_f32 v194, v167, v166
	s_nop 1
	v_fmamk_f32 v166, v187, 0x3e16c740, v206
	v_exp_f32_e32 v167, v166
	v_fmamk_f32 v166, v188, 0x3e16c740, v206
	v_cvt_pk_bf16_f32 v196, v185, v186
	s_nop 1
	v_cvt_pk_bf16_f32 v197, v208, v207
	s_nop 1
	v_exp_f32_e32 v207, v166
	v_fmamk_f32 v166, v189, 0x3e16c740, v206
	v_cvt_pk_bf16_f32 v195, v182, v183
	s_nop 1
	v_exp_f32_e32 v208, v166
	s_waitcnt lgkmcnt(7)
	v_mfma_f32_32x32x16_bf16 v[18:33], v[220:223], v[194:197], v[18:33]
	v_fmamk_f32 v166, v184, 0x3e16c740, v206
	v_cvt_pk_bf16_f32 v182, v209, v210
	s_nop 1
	v_cvt_pk_bf16_f32 v183, v202, v211
	s_nop 1
	v_cvt_pk_bf16_f32 v184, v203, v212
	s_nop 1
	v_cvt_pk_bf16_f32 v185, v204, v213
	s_nop 1
	v_fmamk_f32 v165, v165, 0x3e16c740, v206
	s_waitcnt lgkmcnt(5)
	v_mfma_f32_32x32x16_bf16 v[18:33], v[228:231], v[182:185], v[18:33]
	v_fmamk_f32 v164, v164, 0x3e16c740, v206
	v_fmamk_f32 v160, v160, 0x3e16c740, v206
	v_exp_f32_e32 v160, v160
	v_fmamk_f32 v161, v161, 0x3e16c740, v206
	v_fmamk_f32 v162, v162, 0x3e16c740, v206
	v_fmac_f32_e32 v206, 0x3e16c740, v159
	v_mfma_f32_32x32x16_bf16 v[2:17], v[224:227], v[194:197], v[2:17]
	v_exp_f32_e32 v194, v166
	v_add_f32_e32 v166, v167, v219
	v_add_f32_e32 v166, v207, v166
	v_add_f32_e32 v166, v208, v166
	v_add_f32_e32 v195, v194, v166
	v_exp_f32_e32 v196, v165
	v_cvt_pk_bf16_f32 v165, v215, v216
	s_nop 1
	s_waitcnt lgkmcnt(4)
	v_mfma_f32_32x32x16_bf16 v[2:17], v[232:235], v[182:185], v[2:17]
	v_exp_f32_e32 v190, v164
	v_cvt_pk_bf16_f32 v164, v205, v214
	s_nop 1
	v_cvt_pk_bf16_f32 v166, v217, v218
	s_nop 1
	v_cvt_pk_bf16_f32 v167, v167, v207
	s_nop 1
	v_exp_f32_e32 v161, v161
	v_exp_f32_e32 v162, v162
	s_waitcnt lgkmcnt(3)
	v_mfma_f32_32x32x16_bf16 v[18:33], v[236:239], v[164:167], v[18:33]
	v_exp_f32_e32 v159, v206
	s_waitcnt lgkmcnt(2)
	v_mfma_f32_32x32x16_bf16 v[2:17], v[240:243], v[164:167], v[2:17]
	v_cvt_pk_bf16_f32 v164, v208, v194
	s_nop 1
	v_cvt_pk_bf16_f32 v165, v196, v190
	s_nop 1
	v_cvt_pk_bf16_f32 v166, v160, v161
	s_nop 1
	v_cvt_pk_bf16_f32 v167, v162, v159
	s_nop 1
	s_waitcnt lgkmcnt(1)
	v_mfma_f32_32x32x16_bf16 v[18:33], v[244:247], v[164:167], v[18:33]
	v_add_f32_e32 v186, v196, v195
	v_add_f32_e32 v186, v190, v186
	v_add_f32_e32 v160, v160, v186
	v_add_f32_e32 v160, v161, v160
	v_add_f32_e32 v160, v162, v160
	v_add_f32_e32 v159, v159, v160
	v_add_f32_e32 v142, v159, v142
	s_waitcnt lgkmcnt(0)
	v_mfma_f32_32x32x16_bf16 v[2:17], v[248:251], v[164:167], v[2:17]

; #define MFMA32(a, b, c) __builtin_amdgcn_mfma_f32_32x32x16_bf16((a), (b), (c), 0, 0, 0)
; template <int DQK, bool WIN>
; DI void attn_item(const u16* __restrict__ Qb, int ldq, const u16* __restrict__ Kb, int ldk, const u16* __restrict__ Vtb, int qb,
;                   float qscale, float sink2, const u16* __restrict__ zb, int ldz, u16* __restrict__ ob, int ldo, u16* lds) {
;     ...
;       for (int kb = 0; kb < 2; ++kb) {
; #pragma unroll
;         for (int i = 0; i < 16; ++i) st[kb][i] = 0.f;
; #pragma unroll
;         for (int s = 0; s < NKS; ++s) {
;           bf16x8 a = *(const bf16x8*)(ks + (kb * 32 + r) * KST + 16 * s + 8 * hh);
;           st[kb] = MFMA32(a, qf[s], st[kb]);
;         }
;       }
;       float mx = -INFINITY;
; #pragma unroll
;       for (int kb = 0; kb < 2; ++kb)
; #pragma unroll
;         for (int i = 0; i < 16; ++i) {
;           float v = st[kb][i];
;           if (MASK) {
;             int kg = k0 + kb * 32 + (i & 3) + 8 * (i >> 2) + 4 * hh;
;             bool ok = kg <= qrow;
;             if (WIN) ok = ok && (qrow - kg < 128);
;             v = ok ? v : -INFINITY;
;             st[kb][i] = v;
;           }
;           mx = fmaxf(mx, v);
;         }
;       mx = fmaxf(mx, __shfl_xor(mx, 32));
;       const float mn = fmaxf(m, mx);
;       if (__any(mn != m)) {
;         const float alpha = __builtin_amdgcn_exp2f((m - mn) * qscale);
;         lsum *= alpha;
; #pragma unroll
;         for (int i = 0; i < 16; ++i) { o[0][i] *= alpha; o[1][i] *= alpha; }
;       }
.LBB0_258:
	s_and_saveexec_b64 s[24:25], s[8:9]
	s_cbranch_execz .LBB0_262
	ds_read_b128 v[182:185], v155 offset:22528
	ds_read_b128 v[186:189], v155 offset:22560
	ds_read_b128 v[190:193], v155 offset:22592
	ds_read_b128 v[194:197], v155 offset:29216
	ds_read_b128 v[198:201], v155 offset:22624
	ds_read_b128 v[202:205], v155 offset:22656
	ds_read_b128 v[206:209], v155 offset:22688
	ds_read_b128 v[210:213], v155 offset:29184
	ds_read_b128 v[214:217], v155 offset:29248
	ds_read_b128 v[218:221], v155 offset:29280
	ds_read_b128 v[222:225], v155 offset:29312
	ds_read_b128 v[226:229], v155 offset:29344
	s_nop 7
	v_and_b32_e32 v159, 64, v172
	v_xor_b32_e32 v157, 32, v172
	v_add_u32_e32 v159, 64, v159
	s_waitcnt lgkmcnt(11)
	v_mfma_f32_32x32x16_bf16 v[18:33], v[182:185], v[66:69], 0
	v_cmp_lt_i32_e32 vcc, v157, v159
	s_nop 1
	v_cndmask_b32_e32 v157, v172, v157, vcc
	v_lshlrev_b32_e32 v157, 2, v157
	s_waitcnt lgkmcnt(10)
	v_mfma_f32_32x32x16_bf16 v[18:33], v[186:189], v[70:73], v[18:33]
	s_waitcnt lgkmcnt(9)
	v_mfma_f32_32x32x16_bf16 v[18:33], v[190:193], v[74:77], v[18:33]
	s_waitcnt lgkmcnt(7)
	v_mfma_f32_32x32x16_bf16 v[18:33], v[198:201], v[78:81], v[18:33]
	s_waitcnt lgkmcnt(6)
	v_mfma_f32_32x32x16_bf16 v[18:33], v[202:205], v[82:85], v[18:33]
	s_waitcnt lgkmcnt(5)
	v_mfma_f32_32x32x16_bf16 v[18:33], v[206:209], v[86:89], v[18:33]
	s_waitcnt lgkmcnt(4)
	v_mfma_f32_32x32x16_bf16 v[2:17], v[210:213], v[66:69], 0
	s_nop 8
	s_nop 0
	v_max3_f32 v142, v18, s94, v19
	v_max3_f32 v142, v142, v20, v21
	v_max3_f32 v142, v142, v22, v23
	v_max3_f32 v142, v142, v24, v25
	v_max3_f32 v142, v142, v26, v27
	v_max3_f32 v142, v142, v28, v29
	v_max3_f32 v142, v142, v30, v31
	v_mfma_f32_32x32x16_bf16 v[2:17], v[194:197], v[70:73], v[2:17]
	v_max3_f32 v142, v142, v32, v33
	s_waitcnt lgkmcnt(3)
	v_mfma_f32_32x32x16_bf16 v[2:17], v[214:217], v[74:77], v[2:17]
	s_waitcnt lgkmcnt(2)
	v_mfma_f32_32x32x16_bf16 v[2:17], v[218:221], v[78:81], v[2:17]
	s_waitcnt lgkmcnt(1)
	v_mfma_f32_32x32x16_bf16 v[2:17], v[222:225], v[82:85], v[2:17]
	s_waitcnt lgkmcnt(0)
	v_mfma_f32_32x32x16_bf16 v[2:17], v[226:229], v[86:89], v[2:17]
	s_nop 11
	v_max3_f32 v142, v142, v2, v3
	v_max3_f32 v142, v142, v4, v5
	v_max3_f32 v142, v142, v6, v7
	v_max3_f32 v142, v142, v8, v9
	v_max3_f32 v142, v142, v10, v11
	v_max3_f32 v142, v142, v12, v13
	v_max3_f32 v142, v142, v14, v15
	v_max3_f32 v142, v142, v16, v17
	ds_bpermute_b32 v157, v157, v142
	s_waitcnt lgkmcnt(0)
	v_max3_f32 v142, v158, v142, v157
	v_cmp_neq_f32_e32 vcc, v142, v158
	s_cbranch_vccz .LBB0_261
	v_sub_f32_e32 v157, v158, v142
	v_mul_f32_e32 v157, 0x3e16c740, v157
	v_exp_f32_e32 v158, v157
	s_nop 0
	v_mul_f32_e32 v0, v0, v158
	v_pk_mul_f32 v[48:49], v[48:49], v[158:159] op_sel_hi:[1,0]
	v_pk_mul_f32 v[46:47], v[46:47], v[158:159] op_sel_hi:[1,0]
	v_pk_mul_f32 v[44:45], v[44:45], v[158:159] op_sel_hi:[1,0]
	v_pk_mul_f32 v[42:43], v[42:43], v[158:159] op_sel_hi:[1,0]
	v_pk_mul_f32 v[40:41], v[40:41], v[158:159] op_sel_hi:[1,0]
	v_pk_mul_f32 v[38:39], v[38:39], v[158:159] op_sel_hi:[1,0]
	v_pk_mul_f32 v[36:37], v[36:37], v[158:159] op_sel_hi:[1,0]
	v_pk_mul_f32 v[34:35], v[34:35], v[158:159] op_sel_hi:[1,0]
	v_pk_mul_f32 v[64:65], v[64:65], v[158:159] op_sel_hi:[1,0]
	v_pk_mul_f32 v[62:63], v[62:63], v[158:159] op_sel_hi:[1,0]
	v_pk_mul_f32 v[60:61], v[60:61], v[158:159] op_sel_hi:[1,0]
	v_pk_mul_f32 v[58:59], v[58:59], v[158:159] op_sel_hi:[1,0]
	v_pk_mul_f32 v[56:57], v[56:57], v[158:159] op_sel_hi:[1,0]
	v_pk_mul_f32 v[54:55], v[54:55], v[158:159] op_sel_hi:[1,0]
	v_pk_mul_f32 v[52:53], v[52:53], v[158:159] op_sel_hi:[1,0]
	v_pk_mul_f32 v[50:51], v[50:51], v[158:159] op_sel_hi:[1,0]
; DI unsigned pack2(float a, float b) { unsigned r; asm("v_cvt_pk_bf16_f32 %0, %1, %2\n\ts_nop 1" : "=v"(r) : "v"(a), "v"(b)); return r; }
; #define MFMA32(a, b, c) __builtin_amdgcn_mfma_f32_32x32x16_bf16((a), (b), (c), 0, 0, 0)
; template <int DQK, bool WIN>
; DI void attn_item(const u16* __restrict__ Qb, int ldq, const u16* __restrict__ Kb, int ldk, const u16* __restrict__ Vtb, int qb,
;                   float qscale, float sink2, const u16* __restrict__ zb, int ldz, u16* __restrict__ ob, int ldo, u16* lds) {
;     ...
;       const float nb = -mn * qscale;
;       float ps = 0.f;
; #pragma unroll
;       for (int kb = 0; kb < 2; ++kb)
; #pragma unroll
;         for (int i = 0; i < 16; ++i) { float pv = __builtin_amdgcn_exp2f(fmaf(st[kb][i], qscale, nb)); st[kb][i] = pv; ps += pv; }
;       lsum += ps;
; #pragma unroll
;       for (int kb = 0; kb < 2; ++kb)
; #pragma unroll
;         for (int s2 = 0; s2 < 2; ++s2) {
;           union { bf16x8 v; unsigned u[4]; } pf;
; #pragma unroll
;           for (int j = 0; j < 4; ++j) pf.u[j] = pack2(st[kb][8 * s2 + 2 * j], st[kb][8 * s2 + 2 * j + 1]);
; #pragma unroll
;           for (int vb = 0; vb < 2; ++vb) {
;             const bf16x8 vf = *(const bf16x8*)(vs + (vb * 32 + r) * 72 + (kb * 2 + s2) * 16 + hh * 8);
;             o[vb] = MFMA32(vf, pf.v, o[vb]);
;           }
;         }
.LBB0_261:
	ds_read_b128 v[186:189], v156 offset:35840
	ds_read_b128 v[190:193], v156 offset:35872
	ds_read_b128 v[194:197], v156 offset:40448
	ds_read_b128 v[198:201], v156 offset:40480
	ds_read_b128 v[202:205], v156 offset:35904
	ds_read_b128 v[206:209], v156 offset:40512
	ds_read_b128 v[210:213], v156 offset:35936
	ds_read_b128 v[214:217], v156 offset:40544
	v_mul_f32_e32 v157, 0xbe16c740, v142
	v_fmamk_f32 v18, v18, 0x3e16c740, v157
	v_exp_f32_e32 v18, v18
	v_fmamk_f32 v19, v19, 0x3e16c740, v157
	v_exp_f32_e32 v19, v19
	v_fmamk_f32 v20, v20, 0x3e16c740, v157
	v_exp_f32_e32 v20, v20
	v_fmamk_f32 v21, v21, 0x3e16c740, v157
	v_exp_f32_e32 v21, v21
	v_fmamk_f32 v22, v22, 0x3e16c740, v157
	v_add_f32_e32 v158, 0, v18
	v_exp_f32_e32 v22, v22
	v_fmamk_f32 v23, v23, 0x3e16c740, v157
	v_add_f32_e32 v158, v19, v158
	v_exp_f32_e32 v23, v23
	v_fmamk_f32 v24, v24, 0x3e16c740, v157
	v_add_f32_e32 v158, v20, v158
	v_exp_f32_e32 v24, v24
	v_fmamk_f32 v25, v25, 0x3e16c740, v157
	v_add_f32_e32 v158, v21, v158
	v_exp_f32_e32 v25, v25
	v_fmamk_f32 v26, v26, 0x3e16c740, v157
	v_add_f32_e32 v158, v22, v158
	v_exp_f32_e32 v26, v26
	v_fmamk_f32 v27, v27, 0x3e16c740, v157
	v_add_f32_e32 v158, v23, v158
	v_exp_f32_e32 v27, v27
	v_fmamk_f32 v28, v28, 0x3e16c740, v157
	v_add_f32_e32 v158, v24, v158
	v_exp_f32_e32 v28, v28
	v_fmamk_f32 v29, v29, 0x3e16c740, v157
	v_add_f32_e32 v158, v25, v158
	v_exp_f32_e32 v29, v29
	v_fmamk_f32 v30, v30, 0x3e16c740, v157
	v_add_f32_e32 v158, v26, v158
	v_exp_f32_e32 v30, v30
	v_fmamk_f32 v31, v31, 0x3e16c740, v157
	v_add_f32_e32 v158, v27, v158
	v_exp_f32_e32 v31, v31
	v_fmamk_f32 v32, v32, 0x3e16c740, v157
	v_add_f32_e32 v158, v28, v158
	v_exp_f32_e32 v32, v32
	v_fmamk_f32 v33, v33, 0x3e16c740, v157
	v_add_f32_e32 v158, v29, v158
	v_exp_f32_e32 v33, v33
	v_fmamk_f32 v2, v2, 0x3e16c740, v157
	v_add_f32_e32 v158, v30, v158
	v_exp_f32_e32 v159, v2
	v_add_f32_e32 v158, v31, v158
	v_add_f32_e32 v158, v32, v158
	v_add_f32_e32 v158, v33, v158
	v_fmamk_f32 v3, v3, 0x3e16c740, v157
	v_add_f32_e32 v2, v159, v158
	v_exp_f32_e32 v158, v3
	v_fmamk_f32 v3, v4, 0x3e16c740, v157
	v_exp_f32_e32 v160, v3
	v_fmamk_f32 v3, v5, 0x3e16c740, v157
	v_exp_f32_e32 v161, v3
	v_fmamk_f32 v3, v6, 0x3e16c740, v157
	v_exp_f32_e32 v162, v3
	v_fmamk_f32 v3, v7, 0x3e16c740, v157
	v_add_f32_e32 v2, v158, v2
	v_exp_f32_e32 v164, v3
	v_fmamk_f32 v3, v8, 0x3e16c740, v157
	v_add_f32_e32 v2, v160, v2
	v_exp_f32_e32 v165, v3
	v_fmamk_f32 v3, v9, 0x3e16c740, v157
	v_add_f32_e32 v2, v161, v2
	v_exp_f32_e32 v166, v3
	v_fmamk_f32 v3, v10, 0x3e16c740, v157
	v_add_f32_e32 v2, v162, v2
	v_exp_f32_e32 v167, v3
	v_fmamk_f32 v3, v11, 0x3e16c740, v157
	v_add_f32_e32 v2, v164, v2
	v_exp_f32_e32 v182, v3
	v_fmamk_f32 v3, v12, 0x3e16c740, v157
	v_add_f32_e32 v2, v165, v2
	v_exp_f32_e32 v183, v3
	v_fmamk_f32 v3, v13, 0x3e16c740, v157
	v_add_f32_e32 v2, v166, v2
	v_exp_f32_e32 v184, v3
	v_fmamk_f32 v3, v14, 0x3e16c740, v157
	v_add_f32_e32 v2, v167, v2
	v_exp_f32_e32 v14, v3
	v_fmamk_f32 v3, v15, 0x3e16c740, v157
	v_add_f32_e32 v2, v182, v2
	v_exp_f32_e32 v15, v3
	v_fmamk_f32 v3, v16, 0x3e16c740, v157
	v_add_f32_e32 v2, v183, v2
	v_exp_f32_e32 v16, v3
	v_fmac_f32_e32 v157, 0x3e16c740, v17
	v_add_f32_e32 v2, v184, v2
	v_exp_f32_e32 v17, v157
	v_add_f32_e32 v2, v14, v2
	v_add_f32_e32 v2, v15, v2
	v_add_f32_e32 v2, v16, v2
	v_add_f32_e32 v2, v17, v2
	v_add_f32_e32 v0, v2, v0
	v_cvt_pk_bf16_f32 v2, v18, v19
	s_nop 1
	v_cvt_pk_bf16_f32 v3, v20, v21
	s_nop 1
	v_cvt_pk_bf16_f32 v4, v22, v23
	s_nop 1
	v_cvt_pk_bf16_f32 v5, v24, v25
	s_nop 1
	s_waitcnt lgkmcnt(7)
	v_mfma_f32_32x32x16_bf16 v[34:49], v[186:189], v[2:5], v[34:49]
	s_waitcnt lgkmcnt(5)
	v_mfma_f32_32x32x16_bf16 v[50:65], v[194:197], v[2:5], v[50:65]
	v_cvt_pk_bf16_f32 v2, v26, v27
	s_nop 1
	v_cvt_pk_bf16_f32 v3, v28, v29
	s_nop 1
	v_cvt_pk_bf16_f32 v4, v30, v31
	s_nop 1
	v_cvt_pk_bf16_f32 v5, v32, v33
	s_nop 1
	s_waitcnt lgkmcnt(4)
	v_mfma_f32_32x32x16_bf16 v[50:65], v[198:201], v[2:5], v[50:65]
	v_mfma_f32_32x32x16_bf16 v[34:49], v[190:193], v[2:5], v[34:49]
	v_cvt_pk_bf16_f32 v2, v159, v158
	s_nop 1
	v_cvt_pk_bf16_f32 v3, v160, v161
	s_nop 1
	v_cvt_pk_bf16_f32 v4, v162, v164
	s_nop 1
	v_cvt_pk_bf16_f32 v5, v165, v166
	s_nop 1
	v_mov_b32_e32 v158, v142
	s_waitcnt lgkmcnt(3)
	v_mfma_f32_32x32x16_bf16 v[34:49], v[202:205], v[2:5], v[34:49]
	s_waitcnt lgkmcnt(2)
	v_mfma_f32_32x32x16_bf16 v[50:65], v[206:209], v[2:5], v[50:65]
	v_cvt_pk_bf16_f32 v2, v167, v182
	s_nop 1
	v_cvt_pk_bf16_f32 v3, v183, v184
	s_nop 1
	v_cvt_pk_bf16_f32 v4, v14, v15
	s_nop 1
	v_cvt_pk_bf16_f32 v5, v16, v17
	s_nop 1
	s_waitcnt lgkmcnt(1)
	v_mfma_f32_32x32x16_bf16 v[34:49], v[210:213], v[2:5], v[34:49]
	s_waitcnt lgkmcnt(0)
	v_mfma_f32_32x32x16_bf16 v[50:65], v[214:217], v[2:5], v[50:65]

; #define MFMA32(a, b, c) __builtin_amdgcn_mfma_f32_32x32x16_bf16((a), (b), (c), 0, 0, 0)
; template <int DQK, bool WIN>
; DI void attn_item(const u16* __restrict__ Qb, int ldq, const u16* __restrict__ Kb, int ldk, const u16* __restrict__ Vtb, int qb,
;                   float qscale, float sink2, const u16* __restrict__ zb, int ldz, u16* __restrict__ ob, int ldo, u16* lds) {
;     ...
;     bool active = (k0 <= q0 + 31);
;     if (WIN) active = active && (k0 + 63 >= q0 - 127);
;     if (active) {
;       f32x16 st[2];
; #pragma unroll
;       for (int kb = 0; kb < 2; ++kb) {
; #pragma unroll
;         for (int i = 0; i < 16; ++i) st[kb][i] = 0.f;
; #pragma unroll
;         for (int s = 0; s < NKS; ++s) {
;           bf16x8 a = *(const bf16x8*)(ks + (kb * 32 + r) * KST + 16 * s + 8 * hh);
;           st[kb] = MFMA32(a, qf[s], st[kb]);
;         }
;       }
;       float mx = -INFINITY;
; #pragma unroll
;       for (int kb = 0; kb < 2; ++kb)
; #pragma unroll
;         for (int i = 0; i < 16; ++i) {
;           float v = st[kb][i];
;           if (MASK) {
;             int kg = k0 + kb * 32 + (i & 3) + 8 * (i >> 2) + 4 * hh;
;             bool ok = kg <= qrow;
;             if (WIN) ok = ok && (qrow - kg < 128);
;             v = ok ? v : -INFINITY;
;             st[kb][i] = v;
;           }
;           mx = fmaxf(mx, v);
;         }
.LBB0_317:
	s_add_i32 s0, s26, 0xffffff40
	v_cmp_le_i32_e32 vcc, s0, v137
	s_add_i32 s0, s26, 0xffffff7f
	v_cmp_ge_i32_e64 s[8:9], s0, v138
	s_and_b64 s[0:1], vcc, s[8:9]
	v_add_u32_e32 v143, s26, v0
	s_and_saveexec_b64 s[34:35], s[0:1]
	s_cbranch_execz .LBB0_321
	ds_read_b128 v[152:155], v139
	ds_read_b128 v[164:167], v139 offset:32
	ds_read_b128 v[182:185], v139 offset:64
	ds_read_b128 v[186:189], v139 offset:4640
	ds_read_b128 v[190:193], v139 offset:96
	ds_read_b128 v[194:197], v139 offset:4608
	ds_read_b128 v[198:201], v139 offset:4672
	ds_read_b128 v[202:205], v139 offset:4704
	v_add_u32_e32 v145, 0xffffff40, v143
	v_cmp_le_i32_e64 s[8:9], v145, v114
	s_movk_i32 s0, 0xff7f
	s_waitcnt lgkmcnt(7)
	v_mfma_f32_32x32x16_bf16 v[50:65], v[152:155], v[66:69], 0
	s_waitcnt lgkmcnt(6)
	v_mfma_f32_32x32x16_bf16 v[50:65], v[164:167], v[70:73], v[50:65]
	s_waitcnt lgkmcnt(5)
	v_mfma_f32_32x32x16_bf16 v[50:65], v[182:185], v[74:77], v[50:65]
	s_waitcnt lgkmcnt(3)
	v_mfma_f32_32x32x16_bf16 v[50:65], v[190:193], v[78:81], v[50:65]
	s_waitcnt lgkmcnt(2)
	v_mfma_f32_32x32x16_bf16 v[34:49], v[194:197], v[66:69], 0
	v_mfma_f32_32x32x16_bf16 v[34:49], v[186:189], v[70:73], v[34:49]
	s_waitcnt lgkmcnt(1)
	v_mfma_f32_32x32x16_bf16 v[34:49], v[198:201], v[74:77], v[34:49]
	s_waitcnt lgkmcnt(0)
	v_mfma_f32_32x32x16_bf16 v[34:49], v[202:205], v[78:81], v[34:49]
	v_add_u32_e32 v146, 59, v141
	v_cmp_gt_i32_e32 vcc, s93, v146
	s_and_b64 vcc, s[8:9], vcc
	v_add_u32_e32 v146, 0xffffff42, v143
	s_nop 0
	v_cndmask_b32_e32 v50, v176, v50, vcc
	v_cmp_lt_i32_e32 vcc, v145, v114
	v_add_u32_e32 v145, s26, v142
	v_add_u32_e32 v145, 0xffffff40, v145
	v_cmp_lt_i32_e64 s[8:9], s0, v145
	s_and_b64 vcc, vcc, s[8:9]
	v_add_u32_e32 v147, 57, v141
	v_cndmask_b32_e32 v51, v176, v51, vcc
	v_cmp_gt_i32_e32 vcc, s93, v147
	v_cmp_le_i32_e64 s[8:9], v146, v114
	s_and_b64 vcc, s[8:9], vcc
	v_add_u32_e32 v146, 0xffffff43, v143
	v_add_u32_e32 v147, 56, v141
	v_cndmask_b32_e32 v52, v176, v52, vcc
	v_cmp_gt_i32_e32 vcc, s93, v147
	v_cmp_le_i32_e64 s[8:9], v146, v114
	s_and_b64 vcc, s[8:9], vcc
	v_add_u32_e32 v146, 0xffffff48, v143
	v_add_u32_e32 v147, 51, v141
	v_cndmask_b32_e32 v53, v176, v53, vcc
	v_cmp_gt_i32_e32 vcc, s93, v147
	v_cmp_le_i32_e64 s[8:9], v146, v114
	s_and_b64 vcc, s[8:9], vcc
	v_cndmask_b32_e32 v148, v176, v54, vcc
	v_add_u32_e32 v54, 0xffffff49, v143
	v_add_u32_e32 v146, 50, v141
	v_cmp_gt_i32_e32 vcc, s93, v146
	v_cmp_le_i32_e64 s[8:9], v54, v114
	v_max3_f32 v145, v50, s94, v51
	s_and_b64 vcc, s[8:9], vcc
	v_max3_f32 v145, v145, v52, v53
	v_cndmask_b32_e32 v147, v176, v55, vcc
	v_max3_f32 v54, v145, v148, v147
	v_add_u32_e32 v55, 0xffffff4a, v143
	v_add_u32_e32 v145, 49, v141
	v_cmp_gt_i32_e32 vcc, s93, v145
	v_cmp_le_i32_e64 s[8:9], v55, v114
	s_and_b64 vcc, s[8:9], vcc
	v_cndmask_b32_e32 v149, v176, v56, vcc
	v_add_u32_e32 v55, 0xffffff4b, v143
	v_add_u32_e32 v56, 48, v141
	v_cmp_gt_i32_e32 vcc, s93, v56
	v_cmp_le_i32_e64 s[8:9], v55, v114
	s_and_b64 vcc, s[8:9], vcc
	v_add_u32_e32 v55, 0xffffff50, v143
	v_add_u32_e32 v56, 43, v141
	v_cndmask_b32_e32 v150, v176, v57, vcc
	v_cmp_gt_i32_e32 vcc, s93, v56
	v_cmp_le_i32_e64 s[8:9], v55, v114
	s_and_b64 vcc, s[8:9], vcc
	v_add_u32_e32 v55, 0xffffff51, v143
	v_add_u32_e32 v56, 42, v141
	v_cndmask_b32_e32 v151, v176, v58, vcc
	v_cmp_gt_i32_e32 vcc, s93, v56
	v_cmp_le_i32_e64 s[8:9], v55, v114
	s_and_b64 vcc, s[8:9], vcc
	v_add_u32_e32 v55, 0xffffff52, v143
	v_add_u32_e32 v56, 41, v141
	v_cndmask_b32_e32 v145, v176, v59, vcc
	v_cmp_gt_i32_e32 vcc, s93, v56
	v_cmp_le_i32_e64 s[8:9], v55, v114
	s_and_b64 vcc, s[8:9], vcc
	v_add_u32_e32 v55, 0xffffff53, v143
	v_add_u32_e32 v56, 40, v141
	v_cndmask_b32_e32 v146, v176, v60, vcc
	v_cmp_gt_i32_e32 vcc, s93, v56
	v_cmp_le_i32_e64 s[8:9], v55, v114
	s_and_b64 vcc, s[8:9], vcc
	v_add_u32_e32 v55, 0xffffff58, v143
	v_add_u32_e32 v56, 35, v141
	v_cndmask_b32_e32 v60, v176, v61, vcc
	v_cmp_gt_i32_e32 vcc, s93, v56
	v_cmp_le_i32_e64 s[8:9], v55, v114
	s_and_b64 vcc, s[8:9], vcc
	v_add_u32_e32 v55, 0xffffff59, v143
	v_add_u32_e32 v56, 34, v141
	v_cndmask_b32_e32 v61, v176, v62, vcc
	v_cmp_gt_i32_e32 vcc, s93, v56
	v_cmp_le_i32_e64 s[8:9], v55, v114
	s_and_b64 vcc, s[8:9], vcc
	v_add_u32_e32 v55, 0xffffff5a, v143
	v_add_u32_e32 v56, 33, v141
	v_cndmask_b32_e32 v58, v176, v63, vcc
	v_cmp_gt_i32_e32 vcc, s93, v56
	v_cmp_le_i32_e64 s[8:9], v55, v114
	v_max3_f32 v54, v54, v149, v150
	s_and_b64 vcc, s[8:9], vcc
	v_add_u32_e32 v55, 0xffffff5b, v143
	v_add_u32_e32 v56, 32, v141
	v_max3_f32 v54, v54, v151, v145
	v_cndmask_b32_e32 v59, v176, v64, vcc
	v_cmp_gt_i32_e32 vcc, s93, v56
	v_cmp_le_i32_e64 s[8:9], v55, v114
	v_max3_f32 v54, v54, v146, v60
	s_and_b64 vcc, s[8:9], vcc
	v_max3_f32 v54, v54, v61, v58
	v_cndmask_b32_e32 v56, v176, v65, vcc
	v_max3_f32 v55, v54, v59, v56
	v_add_u32_e32 v54, 0xffffff60, v143
	v_add_u32_e32 v57, 27, v141
	v_cmp_gt_i32_e32 vcc, s93, v57
	v_cmp_le_i32_e64 s[8:9], v54, v114
	s_and_b64 vcc, s[8:9], vcc
	v_cndmask_b32_e32 v57, v176, v34, vcc
	v_add_u32_e32 v34, 0xffffff61, v143
	v_add_u32_e32 v54, 26, v141
	v_cmp_gt_i32_e32 vcc, s93, v54
	v_cmp_le_i32_e64 s[8:9], v34, v114
	s_and_b64 vcc, s[8:9], vcc
	v_cndmask_b32_e32 v54, v176, v35, vcc
	v_max3_f32 v34, v55, v57, v54
	v_add_u32_e32 v35, 0xffffff62, v143
	v_add_u32_e32 v55, 25, v141
	v_cmp_gt_i32_e32 vcc, s93, v55
	v_cmp_le_i32_e64 s[8:9], v35, v114
	s_and_b64 vcc, s[8:9], vcc
	v_cndmask_b32_e32 v55, v176, v36, vcc
	v_add_u32_e32 v35, 0xffffff63, v143
	v_add_u32_e32 v36, 24, v141
	v_cmp_gt_i32_e32 vcc, s93, v36
	v_cmp_le_i32_e64 s[8:9], v35, v114
	s_and_b64 vcc, s[8:9], vcc
	v_cndmask_b32_e32 v36, v176, v37, vcc
; template <int DQK, bool WIN>
; DI void attn_item(const u16* __restrict__ Qb, int ldq, const u16* __restrict__ Kb, int ldk, const u16* __restrict__ Vtb, int qb,
;                   float qscale, float sink2, const u16* __restrict__ zb, int ldz, u16* __restrict__ ob, int ldo, u16* lds) {
;     ...
;           if (MASK) {
;             int kg = k0 + kb * 32 + (i & 3) + 8 * (i >> 2) + 4 * hh;
;             bool ok = kg <= qrow;
;             if (WIN) ok = ok && (qrow - kg < 128);
;             v = ok ? v : -INFINITY;
;             st[kb][i] = v;
;           }
;           mx = fmaxf(mx, v);
;         }
;       mx = fmaxf(mx, __shfl_xor(mx, 32));
;       const float mn = fmaxf(m, mx);
;       if (__any(mn != m)) {
;         const float alpha = __builtin_amdgcn_exp2f((m - mn) * qscale);
;         lsum *= alpha;
; #pragma unroll
;         for (int i = 0; i < 16; ++i) { o[0][i] *= alpha; o[1][i] *= alpha; }
;       }
;       m = mn;
	v_add_u32_e32 v35, 0xffffff68, v143
	v_add_u32_e32 v37, 19, v141
	v_cmp_gt_i32_e32 vcc, s93, v37
	v_cmp_le_i32_e64 s[8:9], v35, v114
	s_and_b64 vcc, s[8:9], vcc
	v_cndmask_b32_e32 v37, v176, v38, vcc
	v_add_u32_e32 v35, 0xffffff69, v143
	v_add_u32_e32 v38, 18, v141
	v_cmp_gt_i32_e32 vcc, s93, v38
	v_cmp_le_i32_e64 s[8:9], v35, v114
	s_and_b64 vcc, s[8:9], vcc
	v_cndmask_b32_e32 v35, v176, v39, vcc
	v_add_u32_e32 v38, 0xffffff6a, v143
	v_add_u32_e32 v39, 17, v141
	v_cmp_gt_i32_e32 vcc, s93, v39
	v_cmp_le_i32_e64 s[8:9], v38, v114
	s_and_b64 vcc, s[8:9], vcc
	v_cndmask_b32_e32 v38, v176, v40, vcc
	v_add_u32_e32 v39, 0xffffff6b, v143
	v_add_u32_e32 v40, 16, v141
	v_cmp_gt_i32_e32 vcc, s93, v40
	v_cmp_le_i32_e64 s[8:9], v39, v114
	s_and_b64 vcc, s[8:9], vcc
	v_cndmask_b32_e32 v39, v176, v41, vcc
	v_add_u32_e32 v40, 0xffffff70, v143
	v_add_u32_e32 v41, 11, v141
	v_cmp_gt_i32_e32 vcc, s93, v41
	v_cmp_le_i32_e64 s[8:9], v40, v114
	s_and_b64 vcc, s[8:9], vcc
	v_cndmask_b32_e32 v40, v176, v42, vcc
	v_add_u32_e32 v41, 0xffffff71, v143
	v_add_u32_e32 v42, 10, v141
	v_cmp_gt_i32_e32 vcc, s93, v42
	v_cmp_le_i32_e64 s[8:9], v41, v114
	s_and_b64 vcc, s[8:9], vcc
	v_cndmask_b32_e32 v41, v176, v43, vcc
	v_add_u32_e32 v42, 0xffffff72, v143
	v_add_u32_e32 v43, 9, v141
	v_cmp_gt_i32_e32 vcc, s93, v43
	v_cmp_le_i32_e64 s[8:9], v42, v114
	s_and_b64 vcc, s[8:9], vcc
	v_cndmask_b32_e32 v42, v176, v44, vcc
	v_add_u32_e32 v43, 0xffffff73, v143
	v_add_u32_e32 v44, 8, v141
	v_cmp_gt_i32_e32 vcc, s93, v44
	v_cmp_le_i32_e64 s[8:9], v43, v114
	s_and_b64 vcc, s[8:9], vcc
	v_cndmask_b32_e32 v43, v176, v45, vcc
	v_add_u32_e32 v44, 0xffffff78, v143
	v_add_u32_e32 v45, 3, v141
	v_cmp_gt_i32_e32 vcc, s93, v45
	v_cmp_le_i32_e64 s[8:9], v44, v114
	s_and_b64 vcc, s[8:9], vcc
	v_cndmask_b32_e32 v44, v176, v46, vcc
	v_add_u32_e32 v45, 0xffffff79, v143
	v_add_u32_e32 v46, 2, v141
	v_cmp_gt_i32_e32 vcc, s93, v46
	v_cmp_le_i32_e64 s[8:9], v45, v114
	s_and_b64 vcc, s[8:9], vcc
	v_cndmask_b32_e32 v45, v176, v47, vcc
	v_add_u32_e32 v46, 0xffffff7a, v143
	v_add_u32_e32 v47, 1, v141
	v_cmp_gt_i32_e32 vcc, s93, v47
	v_cmp_le_i32_e64 s[8:9], v46, v114
	s_and_b64 vcc, s[8:9], vcc
	v_add_u32_e32 v47, 0xffffff7b, v143
	v_max3_f32 v34, v34, v55, v36
	v_cndmask_b32_e32 v46, v176, v48, vcc
	v_cmp_gt_i32_e32 vcc, s93, v141
	v_cmp_le_i32_e64 s[8:9], v47, v114
	v_max3_f32 v34, v34, v37, v35
	s_and_b64 vcc, s[8:9], vcc
	v_max3_f32 v34, v34, v38, v39
	v_cndmask_b32_e32 v47, v176, v49, vcc
	v_and_b32_e32 v49, 64, v172
	v_max3_f32 v34, v34, v40, v41
	v_xor_b32_e32 v48, 32, v172
	v_add_u32_e32 v49, 64, v49
	v_max3_f32 v34, v34, v42, v43
	v_cmp_lt_i32_e32 vcc, v48, v49
	v_max3_f32 v34, v34, v44, v45
	v_max3_f32 v34, v34, v46, v47
	v_cndmask_b32_e32 v48, v172, v48, vcc
	v_lshlrev_b32_e32 v48, 2, v48
	ds_bpermute_b32 v48, v48, v34
	s_waitcnt lgkmcnt(0)
	v_max3_f32 v34, v144, v34, v48
	v_cmp_neq_f32_e32 vcc, v34, v144
	s_cbranch_vccz .LBB0_320
	v_sub_f32_e32 v48, v144, v34
	v_mul_f32_e32 v48, 0x3e38aa3b, v48
	v_exp_f32_e32 v48, v48
	s_nop 0
	v_mul_f32_e32 v116, v116, v48
	v_pk_mul_f32 v[32:33], v[32:33], v[48:49] op_sel_hi:[1,0]
	v_pk_mul_f32 v[30:31], v[30:31], v[48:49] op_sel_hi:[1,0]
	v_pk_mul_f32 v[28:29], v[28:29], v[48:49] op_sel_hi:[1,0]
	v_pk_mul_f32 v[26:27], v[26:27], v[48:49] op_sel_hi:[1,0]
	v_pk_mul_f32 v[24:25], v[24:25], v[48:49] op_sel_hi:[1,0]
	v_pk_mul_f32 v[22:23], v[22:23], v[48:49] op_sel_hi:[1,0]
	v_pk_mul_f32 v[20:21], v[20:21], v[48:49] op_sel_hi:[1,0]
	v_pk_mul_f32 v[18:19], v[18:19], v[48:49] op_sel_hi:[1,0]
	v_pk_mul_f32 v[16:17], v[16:17], v[48:49] op_sel_hi:[1,0]
	v_pk_mul_f32 v[14:15], v[14:15], v[48:49] op_sel_hi:[1,0]
	v_pk_mul_f32 v[12:13], v[12:13], v[48:49] op_sel_hi:[1,0]
	v_pk_mul_f32 v[10:11], v[10:11], v[48:49] op_sel_hi:[1,0]
	v_pk_mul_f32 v[8:9], v[8:9], v[48:49] op_sel_hi:[1,0]
	v_pk_mul_f32 v[6:7], v[6:7], v[48:49] op_sel_hi:[1,0]
	v_pk_mul_f32 v[4:5], v[4:5], v[48:49] op_sel_hi:[1,0]
	v_pk_mul_f32 v[2:3], v[2:3], v[48:49] op_sel_hi:[1,0]
; DI unsigned pack2(float a, float b) { unsigned r; asm("v_cvt_pk_bf16_f32 %0, %1, %2\n\ts_nop 1" : "=v"(r) : "v"(a), "v"(b)); return r; }
; #define MFMA32(a, b, c) __builtin_amdgcn_mfma_f32_32x32x16_bf16((a), (b), (c), 0, 0, 0)
; template <int DQK, bool WIN>
; DI void attn_item(const u16* __restrict__ Qb, int ldq, const u16* __restrict__ Kb, int ldk, const u16* __restrict__ Vtb, int qb,
;                   float qscale, float sink2, const u16* __restrict__ zb, int ldz, u16* __restrict__ ob, int ldo, u16* lds) {
;     ...
;       const float nb = -mn * qscale;
;       float ps = 0.f;
; #pragma unroll
;       for (int kb = 0; kb < 2; ++kb)
; #pragma unroll
;         for (int i = 0; i < 16; ++i) { float pv = __builtin_amdgcn_exp2f(fmaf(st[kb][i], qscale, nb)); st[kb][i] = pv; ps += pv; }
;       lsum += ps;
; #pragma unroll
;       for (int kb = 0; kb < 2; ++kb)
; #pragma unroll
;         for (int s2 = 0; s2 < 2; ++s2) {
;           union { bf16x8 v; unsigned u[4]; } pf;
; #pragma unroll
;           for (int j = 0; j < 4; ++j) pf.u[j] = pack2(st[kb][8 * s2 + 2 * j], st[kb][8 * s2 + 2 * j + 1]);
; #pragma unroll
;           for (int vb = 0; vb < 2; ++vb) {
;             const bf16x8 vf = *(const bf16x8*)(vs + (vb * 32 + r) * 72 + (kb * 2 + s2) * 16 + hh * 8);
;             o[vb] = MFMA32(vf, pf.v, o[vb]);
;           }
;         }
.LBB0_320:
	ds_read_b128 v[164:167], v140 offset:9216
	ds_read_b128 v[182:185], v140 offset:9248
	ds_read_b128 v[186:189], v140 offset:13824
	ds_read_b128 v[190:193], v140 offset:13856
	ds_read_b128 v[194:197], v140 offset:9280
	ds_read_b128 v[198:201], v140 offset:13888
	ds_read_b128 v[202:205], v140 offset:9312
	ds_read_b128 v[206:209], v140 offset:13920
	v_mul_f32_e32 v48, 0xbe38aa3b, v34
	v_fmamk_f32 v49, v50, 0x3e38aa3b, v48
	v_exp_f32_e32 v49, v49
	v_fmamk_f32 v51, v51, 0x3e38aa3b, v48
	v_exp_f32_e32 v51, v51
	v_fmamk_f32 v52, v52, 0x3e38aa3b, v48
	v_exp_f32_e32 v52, v52
	v_fmamk_f32 v53, v53, 0x3e38aa3b, v48
	v_exp_f32_e32 v53, v53
	v_fmamk_f32 v62, v148, 0x3e38aa3b, v48
	v_add_f32_e32 v50, 0, v49
	v_exp_f32_e32 v62, v62
	v_fmamk_f32 v63, v147, 0x3e38aa3b, v48
	v_add_f32_e32 v50, v51, v50
	v_exp_f32_e32 v63, v63
	v_fmamk_f32 v64, v149, 0x3e38aa3b, v48
	v_add_f32_e32 v50, v52, v50
	v_exp_f32_e32 v64, v64
	v_fmamk_f32 v65, v150, 0x3e38aa3b, v48
	v_add_f32_e32 v50, v53, v50
	v_exp_f32_e32 v65, v65
	v_fmamk_f32 v144, v151, 0x3e38aa3b, v48
	v_add_f32_e32 v50, v62, v50
	v_exp_f32_e32 v144, v144
	v_fmamk_f32 v145, v145, 0x3e38aa3b, v48
	v_add_f32_e32 v50, v63, v50
	v_exp_f32_e32 v145, v145
	v_fmamk_f32 v146, v146, 0x3e38aa3b, v48
	v_add_f32_e32 v50, v64, v50
	v_exp_f32_e32 v146, v146
	v_fmamk_f32 v60, v60, 0x3e38aa3b, v48
	v_add_f32_e32 v50, v65, v50
	v_exp_f32_e32 v60, v60
	v_fmamk_f32 v61, v61, 0x3e38aa3b, v48
	v_add_f32_e32 v50, v144, v50
	v_exp_f32_e32 v61, v61
	v_fmamk_f32 v58, v58, 0x3e38aa3b, v48
	v_add_f32_e32 v50, v145, v50
	v_exp_f32_e32 v58, v58
	v_fmamk_f32 v59, v59, 0x3e38aa3b, v48
	v_add_f32_e32 v50, v146, v50
	v_exp_f32_e32 v59, v59
	v_fmamk_f32 v56, v56, 0x3e38aa3b, v48
	v_add_f32_e32 v50, v60, v50
	v_exp_f32_e32 v56, v56
	v_fmamk_f32 v57, v57, 0x3e38aa3b, v48
	v_add_f32_e32 v50, v61, v50
	v_exp_f32_e32 v57, v57
	v_fmamk_f32 v54, v54, 0x3e38aa3b, v48
	v_add_f32_e32 v50, v58, v50
	v_exp_f32_e32 v54, v54
	v_fmamk_f32 v55, v55, 0x3e38aa3b, v48
	v_add_f32_e32 v50, v59, v50
	v_exp_f32_e32 v55, v55
	v_fmamk_f32 v36, v36, 0x3e38aa3b, v48
	v_add_f32_e32 v50, v56, v50
	v_exp_f32_e32 v147, v36
	v_add_f32_e32 v50, v57, v50
	v_add_f32_e32 v50, v54, v50
	v_add_f32_e32 v50, v55, v50
	v_fmamk_f32 v37, v37, 0x3e38aa3b, v48
	v_add_f32_e32 v36, v147, v50
	v_exp_f32_e32 v50, v37
	v_fmamk_f32 v35, v35, 0x3e38aa3b, v48
	v_exp_f32_e32 v35, v35
	v_fmamk_f32 v37, v38, 0x3e38aa3b, v48
	v_exp_f32_e32 v148, v37
	v_fmamk_f32 v37, v39, 0x3e38aa3b, v48
	v_exp_f32_e32 v149, v37
	v_fmamk_f32 v37, v40, 0x3e38aa3b, v48
	v_add_f32_e32 v36, v50, v36
	v_exp_f32_e32 v150, v37
	v_fmamk_f32 v37, v41, 0x3e38aa3b, v48
	v_add_f32_e32 v36, v35, v36
	v_exp_f32_e32 v151, v37
	v_fmamk_f32 v37, v42, 0x3e38aa3b, v48
	v_add_f32_e32 v36, v148, v36
	v_exp_f32_e32 v152, v37
	v_fmamk_f32 v37, v43, 0x3e38aa3b, v48
	v_add_f32_e32 v36, v149, v36
	v_exp_f32_e32 v153, v37
	v_fmamk_f32 v37, v44, 0x3e38aa3b, v48
	v_add_f32_e32 v36, v150, v36
	v_exp_f32_e32 v154, v37
	v_fmamk_f32 v37, v45, 0x3e38aa3b, v48
	v_add_f32_e32 v36, v151, v36
	v_exp_f32_e32 v155, v37
	v_fmamk_f32 v37, v46, 0x3e38aa3b, v48
	v_add_f32_e32 v36, v152, v36
	v_exp_f32_e32 v156, v37
	v_fmac_f32_e32 v48, 0x3e38aa3b, v47
	v_add_f32_e32 v36, v153, v36
	v_exp_f32_e32 v48, v48
	v_add_f32_e32 v36, v154, v36
	v_add_f32_e32 v36, v155, v36
	v_add_f32_e32 v36, v156, v36
	v_add_f32_e32 v36, v48, v36
	v_add_f32_e32 v116, v36, v116
	v_cvt_pk_bf16_f32 v36, v49, v51
	s_nop 1
	v_cvt_pk_bf16_f32 v37, v52, v53
	s_nop 1
	v_cvt_pk_bf16_f32 v38, v62, v63
	s_nop 1
	v_cvt_pk_bf16_f32 v39, v64, v65
	s_nop 1
	s_waitcnt lgkmcnt(7)
	v_mfma_f32_32x32x16_bf16 v[18:33], v[164:167], v[36:39], v[18:33]
	s_waitcnt lgkmcnt(5)
	v_mfma_f32_32x32x16_bf16 v[2:17], v[186:189], v[36:39], v[2:17]
	v_cvt_pk_bf16_f32 v36, v144, v145
	s_nop 1
	v_cvt_pk_bf16_f32 v37, v146, v60
	s_nop 1
	v_cvt_pk_bf16_f32 v38, v61, v58
	s_nop 1
	v_cvt_pk_bf16_f32 v39, v59, v56
	s_nop 1
	v_mov_b32_e32 v144, v34
	s_waitcnt lgkmcnt(4)
	v_mfma_f32_32x32x16_bf16 v[2:17], v[190:193], v[36:39], v[2:17]
	v_mfma_f32_32x32x16_bf16 v[18:33], v[182:185], v[36:39], v[18:33]
	v_cvt_pk_bf16_f32 v36, v57, v54
	s_nop 1
	v_cvt_pk_bf16_f32 v37, v55, v147
	s_nop 1
	v_cvt_pk_bf16_f32 v38, v50, v35
	s_nop 1
	v_cvt_pk_bf16_f32 v39, v148, v149
	s_nop 1
	s_waitcnt lgkmcnt(3)
	v_mfma_f32_32x32x16_bf16 v[18:33], v[194:197], v[36:39], v[18:33]
	s_waitcnt lgkmcnt(2)
	v_mfma_f32_32x32x16_bf16 v[2:17], v[198:201], v[36:39], v[2:17]
	v_cvt_pk_bf16_f32 v36, v150, v151
	s_nop 1
	v_cvt_pk_bf16_f32 v37, v152, v153
	s_nop 1
	v_cvt_pk_bf16_f32 v38, v154, v155
	s_nop 1
	v_cvt_pk_bf16_f32 v39, v156, v48
	s_nop 1
	s_waitcnt lgkmcnt(1)
	v_mfma_f32_32x32x16_bf16 v[18:33], v[202:205], v[36:39], v[18:33]
	s_waitcnt lgkmcnt(0)
	v_mfma_f32_32x32x16_bf16 v[2:17], v[206:209], v[36:39], v[2:17]

; #define MFMA32(a, b, c) __builtin_amdgcn_mfma_f32_32x32x16_bf16((a), (b), (c), 0, 0, 0)
; template <int DQK, bool WIN>
; DI void attn_item(const u16* __restrict__ Qb, int ldq, const u16* __restrict__ Kb, int ldk, const u16* __restrict__ Vtb, int qb,
;                   float qscale, float sink2, const u16* __restrict__ zb, int ldz, u16* __restrict__ ob, int ldo, u16* lds) {
;     ...
;     bool active = (k0 <= q0 + 31);
;     if (WIN) active = active && (k0 + 63 >= q0 - 127);
;     if (active) {
;       f32x16 st[2];
; #pragma unroll
;       for (int kb = 0; kb < 2; ++kb) {
; #pragma unroll
;         for (int i = 0; i < 16; ++i) st[kb][i] = 0.f;
; #pragma unroll
;         for (int s = 0; s < NKS; ++s) {
;           bf16x8 a = *(const bf16x8*)(ks + (kb * 32 + r) * KST + 16 * s + 8 * hh);
;           st[kb] = MFMA32(a, qf[s], st[kb]);
;         }
;       }
;       float mx = -INFINITY;
; #pragma unroll
;       for (int kb = 0; kb < 2; ++kb)
; #pragma unroll
;         for (int i = 0; i < 16; ++i) {
;           float v = st[kb][i];
;           if (MASK) {
;             int kg = k0 + kb * 32 + (i & 3) + 8 * (i >> 2) + 4 * hh;
;             bool ok = kg <= qrow;
;             if (WIN) ok = ok && (qrow - kg < 128);
;             v = ok ? v : -INFINITY;
;             st[kb][i] = v;
;           }
;           mx = fmaxf(mx, v);
;         }
.LBB0_323:
	s_add_i32 s0, s26, 0xffffff80
	v_cmp_le_i32_e32 vcc, s0, v137
	s_add_i32 s0, s26, 0xffffffbf
	v_cmp_ge_i32_e64 s[8:9], s0, v138
	s_and_b64 s[0:1], vcc, s[8:9]
	s_and_saveexec_b64 s[34:35], s[0:1]
	s_cbranch_execz .LBB0_327
	ds_read_b128 v[152:155], v139 offset:18432
	ds_read_b128 v[164:167], v139 offset:18464
	ds_read_b128 v[182:185], v139 offset:18496
	ds_read_b128 v[186:189], v139 offset:23072
	ds_read_b128 v[190:193], v139 offset:18528
	ds_read_b128 v[194:197], v139 offset:23040
	ds_read_b128 v[198:201], v139 offset:23104
	ds_read_b128 v[202:205], v139 offset:23136
	v_add_u32_e32 v145, 0xffffff80, v143
	v_cmp_le_i32_e64 s[8:9], v145, v114
	v_add_u32_e32 v145, 0xffffff81, v143
	s_waitcnt lgkmcnt(7)
	v_mfma_f32_32x32x16_bf16 v[50:65], v[152:155], v[66:69], 0
	s_waitcnt lgkmcnt(6)
	v_mfma_f32_32x32x16_bf16 v[50:65], v[164:167], v[70:73], v[50:65]
	s_waitcnt lgkmcnt(5)
	v_mfma_f32_32x32x16_bf16 v[50:65], v[182:185], v[74:77], v[50:65]
	s_waitcnt lgkmcnt(3)
	v_mfma_f32_32x32x16_bf16 v[50:65], v[190:193], v[78:81], v[50:65]
	s_waitcnt lgkmcnt(2)
	v_mfma_f32_32x32x16_bf16 v[34:49], v[194:197], v[66:69], 0
	v_mfma_f32_32x32x16_bf16 v[34:49], v[186:189], v[70:73], v[34:49]
	s_waitcnt lgkmcnt(1)
	v_mfma_f32_32x32x16_bf16 v[34:49], v[198:201], v[74:77], v[34:49]
	s_waitcnt lgkmcnt(0)
	v_mfma_f32_32x32x16_bf16 v[34:49], v[202:205], v[78:81], v[34:49]
	v_add_u32_e32 v146, -5, v141
	v_cmp_gt_i32_e32 vcc, s93, v146
	s_and_b64 vcc, s[8:9], vcc
	v_add_u32_e32 v146, -6, v141
	s_nop 0
	v_cndmask_b32_e32 v50, v176, v50, vcc
	v_cmp_gt_i32_e32 vcc, s93, v146
	v_cmp_le_i32_e64 s[8:9], v145, v114
	s_and_b64 vcc, s[8:9], vcc
	v_add_u32_e32 v146, 0xffffff82, v143
	v_add_u32_e32 v147, -7, v141
	v_cndmask_b32_e32 v51, v176, v51, vcc
	v_cmp_gt_i32_e32 vcc, s93, v147
	v_cmp_le_i32_e64 s[8:9], v146, v114
	s_and_b64 vcc, s[8:9], vcc
	v_add_u32_e32 v146, 0xffffff83, v143
	v_add_u32_e32 v147, -8, v141
	v_cndmask_b32_e32 v52, v176, v52, vcc
	v_cmp_gt_i32_e32 vcc, s93, v147
	v_cmp_le_i32_e64 s[8:9], v146, v114
	s_and_b64 vcc, s[8:9], vcc
	v_add_u32_e32 v146, 0xffffff88, v143
	v_add_u32_e32 v147, -13, v141
	v_cndmask_b32_e32 v53, v176, v53, vcc
	v_cmp_gt_i32_e32 vcc, s93, v147
	v_cmp_le_i32_e64 s[8:9], v146, v114
	s_and_b64 vcc, s[8:9], vcc
	v_cndmask_b32_e32 v148, v176, v54, vcc
	v_add_u32_e32 v54, 0xffffff89, v143
	v_add_u32_e32 v146, -14, v141
	v_cmp_gt_i32_e32 vcc, s93, v146
	v_cmp_le_i32_e64 s[8:9], v54, v114
	v_max3_f32 v145, v50, s94, v51
	s_and_b64 vcc, s[8:9], vcc
	v_max3_f32 v145, v145, v52, v53
	v_cndmask_b32_e32 v147, v176, v55, vcc
	v_max3_f32 v54, v145, v148, v147
	v_add_u32_e32 v55, 0xffffff8a, v143
	v_add_u32_e32 v145, -15, v141
	v_cmp_gt_i32_e32 vcc, s93, v145
	v_cmp_le_i32_e64 s[8:9], v55, v114
	s_and_b64 vcc, s[8:9], vcc
	v_cndmask_b32_e32 v149, v176, v56, vcc
	v_add_u32_e32 v55, 0xffffff8b, v143
	v_add_u32_e32 v56, -16, v141
	v_cmp_gt_i32_e32 vcc, s93, v56
	v_cmp_le_i32_e64 s[8:9], v55, v114
	s_and_b64 vcc, s[8:9], vcc
	v_add_u32_e32 v55, 0xffffff90, v143
	v_subrev_u32_e32 v56, 21, v141
	v_cndmask_b32_e32 v150, v176, v57, vcc
	v_cmp_gt_i32_e32 vcc, s93, v56
	v_cmp_le_i32_e64 s[8:9], v55, v114
	s_and_b64 vcc, s[8:9], vcc
	v_add_u32_e32 v55, 0xffffff91, v143
	v_subrev_u32_e32 v56, 22, v141
	v_cndmask_b32_e32 v151, v176, v58, vcc
	v_cmp_gt_i32_e32 vcc, s93, v56
	v_cmp_le_i32_e64 s[8:9], v55, v114
	s_and_b64 vcc, s[8:9], vcc
	v_add_u32_e32 v55, 0xffffff92, v143
	v_subrev_u32_e32 v56, 23, v141
	v_cndmask_b32_e32 v145, v176, v59, vcc
	v_cmp_gt_i32_e32 vcc, s93, v56
	v_cmp_le_i32_e64 s[8:9], v55, v114
	s_and_b64 vcc, s[8:9], vcc
	v_add_u32_e32 v55, 0xffffff93, v143
	v_subrev_u32_e32 v56, 24, v141
	v_cndmask_b32_e32 v146, v176, v60, vcc
	v_cmp_gt_i32_e32 vcc, s93, v56
	v_cmp_le_i32_e64 s[8:9], v55, v114
	s_and_b64 vcc, s[8:9], vcc
	v_add_u32_e32 v55, 0xffffff98, v143
	v_subrev_u32_e32 v56, 29, v141
	v_cndmask_b32_e32 v60, v176, v61, vcc
	v_cmp_gt_i32_e32 vcc, s93, v56
	v_cmp_le_i32_e64 s[8:9], v55, v114
	s_and_b64 vcc, s[8:9], vcc
	v_add_u32_e32 v55, 0xffffff99, v143
	v_subrev_u32_e32 v56, 30, v141
	v_cndmask_b32_e32 v61, v176, v62, vcc
	v_cmp_gt_i32_e32 vcc, s93, v56
	v_cmp_le_i32_e64 s[8:9], v55, v114
	s_and_b64 vcc, s[8:9], vcc
	v_add_u32_e32 v55, 0xffffff9a, v143
	v_subrev_u32_e32 v56, 31, v141
	v_cndmask_b32_e32 v58, v176, v63, vcc
	v_cmp_gt_i32_e32 vcc, s93, v56
	v_cmp_le_i32_e64 s[8:9], v55, v114
	v_max3_f32 v54, v54, v149, v150
	s_and_b64 vcc, s[8:9], vcc
	v_add_u32_e32 v55, 0xffffff9b, v143
	v_subrev_u32_e32 v56, 32, v141
	v_max3_f32 v54, v54, v151, v145
	v_cndmask_b32_e32 v59, v176, v64, vcc
	v_cmp_gt_i32_e32 vcc, s93, v56
	v_cmp_le_i32_e64 s[8:9], v55, v114
	v_max3_f32 v54, v54, v146, v60
	s_and_b64 vcc, s[8:9], vcc
	v_max3_f32 v54, v54, v61, v58
	v_cndmask_b32_e32 v56, v176, v65, vcc
	v_max3_f32 v55, v54, v59, v56
	v_add_u32_e32 v54, 0xffffffa0, v143
	v_subrev_u32_e32 v57, 37, v141
	v_cmp_gt_i32_e32 vcc, s93, v57
	v_cmp_le_i32_e64 s[8:9], v54, v114
	s_and_b64 vcc, s[8:9], vcc
	v_cndmask_b32_e32 v57, v176, v34, vcc
	v_add_u32_e32 v34, 0xffffffa1, v143
	v_subrev_u32_e32 v54, 38, v141
	v_cmp_gt_i32_e32 vcc, s93, v54
	v_cmp_le_i32_e64 s[8:9], v34, v114
	s_and_b64 vcc, s[8:9], vcc
	v_cndmask_b32_e32 v54, v176, v35, vcc
	v_max3_f32 v34, v55, v57, v54
	v_add_u32_e32 v35, 0xffffffa2, v143
	v_subrev_u32_e32 v55, 39, v141
	v_cmp_gt_i32_e32 vcc, s93, v55
	v_cmp_le_i32_e64 s[8:9], v35, v114
	s_and_b64 vcc, s[8:9], vcc
	v_cndmask_b32_e32 v55, v176, v36, vcc
	v_add_u32_e32 v35, 0xffffffa3, v143
	v_subrev_u32_e32 v36, 40, v141
	v_cmp_gt_i32_e32 vcc, s93, v36
	v_cmp_le_i32_e64 s[8:9], v35, v114
	s_and_b64 vcc, s[8:9], vcc
	v_cndmask_b32_e32 v36, v176, v37, vcc
; template <int DQK, bool WIN>
; DI void attn_item(const u16* __restrict__ Qb, int ldq, const u16* __restrict__ Kb, int ldk, const u16* __restrict__ Vtb, int qb,
;                   float qscale, float sink2, const u16* __restrict__ zb, int ldz, u16* __restrict__ ob, int ldo, u16* lds) {
;     ...
;           if (MASK) {
;             int kg = k0 + kb * 32 + (i & 3) + 8 * (i >> 2) + 4 * hh;
;             bool ok = kg <= qrow;
;             if (WIN) ok = ok && (qrow - kg < 128);
;             v = ok ? v : -INFINITY;
;             st[kb][i] = v;
;           }
;           mx = fmaxf(mx, v);
;         }
;       mx = fmaxf(mx, __shfl_xor(mx, 32));
;       const float mn = fmaxf(m, mx);
;       if (__any(mn != m)) {
;         const float alpha = __builtin_amdgcn_exp2f((m - mn) * qscale);
;         lsum *= alpha;
; #pragma unroll
;         for (int i = 0; i < 16; ++i) { o[0][i] *= alpha; o[1][i] *= alpha; }
;       }
;       m = mn;
	v_add_u32_e32 v35, 0xffffffa8, v143
	v_subrev_u32_e32 v37, 45, v141
	v_cmp_gt_i32_e32 vcc, s93, v37
	v_cmp_le_i32_e64 s[8:9], v35, v114
	s_and_b64 vcc, s[8:9], vcc
	v_cndmask_b32_e32 v37, v176, v38, vcc
	v_add_u32_e32 v35, 0xffffffa9, v143
	v_subrev_u32_e32 v38, 46, v141
	v_cmp_gt_i32_e32 vcc, s93, v38
	v_cmp_le_i32_e64 s[8:9], v35, v114
	s_and_b64 vcc, s[8:9], vcc
	v_cndmask_b32_e32 v35, v176, v39, vcc
	v_add_u32_e32 v38, 0xffffffaa, v143
	v_subrev_u32_e32 v39, 47, v141
	v_cmp_gt_i32_e32 vcc, s93, v39
	v_cmp_le_i32_e64 s[8:9], v38, v114
	s_and_b64 vcc, s[8:9], vcc
	v_cndmask_b32_e32 v38, v176, v40, vcc
	v_add_u32_e32 v39, 0xffffffab, v143
	v_subrev_u32_e32 v40, 48, v141
	v_cmp_gt_i32_e32 vcc, s93, v40
	v_cmp_le_i32_e64 s[8:9], v39, v114
	s_and_b64 vcc, s[8:9], vcc
	v_cndmask_b32_e32 v39, v176, v41, vcc
	v_add_u32_e32 v40, 0xffffffb0, v143
	v_subrev_u32_e32 v41, 53, v141
	v_cmp_gt_i32_e32 vcc, s93, v41
	v_cmp_le_i32_e64 s[8:9], v40, v114
	s_and_b64 vcc, s[8:9], vcc
	v_cndmask_b32_e32 v40, v176, v42, vcc
	v_add_u32_e32 v41, 0xffffffb1, v143
	v_subrev_u32_e32 v42, 54, v141
	v_cmp_gt_i32_e32 vcc, s93, v42
	v_cmp_le_i32_e64 s[8:9], v41, v114
	s_and_b64 vcc, s[8:9], vcc
	v_cndmask_b32_e32 v41, v176, v43, vcc
	v_add_u32_e32 v42, 0xffffffb2, v143
	v_subrev_u32_e32 v43, 55, v141
	v_cmp_gt_i32_e32 vcc, s93, v43
	v_cmp_le_i32_e64 s[8:9], v42, v114
	s_and_b64 vcc, s[8:9], vcc
	v_cndmask_b32_e32 v42, v176, v44, vcc
	v_add_u32_e32 v43, 0xffffffb3, v143
	v_subrev_u32_e32 v44, 56, v141
	v_cmp_gt_i32_e32 vcc, s93, v44
	v_cmp_le_i32_e64 s[8:9], v43, v114
	s_and_b64 vcc, s[8:9], vcc
	v_cndmask_b32_e32 v43, v176, v45, vcc
	v_add_u32_e32 v44, 0xffffffb8, v143
	v_subrev_u32_e32 v45, 61, v141
	v_cmp_gt_i32_e32 vcc, s93, v45
	v_cmp_le_i32_e64 s[8:9], v44, v114
	s_and_b64 vcc, s[8:9], vcc
	v_cndmask_b32_e32 v44, v176, v46, vcc
	v_add_u32_e32 v45, 0xffffffb9, v143
	v_subrev_u32_e32 v46, 62, v141
	v_cmp_gt_i32_e32 vcc, s93, v46
	v_cmp_le_i32_e64 s[8:9], v45, v114
	s_and_b64 vcc, s[8:9], vcc
	v_cndmask_b32_e32 v45, v176, v47, vcc
	v_add_u32_e32 v46, 0xffffffba, v143
	v_subrev_u32_e32 v47, 63, v141
	v_cmp_gt_i32_e32 vcc, s93, v47
	v_cmp_le_i32_e64 s[8:9], v46, v114
	s_and_b64 vcc, s[8:9], vcc
	v_cndmask_b32_e32 v46, v176, v48, vcc
	v_add_u32_e32 v47, 0xffffffbb, v143
	v_subrev_u32_e32 v48, 64, v141
	v_max3_f32 v34, v34, v55, v36
	v_cmp_gt_i32_e32 vcc, s93, v48
	v_cmp_le_i32_e64 s[8:9], v47, v114
	v_max3_f32 v34, v34, v37, v35
	s_and_b64 vcc, s[8:9], vcc
	v_max3_f32 v34, v34, v38, v39
	v_cndmask_b32_e32 v47, v176, v49, vcc
	v_and_b32_e32 v49, 64, v172
	v_max3_f32 v34, v34, v40, v41
	v_xor_b32_e32 v48, 32, v172
	v_add_u32_e32 v49, 64, v49
	v_max3_f32 v34, v34, v42, v43
	v_cmp_lt_i32_e32 vcc, v48, v49
	v_max3_f32 v34, v34, v44, v45
	v_max3_f32 v34, v34, v46, v47
	v_cndmask_b32_e32 v48, v172, v48, vcc
	v_lshlrev_b32_e32 v48, 2, v48
	ds_bpermute_b32 v48, v48, v34
	s_waitcnt lgkmcnt(0)
	v_max3_f32 v34, v144, v34, v48
	v_cmp_neq_f32_e32 vcc, v34, v144
	s_cbranch_vccz .LBB0_326
	v_sub_f32_e32 v48, v144, v34
	v_mul_f32_e32 v48, 0x3e38aa3b, v48
	v_exp_f32_e32 v48, v48
	s_nop 0
	v_mul_f32_e32 v116, v116, v48
	v_pk_mul_f32 v[32:33], v[32:33], v[48:49] op_sel_hi:[1,0]
	v_pk_mul_f32 v[30:31], v[30:31], v[48:49] op_sel_hi:[1,0]
	v_pk_mul_f32 v[28:29], v[28:29], v[48:49] op_sel_hi:[1,0]
	v_pk_mul_f32 v[26:27], v[26:27], v[48:49] op_sel_hi:[1,0]
	v_pk_mul_f32 v[24:25], v[24:25], v[48:49] op_sel_hi:[1,0]
	v_pk_mul_f32 v[22:23], v[22:23], v[48:49] op_sel_hi:[1,0]
	v_pk_mul_f32 v[20:21], v[20:21], v[48:49] op_sel_hi:[1,0]
	v_pk_mul_f32 v[18:19], v[18:19], v[48:49] op_sel_hi:[1,0]
	v_pk_mul_f32 v[16:17], v[16:17], v[48:49] op_sel_hi:[1,0]
	v_pk_mul_f32 v[14:15], v[14:15], v[48:49] op_sel_hi:[1,0]
	v_pk_mul_f32 v[12:13], v[12:13], v[48:49] op_sel_hi:[1,0]
	v_pk_mul_f32 v[10:11], v[10:11], v[48:49] op_sel_hi:[1,0]
	v_pk_mul_f32 v[8:9], v[8:9], v[48:49] op_sel_hi:[1,0]
	v_pk_mul_f32 v[6:7], v[6:7], v[48:49] op_sel_hi:[1,0]
	v_pk_mul_f32 v[4:5], v[4:5], v[48:49] op_sel_hi:[1,0]
	v_pk_mul_f32 v[2:3], v[2:3], v[48:49] op_sel_hi:[1,0]
; DI unsigned pack2(float a, float b) { unsigned r; asm("v_cvt_pk_bf16_f32 %0, %1, %2\n\ts_nop 1" : "=v"(r) : "v"(a), "v"(b)); return r; }
; #define MFMA32(a, b, c) __builtin_amdgcn_mfma_f32_32x32x16_bf16((a), (b), (c), 0, 0, 0)
; template <int DQK, bool WIN>
; DI void attn_item(const u16* __restrict__ Qb, int ldq, const u16* __restrict__ Kb, int ldk, const u16* __restrict__ Vtb, int qb,
;                   float qscale, float sink2, const u16* __restrict__ zb, int ldz, u16* __restrict__ ob, int ldo, u16* lds) {
;     ...
;       const float nb = -mn * qscale;
;       float ps = 0.f;
; #pragma unroll
;       for (int kb = 0; kb < 2; ++kb)
; #pragma unroll
;         for (int i = 0; i < 16; ++i) { float pv = __builtin_amdgcn_exp2f(fmaf(st[kb][i], qscale, nb)); st[kb][i] = pv; ps += pv; }
;       lsum += ps;
; #pragma unroll
;       for (int kb = 0; kb < 2; ++kb)
; #pragma unroll
;         for (int s2 = 0; s2 < 2; ++s2) {
;           union { bf16x8 v; unsigned u[4]; } pf;
; #pragma unroll
;           for (int j = 0; j < 4; ++j) pf.u[j] = pack2(st[kb][8 * s2 + 2 * j], st[kb][8 * s2 + 2 * j + 1]);
; #pragma unroll
;           for (int vb = 0; vb < 2; ++vb) {
;             const bf16x8 vf = *(const bf16x8*)(vs + (vb * 32 + r) * 72 + (kb * 2 + s2) * 16 + hh * 8);
;             o[vb] = MFMA32(vf, pf.v, o[vb]);
;           }
;         }
.LBB0_326:
	ds_read_b128 v[164:167], v140 offset:27648
	ds_read_b128 v[182:185], v140 offset:27680
	ds_read_b128 v[186:189], v140 offset:32256
	ds_read_b128 v[190:193], v140 offset:32288
	ds_read_b128 v[194:197], v140 offset:27712
	ds_read_b128 v[198:201], v140 offset:32320
	ds_read_b128 v[202:205], v140 offset:27744
	ds_read_b128 v[206:209], v140 offset:32352
	v_mul_f32_e32 v48, 0xbe38aa3b, v34
	v_fmamk_f32 v49, v50, 0x3e38aa3b, v48
	v_exp_f32_e32 v49, v49
	v_fmamk_f32 v51, v51, 0x3e38aa3b, v48
	v_exp_f32_e32 v51, v51
	v_fmamk_f32 v52, v52, 0x3e38aa3b, v48
	v_exp_f32_e32 v52, v52
	v_fmamk_f32 v53, v53, 0x3e38aa3b, v48
	v_exp_f32_e32 v53, v53
	v_fmamk_f32 v62, v148, 0x3e38aa3b, v48
	v_add_f32_e32 v50, 0, v49
	v_exp_f32_e32 v62, v62
	v_fmamk_f32 v63, v147, 0x3e38aa3b, v48
	v_add_f32_e32 v50, v51, v50
	v_exp_f32_e32 v63, v63
	v_fmamk_f32 v64, v149, 0x3e38aa3b, v48
	v_add_f32_e32 v50, v52, v50
	v_exp_f32_e32 v64, v64
	v_fmamk_f32 v65, v150, 0x3e38aa3b, v48
	v_add_f32_e32 v50, v53, v50
	v_exp_f32_e32 v65, v65
	v_fmamk_f32 v143, v151, 0x3e38aa3b, v48
	v_add_f32_e32 v50, v62, v50
	v_exp_f32_e32 v143, v143
	v_fmamk_f32 v144, v145, 0x3e38aa3b, v48
	v_add_f32_e32 v50, v63, v50
	v_exp_f32_e32 v144, v144
	v_fmamk_f32 v145, v146, 0x3e38aa3b, v48
	v_add_f32_e32 v50, v64, v50
	v_exp_f32_e32 v145, v145
	v_fmamk_f32 v60, v60, 0x3e38aa3b, v48
	v_add_f32_e32 v50, v65, v50
	v_exp_f32_e32 v60, v60
	v_fmamk_f32 v61, v61, 0x3e38aa3b, v48
	v_add_f32_e32 v50, v143, v50
	v_exp_f32_e32 v61, v61
	v_fmamk_f32 v58, v58, 0x3e38aa3b, v48
	v_add_f32_e32 v50, v144, v50
	v_exp_f32_e32 v58, v58
	v_fmamk_f32 v59, v59, 0x3e38aa3b, v48
	v_add_f32_e32 v50, v145, v50
	v_exp_f32_e32 v59, v59
	v_fmamk_f32 v56, v56, 0x3e38aa3b, v48
	v_add_f32_e32 v50, v60, v50
	v_exp_f32_e32 v56, v56
	v_fmamk_f32 v57, v57, 0x3e38aa3b, v48
	v_add_f32_e32 v50, v61, v50
	v_exp_f32_e32 v57, v57
	v_fmamk_f32 v54, v54, 0x3e38aa3b, v48
	v_add_f32_e32 v50, v58, v50
	v_exp_f32_e32 v54, v54
	v_fmamk_f32 v55, v55, 0x3e38aa3b, v48
	v_add_f32_e32 v50, v59, v50
	v_exp_f32_e32 v55, v55
	v_fmamk_f32 v36, v36, 0x3e38aa3b, v48
	v_add_f32_e32 v50, v56, v50
	v_exp_f32_e32 v146, v36
	v_add_f32_e32 v50, v57, v50
	v_add_f32_e32 v50, v54, v50
	v_add_f32_e32 v50, v55, v50
	v_fmamk_f32 v37, v37, 0x3e38aa3b, v48
	v_add_f32_e32 v36, v146, v50
	v_exp_f32_e32 v50, v37
	v_fmamk_f32 v35, v35, 0x3e38aa3b, v48
	v_exp_f32_e32 v35, v35
	v_fmamk_f32 v37, v38, 0x3e38aa3b, v48
	v_exp_f32_e32 v147, v37
	v_fmamk_f32 v37, v39, 0x3e38aa3b, v48
	v_exp_f32_e32 v148, v37
	v_fmamk_f32 v37, v40, 0x3e38aa3b, v48
	v_add_f32_e32 v36, v50, v36
	v_exp_f32_e32 v149, v37
	v_fmamk_f32 v37, v41, 0x3e38aa3b, v48
	v_add_f32_e32 v36, v35, v36
	v_exp_f32_e32 v150, v37
	v_fmamk_f32 v37, v42, 0x3e38aa3b, v48
	v_add_f32_e32 v36, v147, v36
	v_exp_f32_e32 v151, v37
	v_fmamk_f32 v37, v43, 0x3e38aa3b, v48
	v_add_f32_e32 v36, v148, v36
	v_exp_f32_e32 v152, v37
	v_fmamk_f32 v37, v44, 0x3e38aa3b, v48
	v_add_f32_e32 v36, v149, v36
	v_exp_f32_e32 v153, v37
	v_fmamk_f32 v37, v45, 0x3e38aa3b, v48
	v_add_f32_e32 v36, v150, v36
	v_exp_f32_e32 v154, v37
	v_fmamk_f32 v37, v46, 0x3e38aa3b, v48
	v_add_f32_e32 v36, v151, v36
	v_exp_f32_e32 v155, v37
	v_fmac_f32_e32 v48, 0x3e38aa3b, v47
	v_add_f32_e32 v36, v152, v36
	v_exp_f32_e32 v48, v48
	v_add_f32_e32 v36, v153, v36
	v_add_f32_e32 v36, v154, v36
	v_add_f32_e32 v36, v155, v36
	v_add_f32_e32 v36, v48, v36
	v_add_f32_e32 v116, v36, v116
	v_cvt_pk_bf16_f32 v36, v49, v51
	s_nop 1
	v_cvt_pk_bf16_f32 v37, v52, v53
	s_nop 1
	v_cvt_pk_bf16_f32 v38, v62, v63
	s_nop 1
	v_cvt_pk_bf16_f32 v39, v64, v65
	s_nop 1
	s_waitcnt lgkmcnt(7)
	v_mfma_f32_32x32x16_bf16 v[18:33], v[164:167], v[36:39], v[18:33]
	s_waitcnt lgkmcnt(5)
	v_mfma_f32_32x32x16_bf16 v[2:17], v[186:189], v[36:39], v[2:17]
	v_cvt_pk_bf16_f32 v36, v143, v144
	s_nop 1
	v_cvt_pk_bf16_f32 v37, v145, v60
	s_nop 1
	v_cvt_pk_bf16_f32 v38, v61, v58
	s_nop 1
	v_cvt_pk_bf16_f32 v39, v59, v56
	s_nop 1
	v_mov_b32_e32 v144, v34
	s_waitcnt lgkmcnt(4)
	v_mfma_f32_32x32x16_bf16 v[2:17], v[190:193], v[36:39], v[2:17]
	v_mfma_f32_32x32x16_bf16 v[18:33], v[182:185], v[36:39], v[18:33]
	v_cvt_pk_bf16_f32 v36, v57, v54
	s_nop 1
	v_cvt_pk_bf16_f32 v37, v55, v146
	s_nop 1
	v_cvt_pk_bf16_f32 v38, v50, v35
	s_nop 1
	v_cvt_pk_bf16_f32 v39, v147, v148
	s_nop 1
	s_waitcnt lgkmcnt(3)
	v_mfma_f32_32x32x16_bf16 v[18:33], v[194:197], v[36:39], v[18:33]
	s_waitcnt lgkmcnt(2)
	v_mfma_f32_32x32x16_bf16 v[2:17], v[198:201], v[36:39], v[2:17]
	v_cvt_pk_bf16_f32 v36, v149, v150
	s_nop 1
	v_cvt_pk_bf16_f32 v37, v151, v152
	s_nop 1
	v_cvt_pk_bf16_f32 v38, v153, v154
	s_nop 1
	v_cvt_pk_bf16_f32 v39, v155, v48
	s_nop 1
	s_waitcnt lgkmcnt(1)
	v_mfma_f32_32x32x16_bf16 v[18:33], v[202:205], v[36:39], v[18:33]
	s_waitcnt lgkmcnt(0)
	v_mfma_f32_32x32x16_bf16 v[2:17], v[206:209], v[36:39], v[2:17]
